# GEMM epilogues of o-proj, both FFN-down and hin-x1: adjacent 16-column fragments exchanged with v_permlane16_swap and stored as 16-byte global_store_dwordx4 (half the store instructions)
# speedup vs baseline: 1.0368x; 1.0089x over previous
; template <bool SWAP, class Epi, bool THIN = false> ...
;     ...
;     for (int st = 0; st < ns; ++st) {
;       asm volatile("s_waitcnt vmcnt(0)" ::: "memory");
;       __builtin_amdgcn_s_barrier();
;       asm volatile("" ::: "memory");
;       if (st + 1 < ns) {
;         char* nb = smem + ((st + 1) & 1) * 65536;
;         const int ko = (st + 1) * 64;
; #pragma unroll
;         for (int i = 0; i < 4; ++i) { GLDS16(A + (size_t)(ap[i] + ko), nb + tid * 16 + i * 8192); GLDS16(Bt + (size_t)(bp[i] + ko), nb + 32768 + tid * 16 + i * 8192); }
;       }
;       const char* sa = smem + (st & 1) * 65536 + (wr * 64 + fr) * 128;
;       const char* sb = smem + (st & 1) * 65536 + 32768 + (wc * 128 + fr) * 128;
;       if constexpr (THIN) {
;         if (wc == 0) {
; #pragma unroll
;           for (int ks = 0; ks < 2; ++ks) {
;             bf16x8 af[4], bf[2];
; #pragma unroll
;             for (int m = 0; m < 4; ++m) af[m] = *(const bf16x8*)(sa + m * 2048 + (((ks * 4 + fq) ^ swz) << 4));
; #pragma unroll
;             for (int n = 0; n < 2; ++n) bf[n] = *(const bf16x8*)(sb + n * 2048 + (((ks * 4 + fq) ^ swz) << 4));
; #pragma unroll
;             for (int m = 0; m < 4; ++m)
; #pragma unroll
;               for (int n = 0; n < 2; ++n)
;                 acc[m][n] = SWAP ? __builtin_amdgcn_mfma_f32_16x16x32_bf16(bf[n], af[m], acc[m][n], 0, 0, 0)
;                                  : __builtin_amdgcn_mfma_f32_16x16x32_bf16(af[m], bf[n], acc[m][n], 0, 0, 0);
;           }
;         }
;       } else {
;       bf16x8 afA[4], afB[4], bfb[2][2];
; #pragma unroll
;       for (int m = 0; m < 4; ++m) afA[m] = *(const bf16x8*)(sa + m * 2048 + ((fq ^ swz) << 4));
; #pragma unroll
;       for (int n = 0; n < 2; ++n) bfb[0][n] = *(const bf16x8*)(sb + n * 2048 + ((fq ^ swz) << 4));
; #pragma unroll
;       for (int gq = 0; gq < 8; ++gq) {
;         const int ks = gq >> 2, nh = gq & 3;
;         if (gq < 7) {
;           const int ks2 = (gq + 1) >> 2, nh2 = (gq + 1) & 3;
; #pragma unroll
;           for (int n = 0; n < 2; ++n) bfb[(gq + 1) & 1][n] = *(const bf16x8*)(sb + (nh2 * 2 + n) * 2048 + (((ks2 * 4 + fq) ^ swz) << 4));
;         }
;         if (gq == 3) {
; #pragma unroll
;           for (int m = 0; m < 4; ++m) afB[m] = *(const bf16x8*)(sa + m * 2048 + (((4 + fq) ^ swz) << 4));
;         }
;         __builtin_amdgcn_sched_barrier(0);
; #pragma unroll
.LBB0_2116:
	s_add_i32 s8, s7, 0x10000
	s_and_b32 s9, s8, 0x10000
	v_add_u32_e32 v169, s9, v144
	s_nop 0
	v_readfirstlane_b32 s9, v169
	s_waitcnt vmcnt(0)
	s_barrier
	s_and_b32 s7, s7, 0x10000
	v_add_u32_e32 v130, s7, v145
	v_add_u32_e32 v140, v130, v147
	ds_read_b128 v[170:173], v140
	ds_read_b128 v[174:177], v140 offset:2048
	ds_read_b128 v[178:181], v140 offset:4096
	ds_read_b128 v[182:185], v140 offset:6144
	v_or_b32_e32 v140, s7, v146
	v_add_u32_e32 v141, v140, v147
	ds_read_b128 v[186:189], v141 offset:32768
	ds_read_b128 v[190:193], v141 offset:34816
	ds_read_b128 v[194:197], v141 offset:36864
	ds_read_b128 v[198:201], v141 offset:38912
	v_add_u32_e32 v130, v130, v148
	s_waitcnt lgkmcnt(3)
	v_mfma_f32_16x16x32_bf16 v[126:129], v[186:189], v[170:173], v[126:129]
	s_mov_b32 m0, s9
	v_mfma_f32_16x16x32_bf16 v[110:113], v[186:189], v[174:177], v[110:113]
	global_load_lds_dwordx4 v139, s[18:19]
	v_add_u32_e32 v139, 0x80, v139
	v_mfma_f32_16x16x32_bf16 v[82:85], v[186:189], v[178:181], v[82:85]
	v_mfma_f32_16x16x32_bf16 v[50:53], v[186:189], v[182:185], v[50:53]
	ds_read_b128 v[186:189], v141 offset:40960
	ds_read_b128 v[202:205], v141 offset:43008
	s_waitcnt lgkmcnt(4)
	v_mfma_f32_16x16x32_bf16 v[122:125], v[190:193], v[170:173], v[122:125]
	s_add_u32 m0, s9, 0x8000
	v_mfma_f32_16x16x32_bf16 v[106:109], v[190:193], v[174:177], v[106:109]
	global_load_lds_dwordx4 v138, s[24:25]
	v_add_u32_e32 v138, 0x80, v138
	v_mfma_f32_16x16x32_bf16 v[78:81], v[190:193], v[178:181], v[78:81]
	v_mfma_f32_16x16x32_bf16 v[42:45], v[190:193], v[182:185], v[42:45]
	s_waitcnt lgkmcnt(3)
	v_mfma_f32_16x16x32_bf16 v[118:121], v[194:197], v[170:173], v[118:121]
	s_add_u32 m0, s9, 0x2000
	v_mfma_f32_16x16x32_bf16 v[94:97], v[194:197], v[174:177], v[94:97]
	global_load_lds_dwordx4 v137, s[18:19]
	v_add_u32_e32 v137, 0x80, v137
	v_mfma_f32_16x16x32_bf16 v[58:61], v[194:197], v[178:181], v[58:61]
	v_mfma_f32_16x16x32_bf16 v[26:29], v[194:197], v[182:185], v[26:29]
	ds_read_b128 v[190:193], v141 offset:45056
	ds_read_b128 v[194:197], v141 offset:47104
	s_waitcnt lgkmcnt(4)
	v_mfma_f32_16x16x32_bf16 v[114:117], v[198:201], v[170:173], v[114:117]
	s_add_u32 m0, s9, 0xa000
	v_mfma_f32_16x16x32_bf16 v[86:89], v[198:201], v[174:177], v[86:89]
	global_load_lds_dwordx4 v136, s[24:25]
	v_add_u32_e32 v136, 0x80, v136
	v_mfma_f32_16x16x32_bf16 v[54:57], v[198:201], v[178:181], v[54:57]
	v_mfma_f32_16x16x32_bf16 v[22:25], v[198:201], v[182:185], v[22:25]
	v_add_u32_e32 v140, v140, v148
	s_waitcnt lgkmcnt(3)
	v_mfma_f32_16x16x32_bf16 v[102:105], v[186:189], v[170:173], v[102:105]
	ds_read_b128 v[198:201], v140 offset:32768
	ds_read_b128 v[206:209], v140 offset:34816
	s_add_u32 m0, s9, 0x4000
	v_mfma_f32_16x16x32_bf16 v[74:77], v[186:189], v[174:177], v[74:77]
	global_load_lds_dwordx4 v135, s[18:19]
	v_add_u32_e32 v135, 0x80, v135
	v_mfma_f32_16x16x32_bf16 v[46:49], v[186:189], v[178:181], v[46:49]
	v_mfma_f32_16x16x32_bf16 v[10:13], v[186:189], v[182:185], v[10:13]
	ds_read_b128 v[186:189], v130
	ds_read_b128 v[210:213], v130 offset:2048
	ds_read_b128 v[214:217], v130 offset:4096
	ds_read_b128 v[218:221], v130 offset:6144
	s_waitcnt lgkmcnt(8)
	v_mfma_f32_16x16x32_bf16 v[98:101], v[202:205], v[170:173], v[98:101]
	s_add_u32 m0, s9, 0xc000
	v_mfma_f32_16x16x32_bf16 v[66:69], v[202:205], v[174:177], v[66:69]
	global_load_lds_dwordx4 v134, s[24:25]
	v_add_u32_e32 v134, 0x80, v134
	v_mfma_f32_16x16x32_bf16 v[30:33], v[202:205], v[178:181], v[30:33]
	v_mfma_f32_16x16x32_bf16 v[6:9], v[202:205], v[182:185], v[6:9]
	s_waitcnt lgkmcnt(7)
	v_mfma_f32_16x16x32_bf16 v[70:73], v[190:193], v[170:173], v[70:73]
	s_add_u32 m0, s9, 0x6000
	s_waitcnt lgkmcnt(6)
	v_mfma_f32_16x16x32_bf16 v[62:65], v[194:197], v[170:173], v[62:65]
	global_load_lds_dwordx4 v133, s[18:19]
	v_add_u32_e32 v133, 0x80, v133
	v_mfma_f32_16x16x32_bf16 v[38:41], v[190:193], v[174:177], v[38:41]
	v_mfma_f32_16x16x32_bf16 v[34:37], v[194:197], v[174:177], v[34:37]
	ds_read_b128 v[170:173], v140 offset:36864
	ds_read_b128 v[174:177], v140 offset:38912
	v_mfma_f32_16x16x32_bf16 v[18:21], v[190:193], v[178:181], v[18:21]
	s_add_u32 m0, s9, 0xe000
	v_mfma_f32_16x16x32_bf16 v[14:17], v[194:197], v[178:181], v[14:17]
	global_load_lds_dwordx4 v132, s[24:25]
	v_add_u32_e32 v132, 0x80, v132
	v_mfma_f32_16x16x32_bf16 v[2:5], v[190:193], v[182:185], v[2:5]
	v_mfma_f32_16x16x32_bf16 v[90:93], v[194:197], v[182:185], v[90:93]
	ds_read_b128 v[178:181], v140 offset:40960
	ds_read_b128 v[182:185], v140 offset:43008
	s_waitcnt lgkmcnt(7)
	v_mfma_f32_16x16x32_bf16 v[126:129], v[198:201], v[186:189], v[126:129]
	v_mfma_f32_16x16x32_bf16 v[122:125], v[206:209], v[186:189], v[122:125]
	s_waitcnt lgkmcnt(6)
	v_mfma_f32_16x16x32_bf16 v[110:113], v[198:201], v[210:213], v[110:113]
	v_mfma_f32_16x16x32_bf16 v[106:109], v[206:209], v[210:213], v[106:109]
	s_waitcnt lgkmcnt(5)
	v_mfma_f32_16x16x32_bf16 v[82:85], v[198:201], v[214:217], v[82:85]
	v_mfma_f32_16x16x32_bf16 v[78:81], v[206:209], v[214:217], v[78:81]
	s_waitcnt lgkmcnt(4)
	v_mfma_f32_16x16x32_bf16 v[50:53], v[198:201], v[218:221], v[50:53]
	v_mfma_f32_16x16x32_bf16 v[42:45], v[206:209], v[218:221], v[42:45]
	s_waitcnt lgkmcnt(3)
	v_mfma_f32_16x16x32_bf16 v[118:121], v[170:173], v[186:189], v[118:121]
	v_mfma_f32_16x16x32_bf16 v[94:97], v[170:173], v[210:213], v[94:97]
	v_mfma_f32_16x16x32_bf16 v[58:61], v[170:173], v[214:217], v[58:61]
	v_mfma_f32_16x16x32_bf16 v[26:29], v[170:173], v[218:221], v[26:29]
	ds_read_b128 v[170:173], v140 offset:45056
	ds_read_b128 v[190:193], v140 offset:47104
	s_waitcnt lgkmcnt(4)
; template <bool SWAP, class Epi, bool THIN = false> ...
;     ...
;     for (int st = 0; st < ns; ++st) {
;       asm volatile("s_waitcnt vmcnt(0)" ::: "memory");
;       __builtin_amdgcn_s_barrier();
;       asm volatile("" ::: "memory");
;       if (st + 1 < ns) {
;         char* nb = smem + ((st + 1) & 1) * 65536;
;         const int ko = (st + 1) * 64;
; #pragma unroll
;         for (int i = 0; i < 4; ++i) { GLDS16(A + (size_t)(ap[i] + ko), nb + tid * 16 + i * 8192); GLDS16(Bt + (size_t)(bp[i] + ko), nb + 32768 + tid * 16 + i * 8192); }
;       }
;       const char* sa = smem + (st & 1) * 65536 + (wr * 64 + fr) * 128;
;       const char* sb = smem + (st & 1) * 65536 + 32768 + (wc * 128 + fr) * 128;
;       if constexpr (THIN) {
;         if (wc == 0) {
; #pragma unroll
;           for (int ks = 0; ks < 2; ++ks) {
;             bf16x8 af[4], bf[2];
; #pragma unroll
;             for (int m = 0; m < 4; ++m) af[m] = *(const bf16x8*)(sa + m * 2048 + (((ks * 4 + fq) ^ swz) << 4));
; #pragma unroll
;             for (int n = 0; n < 2; ++n) bf[n] = *(const bf16x8*)(sb + n * 2048 + (((ks * 4 + fq) ^ swz) << 4));
; #pragma unroll
;             for (int m = 0; m < 4; ++m)
; #pragma unroll
;               for (int n = 0; n < 2; ++n)
;                 acc[m][n] = SWAP ? __builtin_amdgcn_mfma_f32_16x16x32_bf16(bf[n], af[m], acc[m][n], 0, 0, 0)
;                                  : __builtin_amdgcn_mfma_f32_16x16x32_bf16(af[m], bf[n], acc[m][n], 0, 0, 0);
;           }
;         }
;       } else {
;       bf16x8 afA[4], afB[4], bfb[2][2];
; #pragma unroll
;       for (int m = 0; m < 4; ++m) afA[m] = *(const bf16x8*)(sa + m * 2048 + ((fq ^ swz) << 4));
; #pragma unroll
;       for (int n = 0; n < 2; ++n) bfb[0][n] = *(const bf16x8*)(sb + n * 2048 + ((fq ^ swz) << 4));
; #pragma unroll
;       for (int gq = 0; gq < 8; ++gq) {
;         const int ks = gq >> 2, nh = gq & 3;
;         if (gq < 7) {
;           const int ks2 = (gq + 1) >> 2, nh2 = (gq + 1) & 3;
; #pragma unroll
;           for (int n = 0; n < 2; ++n) bfb[(gq + 1) & 1][n] = *(const bf16x8*)(sb + (nh2 * 2 + n) * 2048 + (((ks2 * 4 + fq) ^ swz) << 4));
;         }
;         if (gq == 3) {
; #pragma unroll
;           for (int m = 0; m < 4; ++m) afB[m] = *(const bf16x8*)(sa + m * 2048 + (((4 + fq) ^ swz) << 4));
;         }
;         __builtin_amdgcn_sched_barrier(0);
; #pragma unroll
	v_mfma_f32_16x16x32_bf16 v[114:117], v[174:177], v[186:189], v[114:117]
	v_mfma_f32_16x16x32_bf16 v[86:89], v[174:177], v[210:213], v[86:89]
	v_mfma_f32_16x16x32_bf16 v[54:57], v[174:177], v[214:217], v[54:57]
	v_mfma_f32_16x16x32_bf16 v[22:25], v[174:177], v[218:221], v[22:25]
	s_waitcnt lgkmcnt(3)
	v_mfma_f32_16x16x32_bf16 v[102:105], v[178:181], v[186:189], v[102:105]
	s_waitcnt lgkmcnt(2)
	v_mfma_f32_16x16x32_bf16 v[98:101], v[182:185], v[186:189], v[98:101]
	v_mfma_f32_16x16x32_bf16 v[74:77], v[178:181], v[210:213], v[74:77]
	v_mfma_f32_16x16x32_bf16 v[66:69], v[182:185], v[210:213], v[66:69]
	v_mfma_f32_16x16x32_bf16 v[46:49], v[178:181], v[214:217], v[46:49]
	v_mfma_f32_16x16x32_bf16 v[30:33], v[182:185], v[214:217], v[30:33]
	v_mfma_f32_16x16x32_bf16 v[10:13], v[178:181], v[218:221], v[10:13]
	v_mfma_f32_16x16x32_bf16 v[6:9], v[182:185], v[218:221], v[6:9]
	s_waitcnt lgkmcnt(1)
	v_mfma_f32_16x16x32_bf16 v[70:73], v[170:173], v[186:189], v[70:73]
	s_add_i32 s6, s6, 64
	s_cmpk_eq_i32 s6, 0x3c0
	s_mov_b32 s7, s8
	s_waitcnt lgkmcnt(0)
	v_mfma_f32_16x16x32_bf16 v[62:65], v[190:193], v[186:189], v[62:65]
	v_mfma_f32_16x16x32_bf16 v[38:41], v[170:173], v[210:213], v[38:41]
	v_mfma_f32_16x16x32_bf16 v[34:37], v[190:193], v[210:213], v[34:37]
	v_mfma_f32_16x16x32_bf16 v[18:21], v[170:173], v[214:217], v[18:21]
	v_mfma_f32_16x16x32_bf16 v[14:17], v[190:193], v[214:217], v[14:17]
	v_mfma_f32_16x16x32_bf16 v[2:5], v[170:173], v[218:221], v[2:5]
	v_mfma_f32_16x16x32_bf16 v[90:93], v[190:193], v[218:221], v[90:93]
	s_cbranch_scc0 .LBB0_2116
	s_waitcnt vmcnt(0)
	s_barrier
	v_add_u32_e32 v130, v159, v147
	ds_read_b128 v[132:135], v130
	ds_read_b128 v[136:139], v130 offset:2048
	ds_read_b128 v[170:173], v130 offset:4096
	ds_read_b128 v[174:177], v130 offset:6144
	v_add_u32_e32 v130, v160, v147
	ds_read_b128 v[178:181], v130
	ds_read_b128 v[182:185], v130 offset:2048
	ds_read_b128 v[186:189], v130 offset:4096
	ds_read_b128 v[190:193], v130 offset:6144
	s_waitcnt lgkmcnt(0)
	v_mfma_f32_16x16x32_bf16 v[126:129], v[178:181], v[132:135], v[126:129]
	v_mfma_f32_16x16x32_bf16 v[110:113], v[178:181], v[136:139], v[110:113]
	v_mfma_f32_16x16x32_bf16 v[82:85], v[178:181], v[170:173], v[82:85]
	v_mfma_f32_16x16x32_bf16 v[50:53], v[178:181], v[174:177], v[50:53]
	ds_read_b128 v[178:181], v130 offset:8192
	ds_read_b128 v[194:197], v130 offset:10240
	v_mfma_f32_16x16x32_bf16 v[122:125], v[182:185], v[132:135], v[122:125]
	v_mfma_f32_16x16x32_bf16 v[106:109], v[182:185], v[136:139], v[106:109]
	v_mfma_f32_16x16x32_bf16 v[78:81], v[182:185], v[170:173], v[78:81]
	v_mfma_f32_16x16x32_bf16 v[42:45], v[182:185], v[174:177], v[42:45]
	v_mfma_f32_16x16x32_bf16 v[118:121], v[186:189], v[132:135], v[118:121]
	v_mfma_f32_16x16x32_bf16 v[182:185], v[186:189], v[136:139], v[94:97]
	v_mfma_f32_16x16x32_bf16 v[202:205], v[186:189], v[170:173], v[58:61]
	v_mfma_f32_16x16x32_bf16 v[206:209], v[190:193], v[170:173], v[54:57]
	v_mfma_f32_16x16x32_bf16 v[186:189], v[186:189], v[174:177], v[26:29]
	s_nop 2
	ds_read_b128 v[26:29], v130 offset:12288
	ds_read_b128 v[54:57], v130 offset:14336
	v_mfma_f32_16x16x32_bf16 v[114:117], v[190:193], v[132:135], v[114:117]
	v_mfma_f32_16x16x32_bf16 v[198:201], v[190:193], v[136:139], v[86:89]
	v_mfma_f32_16x16x32_bf16 v[190:193], v[190:193], v[174:177], v[22:25]
	v_add_u32_e32 v130, v160, v148
	s_waitcnt lgkmcnt(0)
	v_mfma_f32_16x16x32_bf16 v[210:213], v[194:197], v[170:173], v[30:33]
	ds_read_b128 v[22:25], v130
	ds_read_b128 v[86:89], v130 offset:2048
	s_nop 0
	v_add_u32_e32 v30, v159, v148
	v_mfma_f32_16x16x32_bf16 v[102:105], v[178:181], v[132:135], v[102:105]
	v_mfma_f32_16x16x32_bf16 v[74:77], v[178:181], v[136:139], v[74:77]
	v_mfma_f32_16x16x32_bf16 v[46:49], v[178:181], v[170:173], v[46:49]
	v_mfma_f32_16x16x32_bf16 v[10:13], v[178:181], v[174:177], v[10:13]
	ds_read_b128 v[178:181], v30
	ds_read_b128 v[214:217], v30 offset:2048
	ds_read_b128 v[218:221], v30 offset:4096
	ds_read_b128 v[222:225], v30 offset:6144
	v_mfma_f32_16x16x32_bf16 v[98:101], v[194:197], v[132:135], v[98:101]
	v_mfma_f32_16x16x32_bf16 v[66:69], v[194:197], v[136:139], v[66:69]
	v_mfma_f32_16x16x32_bf16 v[6:9], v[194:197], v[174:177], v[6:9]
	v_mfma_f32_16x16x32_bf16 v[38:41], v[26:29], v[136:139], v[38:41]
	v_mfma_f32_16x16x32_bf16 v[34:37], v[54:57], v[136:139], v[34:37]
	v_mfma_f32_16x16x32_bf16 v[136:139], v[26:29], v[170:173], v[18:21]
	v_mfma_f32_16x16x32_bf16 v[170:173], v[54:57], v[170:173], v[14:17]
	s_nop 2
	ds_read_b128 v[14:17], v130 offset:4096
	ds_read_b128 v[18:21], v130 offset:6144
	v_mfma_f32_16x16x32_bf16 v[70:73], v[26:29], v[132:135], v[70:73]
	v_mfma_f32_16x16x32_bf16 v[132:135], v[54:57], v[132:135], v[62:65]
	v_mfma_f32_16x16x32_bf16 v[2:5], v[26:29], v[174:177], v[2:5]
	v_mfma_f32_16x16x32_bf16 v[174:177], v[54:57], v[174:177], v[90:93]
	ds_read_b128 v[194:197], v130 offset:8192
	ds_read_b128 v[226:229], v130 offset:10240
	s_waitcnt lgkmcnt(0)
	v_mfma_f32_16x16x32_bf16 v[126:129], v[22:25], v[178:181], v[126:129]
	v_mfma_f32_16x16x32_bf16 v[122:125], v[86:89], v[178:181], v[122:125]
	v_mfma_f32_16x16x32_bf16 v[94:97], v[22:25], v[214:217], v[110:113]
	v_mfma_f32_16x16x32_bf16 v[90:93], v[86:89], v[214:217], v[106:109]
	v_mfma_f32_16x16x32_bf16 v[62:65], v[22:25], v[218:221], v[82:85]
	v_mfma_f32_16x16x32_bf16 v[58:61], v[86:89], v[218:221], v[78:81]
	v_mfma_f32_16x16x32_bf16 v[30:33], v[22:25], v[222:225], v[50:53]
	v_mfma_f32_16x16x32_bf16 v[26:29], v[86:89], v[222:225], v[42:45]
	v_mfma_f32_16x16x32_bf16 v[86:89], v[14:17], v[214:217], v[182:185]
	v_mfma_f32_16x16x32_bf16 v[22:25], v[14:17], v[222:225], v[186:189]
	s_nop 1
	ds_read_b128 v[182:185], v130 offset:12288
	ds_read_b128 v[186:189], v130 offset:14336
	v_mfma_f32_16x16x32_bf16 v[118:121], v[14:17], v[178:181], v[118:121]
	v_mfma_f32_16x16x32_bf16 v[114:117], v[18:21], v[178:181], v[114:117]
	v_mfma_f32_16x16x32_bf16 v[82:85], v[18:21], v[214:217], v[198:201]
	v_mfma_f32_16x16x32_bf16 v[54:57], v[14:17], v[218:221], v[202:205]
	v_mfma_f32_16x16x32_bf16 v[50:53], v[18:21], v[218:221], v[206:209]
	v_mfma_f32_16x16x32_bf16 v[18:21], v[18:21], v[222:225], v[190:193]
	v_mfma_f32_16x16x32_bf16 v[110:113], v[194:197], v[178:181], v[102:105]
	v_mfma_f32_16x16x32_bf16 v[106:109], v[226:229], v[178:181], v[98:101]
	v_mfma_f32_16x16x32_bf16 v[78:81], v[194:197], v[214:217], v[74:77]
	v_mfma_f32_16x16x32_bf16 v[74:77], v[226:229], v[214:217], v[66:69]
	v_mfma_f32_16x16x32_bf16 v[46:49], v[194:197], v[218:221], v[46:49]
	v_mfma_f32_16x16x32_bf16 v[42:45], v[226:229], v[218:221], v[210:213]
	v_mfma_f32_16x16x32_bf16 v[14:17], v[194:197], v[222:225], v[10:13]
	v_mfma_f32_16x16x32_bf16 v[6:9], v[226:229], v[222:225], v[6:9]
	v_mov_b32_e32 v130, v1
	s_waitcnt vmcnt(0) lgkmcnt(0)
	s_barrier
; __device__ __forceinline__ unsigned pack2(float a, float b) { unsigned r; asm("v_cvt_pk_bf16_f32 %0, %1, %2" : "=v"(r) : "v"(a), "v"(b)); return r; }
; __device__ __forceinline__ float bf2f(bf16_t h) { return __uint_as_float(((unsigned)h) << 16); }
;   __device__ __forceinline__ void c4(int g, int rig, int col, f32x4 v) const {
;     const size_t o = ((size_t)g * 2048 + rig) * 1024 + col;
;     f32x4 bs;
;     if (BASE_F32) bs = __builtin_nontemporal_load((const f32x4*)((const float*)base + o));
;     else {
;       const uint2 u = *(const uint2*)((const bf16_t*)base + o);
;       bs[0] = bf2f((bf16_t)(u.x & 0xffff)); bs[1] = bf2f((bf16_t)(u.x >> 16)); bs[2] = bf2f((bf16_t)(u.y & 0xffff)); bs[3] = bf2f((bf16_t)(u.y >> 16));
;     }
;     const f32x4 gt = *(const f32x4*)(gate + (size_t)g * 6144 + col);
;     f32x4 bi = {0.f, 0.f, 0.f, 0.f};
;     if (bias) bi = *(const f32x4*)(bias + col);
;     f32x4 r;
; #pragma unroll
;     for (int j = 0; j < 4; ++j) r[j] = bs[j] + gt[j] * (v[j] + bi[j]);
;     uint2 w; w.x = pack2(r[0], r[1]); w.y = pack2(r[2], r[3]);
;     *(uint2*)(X16 + o) = w;
;   }
; template <bool SWAP, class Epi, bool THIN = false> ...
;     ...
;     if constexpr (Epi::KIND == 0) {
; #pragma unroll
;       for (int m = 0; m < 4; ++m) {
;         const int rig = rig0 + rw + m * 16 + fr_e;
;         if constexpr (Epi::ROWSUM) {
;           float ss = 0.f;
; #pragma unroll
;           for (int n = 0; n < 8; ++n) {
;             const int col = nt * 256 + wc_e * 128 + n * 16 + fq_e * 4;
;             if (col < N) ss += epi.c4(g, rig, col, acc[m][n]);
;           }
;           ss += __shfl_xor(ss, 16); ss += __shfl_xor(ss, 32);
;           if (fq_e == 0) epi.rowsum(g, rig, nt * 2 + wc_e, ss);
;         } else {
; #pragma unroll
;           for (int n = 0; n < 8; ++n) {
;             const int col = nt * 256 + wc_e * 128 + n * 16 + fq_e * 4;
;             if (col < N) epi.c4(g, rig, col, acc[m][n]);
;           }
;         }
	v_mfma_f32_16x16x32_bf16 v[98:101], v[186:189], v[178:181], v[132:135]
	v_ashrrev_i32_e32 v11, 8, v130
	v_add_u32_e32 v11, s5, v11
	v_ashrrev_i32_e32 v12, 31, v11
	v_lshrrev_b32_e32 v12, 28, v12
	v_add_u32_e32 v12, v11, v12
	v_ashrrev_i32_e32 v134, 4, v12
	v_lshlrev_b32_e32 v12, 11, v134
	v_lshlrev_b32_e32 v11, 7, v11
	v_sub_u32_e32 v11, v11, v12
	v_lshrrev_b32_e32 v12, 1, v130
	v_and_b32_e32 v10, 15, v130
	v_and_b32_e32 v12, 64, v12
	v_mfma_f32_16x16x32_bf16 v[102:105], v[182:185], v[178:181], v[70:73]
	v_ashrrev_i32_e32 v135, 31, v134
	v_mfma_f32_16x16x32_bf16 v[70:73], v[182:185], v[214:217], v[38:41]
	v_mfma_f32_16x16x32_bf16 v[38:41], v[182:185], v[218:221], v[136:139]
	s_nop 2
	v_or3_b32 v136, v11, v12, v10
	v_lshlrev_b32_e32 v10, 1, v130
	v_and_b32_e32 v132, 0x80, v10
	v_mfma_f32_16x16x32_bf16 v[10:13], v[182:185], v[222:225], v[2:5]
	v_ashrrev_i32_e32 v137, 31, v136
	v_lshlrev_b64 v[138:139], 21, v[134:135]
	v_lshlrev_b64 v[140:141], 10, v[136:137]
	v_lshrrev_b32_e32 v2, 2, v130
	v_and_b32_e32 v2, 12, v2
	v_mfma_f32_16x16x32_bf16 v[66:69], v[186:189], v[214:217], v[34:37]
	v_or3_b32 v132, v2, v132, s4
	v_bfe_u32 v246, v130, 4, 1
	v_mul_u32_u24_e32 v246, 24, v246
	v_mov_b32_e32 v247, 0
	v_mad_i64_i32 v[134:135], s[4:5], v134, s33, 0
	v_mfma_f32_16x16x32_bf16 v[34:37], v[186:189], v[218:221], v[170:173]
	v_lshl_add_u64 v[140:141], v[140:141], 0, v[138:139]
	v_cmp_gt_i32_e32 vcc, s34, v132
	v_ashrrev_i32_e32 v133, 31, v132
	v_mfma_f32_16x16x32_bf16 v[2:5], v[186:189], v[222:225], v[174:177]
	v_lshl_add_u64 v[134:135], s[26:27], 0, v[134:135]
	v_lshl_add_u64 v[168:169], v[132:133], 2, v[134:135]
	global_load_dwordx4 v[180:183], v[168:169], off
	global_load_dwordx4 v[184:187], v[168:169], off offset:64
	global_load_dwordx4 v[188:191], v[168:169], off offset:128
	global_load_dwordx4 v[192:195], v[168:169], off offset:192
	global_load_dwordx4 v[196:199], v[168:169], off offset:256
	global_load_dwordx4 v[200:203], v[168:169], off offset:320
	global_load_dwordx4 v[204:207], v[168:169], off offset:384
	global_load_dwordx4 v[208:211], v[168:169], off offset:448
	v_lshl_add_u64 v[178:179], v[140:141], 0, v[132:133]
	v_lshl_add_u64 v[244:245], v[140:141], 0, v[132:133]
	v_lshl_add_u64 v[244:245], v[244:245], 2, s[22:23]
	global_load_dwordx4 v[212:215], v[244:245], off nt
	global_load_dwordx4 v[216:219], v[244:245], off offset:64 nt
	global_load_dwordx4 v[220:223], v[244:245], off offset:128 nt
	global_load_dwordx4 v[224:227], v[244:245], off offset:192 nt
	global_load_dwordx4 v[228:231], v[244:245], off offset:256 nt
	global_load_dwordx4 v[232:235], v[244:245], off offset:320 nt
	global_load_dwordx4 v[236:239], v[244:245], off offset:384 nt
	global_load_dwordx4 v[240:243], v[244:245], off offset:448 nt
	s_nop 0
	v_add_f32_e32 v126, 0, v126
	v_add_f32_e32 v127, 0, v127
	v_add_f32_e32 v128, 0, v128
	v_add_f32_e32 v129, 0, v129
	s_waitcnt vmcnt(7)
	v_fma_f32 v126, v126, v180, v212
	v_fma_f32 v127, v127, v181, v213
	v_fma_f32 v128, v128, v182, v214
	v_fma_f32 v177, v129, v183, v215
	v_cvt_pk_bf16_f32 v126, v126, v127
	v_cvt_pk_bf16_f32 v127, v128, v177
	v_lshl_add_u64 v[174:175], v[140:141], 0, v[132:133]
	s_nop 0
	v_add_f32_e32 v122, 0, v122
	v_add_f32_e32 v123, 0, v123
	v_add_f32_e32 v124, 0, v124
	v_add_f32_e32 v125, 0, v125
	s_waitcnt vmcnt(6)
	v_fma_f32 v122, v122, v184, v216
	v_fma_f32 v123, v123, v185, v217
	v_fma_f32 v124, v124, v186, v218
	v_fma_f32 v173, v125, v187, v219
	v_cvt_pk_bf16_f32 v128, v122, v123
	v_cvt_pk_bf16_f32 v129, v124, v173
	v_lshl_add_u64 v[124:125], v[174:175], 1, s[20:21]
	s_nop 1
	v_permlane16_swap_b32 v126, v128
	v_permlane16_swap_b32 v127, v129
	v_lshl_add_u64 v[248:249], v[124:125], 0, v[246:247]
	s_nop 0
	global_store_dwordx4 v[248:249], v[126:129], off
	s_nop 1
	v_or_b32_e32 v122, 32, v132
	v_lshl_add_u64 v[170:171], v[140:141], 0, v[132:133]
	s_nop 0
	v_add_f32_e32 v118, 0, v118
	v_add_f32_e32 v119, 0, v119
	v_add_f32_e32 v120, 0, v120
	v_add_f32_e32 v121, 0, v121
	s_waitcnt vmcnt(6)
	v_fma_f32 v118, v118, v188, v220
	v_fma_f32 v119, v119, v189, v221
	v_fma_f32 v120, v120, v190, v222
	v_fma_f32 v129, v121, v191, v223
	v_cvt_pk_bf16_f32 v118, v118, v119
	v_cvt_pk_bf16_f32 v119, v120, v129
	v_lshl_add_u64 v[126:127], v[140:141], 0, v[132:133]
	s_nop 0
	v_add_f32_e32 v114, 0, v114
	v_add_f32_e32 v115, 0, v115
	v_add_f32_e32 v116, 0, v116
	v_add_f32_e32 v117, 0, v117
	s_waitcnt vmcnt(5)
	v_fma_f32 v114, v114, v192, v224
	v_fma_f32 v115, v115, v193, v225
	v_fma_f32 v116, v116, v194, v226
	v_fma_f32 v125, v117, v195, v227
	v_cvt_pk_bf16_f32 v120, v114, v115
	v_cvt_pk_bf16_f32 v121, v116, v125
	v_lshl_add_u64 v[116:117], v[126:127], 1, s[20:21]
	s_nop 1
	v_permlane16_swap_b32 v118, v120
	v_permlane16_swap_b32 v119, v121
	v_lshl_add_u64 v[248:249], v[116:117], 0, v[246:247]
	s_nop 0
	global_store_dwordx4 v[248:249], v[118:121], off offset:64
	s_nop 1
	v_or_b32_e32 v114, 64, v132
	v_lshl_add_u64 v[122:123], v[140:141], 0, v[132:133]
	s_nop 0
	v_add_f32_e32 v110, 0, v110
	v_add_f32_e32 v111, 0, v111
	v_add_f32_e32 v112, 0, v112
	v_add_f32_e32 v113, 0, v113
	s_waitcnt vmcnt(5)
	v_fma_f32 v110, v110, v196, v228
	v_fma_f32 v111, v111, v197, v229
	v_fma_f32 v112, v112, v198, v230
	v_fma_f32 v121, v113, v199, v231
	v_cvt_pk_bf16_f32 v110, v110, v111
	v_cvt_pk_bf16_f32 v111, v112, v121
	v_lshl_add_u64 v[118:119], v[140:141], 0, v[132:133]
	s_nop 0
	v_add_f32_e32 v106, 0, v106
	v_add_f32_e32 v107, 0, v107
	v_add_f32_e32 v108, 0, v108
	v_add_f32_e32 v109, 0, v109
	s_waitcnt vmcnt(4)
; __device__ __forceinline__ unsigned pack2(float a, float b) { unsigned r; asm("v_cvt_pk_bf16_f32 %0, %1, %2" : "=v"(r) : "v"(a), "v"(b)); return r; }
; __device__ __forceinline__ float bf2f(bf16_t h) { return __uint_as_float(((unsigned)h) << 16); }
;   __device__ __forceinline__ void c4(int g, int rig, int col, f32x4 v) const {
;     const size_t o = ((size_t)g * 2048 + rig) * 1024 + col;
;     f32x4 bs;
;     if (BASE_F32) bs = __builtin_nontemporal_load((const f32x4*)((const float*)base + o));
;     else {
;       const uint2 u = *(const uint2*)((const bf16_t*)base + o);
;       bs[0] = bf2f((bf16_t)(u.x & 0xffff)); bs[1] = bf2f((bf16_t)(u.x >> 16)); bs[2] = bf2f((bf16_t)(u.y & 0xffff)); bs[3] = bf2f((bf16_t)(u.y >> 16));
;     }
;     const f32x4 gt = *(const f32x4*)(gate + (size_t)g * 6144 + col);
;     f32x4 bi = {0.f, 0.f, 0.f, 0.f};
;     if (bias) bi = *(const f32x4*)(bias + col);
;     f32x4 r;
; #pragma unroll
;     for (int j = 0; j < 4; ++j) r[j] = bs[j] + gt[j] * (v[j] + bi[j]);
;     uint2 w; w.x = pack2(r[0], r[1]); w.y = pack2(r[2], r[3]);
;     *(uint2*)(X16 + o) = w;
;   }
; template <bool SWAP, class Epi, bool THIN = false> ...
;     ...
;     if constexpr (Epi::KIND == 0) {
; #pragma unroll
;       for (int m = 0; m < 4; ++m) {
;         const int rig = rig0 + rw + m * 16 + fr_e;
;         if constexpr (Epi::ROWSUM) {
;           float ss = 0.f;
; #pragma unroll
;           for (int n = 0; n < 8; ++n) {
;             const int col = nt * 256 + wc_e * 128 + n * 16 + fq_e * 4;
;             if (col < N) ss += epi.c4(g, rig, col, acc[m][n]);
;           }
;           ss += __shfl_xor(ss, 16); ss += __shfl_xor(ss, 32);
;           if (fq_e == 0) epi.rowsum(g, rig, nt * 2 + wc_e, ss);
;         } else {
; #pragma unroll
;           for (int n = 0; n < 8; ++n) {
;             const int col = nt * 256 + wc_e * 128 + n * 16 + fq_e * 4;
;             if (col < N) epi.c4(g, rig, col, acc[m][n]);
;           }
;         }
	v_fma_f32 v106, v106, v200, v232
	v_fma_f32 v107, v107, v201, v233
	v_fma_f32 v108, v108, v202, v234
	v_fma_f32 v117, v109, v203, v235
	v_cvt_pk_bf16_f32 v112, v106, v107
	v_cvt_pk_bf16_f32 v113, v108, v117
	v_lshl_add_u64 v[108:109], v[118:119], 1, s[20:21]
	s_nop 1
	v_permlane16_swap_b32 v110, v112
	v_permlane16_swap_b32 v111, v113
	v_lshl_add_u64 v[248:249], v[108:109], 0, v[246:247]
	s_nop 0
	global_store_dwordx4 v[248:249], v[110:113], off offset:128
	s_nop 1
	v_or_b32_e32 v106, 0x60, v132
	v_lshl_add_u64 v[114:115], v[140:141], 0, v[132:133]
	s_nop 0
	v_add_f32_e32 v102, 0, v102
	v_add_f32_e32 v103, 0, v103
	v_add_f32_e32 v104, 0, v104
	v_add_f32_e32 v105, 0, v105
	s_waitcnt vmcnt(4)
	v_fma_f32 v102, v102, v204, v236
	v_fma_f32 v103, v103, v205, v237
	v_fma_f32 v104, v104, v206, v238
	v_fma_f32 v113, v105, v207, v239
	v_cvt_pk_bf16_f32 v102, v102, v103
	v_cvt_pk_bf16_f32 v103, v104, v113
	v_lshl_add_u64 v[110:111], v[140:141], 0, v[132:133]
	s_nop 0
	v_add_f32_e32 v98, 0, v98
	v_add_f32_e32 v99, 0, v99
	v_add_f32_e32 v100, 0, v100
	v_add_f32_e32 v101, 0, v101
	s_waitcnt vmcnt(3)
	v_fma_f32 v98, v98, v208, v240
	v_fma_f32 v99, v99, v209, v241
	v_fma_f32 v100, v100, v210, v242
	v_fma_f32 v109, v101, v211, v243
	v_cvt_pk_bf16_f32 v104, v98, v99
	v_cvt_pk_bf16_f32 v105, v100, v109
	v_lshl_add_u64 v[100:101], v[110:111], 1, s[20:21]
	s_nop 1
	v_permlane16_swap_b32 v102, v104
	v_permlane16_swap_b32 v103, v105
	v_lshl_add_u64 v[248:249], v[100:101], 0, v[246:247]
	s_nop 0
	global_store_dwordx4 v[248:249], v[102:105], off offset:192
	s_nop 1
	v_or_b32_e32 v98, 16, v136
	v_ashrrev_i32_e32 v99, 31, v98
	v_lshlrev_b64 v[98:99], 10, v[98:99]
	v_lshl_add_u64 v[98:99], v[98:99], 0, v[138:139]
	v_lshl_add_u64 v[108:109], v[98:99], 0, v[132:133]
	v_lshl_add_u64 v[244:245], v[98:99], 0, v[132:133]
	v_lshl_add_u64 v[244:245], v[244:245], 2, s[22:23]
	global_load_dwordx4 v[212:215], v[244:245], off nt
	global_load_dwordx4 v[216:219], v[244:245], off offset:64 nt
	global_load_dwordx4 v[220:223], v[244:245], off offset:128 nt
	global_load_dwordx4 v[224:227], v[244:245], off offset:192 nt
	global_load_dwordx4 v[228:231], v[244:245], off offset:256 nt
	global_load_dwordx4 v[232:235], v[244:245], off offset:320 nt
	global_load_dwordx4 v[236:239], v[244:245], off offset:384 nt
	global_load_dwordx4 v[240:243], v[244:245], off offset:448 nt
	s_nop 0
	v_add_f32_e32 v94, 0, v94
	v_add_f32_e32 v95, 0, v95
	v_add_f32_e32 v96, 0, v96
	v_add_f32_e32 v97, 0, v97
	s_waitcnt vmcnt(7)
	v_fma_f32 v94, v94, v180, v212
	v_fma_f32 v95, v95, v181, v213
	v_fma_f32 v96, v96, v182, v214
	v_fma_f32 v107, v97, v183, v215
	v_cvt_pk_bf16_f32 v94, v94, v95
	v_cvt_pk_bf16_f32 v95, v96, v107
	v_lshl_add_u64 v[104:105], v[98:99], 0, v[132:133]
	s_nop 0
	v_add_f32_e32 v90, 0, v90
	v_add_f32_e32 v91, 0, v91
	v_add_f32_e32 v92, 0, v92
	v_add_f32_e32 v93, 0, v93
	s_waitcnt vmcnt(6)
	v_fma_f32 v90, v90, v184, v216
	v_fma_f32 v91, v91, v185, v217
	v_fma_f32 v92, v92, v186, v218
	v_fma_f32 v103, v93, v187, v219
	v_cvt_pk_bf16_f32 v96, v90, v91
	v_cvt_pk_bf16_f32 v97, v92, v103
	v_lshl_add_u64 v[92:93], v[104:105], 1, s[20:21]
	s_nop 1
	v_permlane16_swap_b32 v94, v96
	v_permlane16_swap_b32 v95, v97
	v_lshl_add_u64 v[248:249], v[92:93], 0, v[246:247]
	s_nop 0
	global_store_dwordx4 v[248:249], v[94:97], off
	s_nop 1
	v_lshl_add_u64 v[100:101], v[98:99], 0, v[132:133]
	s_nop 0
	v_add_f32_e32 v86, 0, v86
	v_add_f32_e32 v87, 0, v87
	v_add_f32_e32 v88, 0, v88
	v_add_f32_e32 v89, 0, v89
	s_waitcnt vmcnt(6)
	v_fma_f32 v86, v86, v188, v220
	v_fma_f32 v87, v87, v189, v221
	v_fma_f32 v88, v88, v190, v222
	v_fma_f32 v97, v89, v191, v223
	v_cvt_pk_bf16_f32 v86, v86, v87
	v_cvt_pk_bf16_f32 v87, v88, v97
	v_lshl_add_u64 v[94:95], v[98:99], 0, v[132:133]
	s_nop 0
	v_add_f32_e32 v82, 0, v82
	v_add_f32_e32 v83, 0, v83
	v_add_f32_e32 v84, 0, v84
	v_add_f32_e32 v85, 0, v85
	s_waitcnt vmcnt(5)
	v_fma_f32 v82, v82, v192, v224
	v_fma_f32 v83, v83, v193, v225
	v_fma_f32 v84, v84, v194, v226
	v_fma_f32 v93, v85, v195, v227
	v_cvt_pk_bf16_f32 v88, v82, v83
	v_cvt_pk_bf16_f32 v89, v84, v93
	v_lshl_add_u64 v[84:85], v[94:95], 1, s[20:21]
	s_nop 1
	v_permlane16_swap_b32 v86, v88
	v_permlane16_swap_b32 v87, v89
	v_lshl_add_u64 v[248:249], v[84:85], 0, v[246:247]
	s_nop 0
	global_store_dwordx4 v[248:249], v[86:89], off offset:64
	s_nop 1
	v_lshl_add_u64 v[90:91], v[98:99], 0, v[132:133]
	s_nop 0
	v_add_f32_e32 v78, 0, v78
	v_add_f32_e32 v79, 0, v79
	v_add_f32_e32 v80, 0, v80
	v_add_f32_e32 v81, 0, v81
	s_waitcnt vmcnt(5)
	v_fma_f32 v78, v78, v196, v228
	v_fma_f32 v79, v79, v197, v229
	v_fma_f32 v80, v80, v198, v230
	v_fma_f32 v89, v81, v199, v231
	v_cvt_pk_bf16_f32 v78, v78, v79
	v_cvt_pk_bf16_f32 v79, v80, v89
	v_lshl_add_u64 v[86:87], v[98:99], 0, v[132:133]
	s_nop 0
	v_add_f32_e32 v74, 0, v74
	v_add_f32_e32 v75, 0, v75
	v_add_f32_e32 v76, 0, v76
	v_add_f32_e32 v77, 0, v77
	s_waitcnt vmcnt(4)
	v_fma_f32 v74, v74, v200, v232
	v_fma_f32 v75, v75, v201, v233
	v_fma_f32 v76, v76, v202, v234
	v_fma_f32 v85, v77, v203, v235
	v_cvt_pk_bf16_f32 v80, v74, v75
	v_cvt_pk_bf16_f32 v81, v76, v85
	v_lshl_add_u64 v[76:77], v[86:87], 1, s[20:21]
	s_nop 1
	v_permlane16_swap_b32 v78, v80
	v_permlane16_swap_b32 v79, v81
	v_lshl_add_u64 v[248:249], v[76:77], 0, v[246:247]
	s_nop 0
	global_store_dwordx4 v[248:249], v[78:81], off offset:128
	s_nop 1
	v_lshl_add_u64 v[82:83], v[98:99], 0, v[132:133]
	v_add_f32_e32 v70, 0, v70
	v_add_f32_e32 v71, 0, v71
	v_add_f32_e32 v72, 0, v72
	v_add_f32_e32 v73, 0, v73
	s_waitcnt vmcnt(4)
; __device__ __forceinline__ unsigned pack2(float a, float b) { unsigned r; asm("v_cvt_pk_bf16_f32 %0, %1, %2" : "=v"(r) : "v"(a), "v"(b)); return r; }
; __device__ __forceinline__ float bf2f(bf16_t h) { return __uint_as_float(((unsigned)h) << 16); }
;   __device__ __forceinline__ void c4(int g, int rig, int col, f32x4 v) const {
;     const size_t o = ((size_t)g * 2048 + rig) * 1024 + col;
;     f32x4 bs;
;     if (BASE_F32) bs = __builtin_nontemporal_load((const f32x4*)((const float*)base + o));
;     else {
;       const uint2 u = *(const uint2*)((const bf16_t*)base + o);
;       bs[0] = bf2f((bf16_t)(u.x & 0xffff)); bs[1] = bf2f((bf16_t)(u.x >> 16)); bs[2] = bf2f((bf16_t)(u.y & 0xffff)); bs[3] = bf2f((bf16_t)(u.y >> 16));
;     }
;     const f32x4 gt = *(const f32x4*)(gate + (size_t)g * 6144 + col);
;     f32x4 bi = {0.f, 0.f, 0.f, 0.f};
;     if (bias) bi = *(const f32x4*)(bias + col);
;     f32x4 r;
; #pragma unroll
;     for (int j = 0; j < 4; ++j) r[j] = bs[j] + gt[j] * (v[j] + bi[j]);
;     uint2 w; w.x = pack2(r[0], r[1]); w.y = pack2(r[2], r[3]);
;     *(uint2*)(X16 + o) = w;
;   }
; template <bool SWAP, class Epi, bool THIN = false> ...
;     ...
;     if constexpr (Epi::KIND == 0) {
; #pragma unroll
;       for (int m = 0; m < 4; ++m) {
;         const int rig = rig0 + rw + m * 16 + fr_e;
;         if constexpr (Epi::ROWSUM) {
;           float ss = 0.f;
; #pragma unroll
;           for (int n = 0; n < 8; ++n) {
;             const int col = nt * 256 + wc_e * 128 + n * 16 + fq_e * 4;
;             if (col < N) ss += epi.c4(g, rig, col, acc[m][n]);
;           }
;           ss += __shfl_xor(ss, 16); ss += __shfl_xor(ss, 32);
;           if (fq_e == 0) epi.rowsum(g, rig, nt * 2 + wc_e, ss);
;         } else {
; #pragma unroll
;           for (int n = 0; n < 8; ++n) {
;             const int col = nt * 256 + wc_e * 128 + n * 16 + fq_e * 4;
;             if (col < N) epi.c4(g, rig, col, acc[m][n]);
;           }
;         }
	v_fma_f32 v70, v70, v204, v236
	v_fma_f32 v71, v71, v205, v237
	v_fma_f32 v72, v72, v206, v238
	v_fma_f32 v81, v73, v207, v239
	v_cvt_pk_bf16_f32 v70, v70, v71
	v_cvt_pk_bf16_f32 v71, v72, v81
	v_lshl_add_u64 v[78:79], v[98:99], 0, v[132:133]
	v_add_f32_e32 v66, 0, v66
	v_add_f32_e32 v67, 0, v67
	v_add_f32_e32 v68, 0, v68
	v_add_f32_e32 v69, 0, v69
	s_waitcnt vmcnt(3)
	v_fma_f32 v66, v66, v208, v240
	v_fma_f32 v67, v67, v209, v241
	v_fma_f32 v68, v68, v210, v242
	v_fma_f32 v77, v69, v211, v243
	v_cvt_pk_bf16_f32 v72, v66, v67
	v_cvt_pk_bf16_f32 v73, v68, v77
	v_lshl_add_u64 v[68:69], v[78:79], 1, s[20:21]
	s_nop 1
	v_permlane16_swap_b32 v70, v72
	v_permlane16_swap_b32 v71, v73
	v_lshl_add_u64 v[248:249], v[68:69], 0, v[246:247]
	s_nop 0
	global_store_dwordx4 v[248:249], v[70:73], off offset:192
	s_nop 1
	v_or_b32_e32 v66, 32, v136
	v_ashrrev_i32_e32 v67, 31, v66
	v_lshlrev_b64 v[66:67], 10, v[66:67]
	v_lshl_add_u64 v[66:67], v[66:67], 0, v[138:139]
	v_lshl_add_u64 v[76:77], v[66:67], 0, v[132:133]
	v_lshl_add_u64 v[244:245], v[66:67], 0, v[132:133]
	v_lshl_add_u64 v[244:245], v[244:245], 2, s[22:23]
	global_load_dwordx4 v[212:215], v[244:245], off nt
	global_load_dwordx4 v[216:219], v[244:245], off offset:64 nt
	global_load_dwordx4 v[220:223], v[244:245], off offset:128 nt
	global_load_dwordx4 v[224:227], v[244:245], off offset:192 nt
	global_load_dwordx4 v[228:231], v[244:245], off offset:256 nt
	global_load_dwordx4 v[232:235], v[244:245], off offset:320 nt
	global_load_dwordx4 v[236:239], v[244:245], off offset:384 nt
	global_load_dwordx4 v[240:243], v[244:245], off offset:448 nt
	v_add_f32_e32 v62, 0, v62
	v_add_f32_e32 v63, 0, v63
	v_add_f32_e32 v64, 0, v64
	v_add_f32_e32 v65, 0, v65
	s_waitcnt vmcnt(7)
	v_fma_f32 v62, v62, v180, v212
	v_fma_f32 v63, v63, v181, v213
	v_fma_f32 v64, v64, v182, v214
	v_fma_f32 v75, v65, v183, v215
	v_cvt_pk_bf16_f32 v62, v62, v63
	v_cvt_pk_bf16_f32 v63, v64, v75
	v_lshl_add_u64 v[72:73], v[66:67], 0, v[132:133]
	v_add_f32_e32 v58, 0, v58
	v_add_f32_e32 v59, 0, v59
	v_add_f32_e32 v60, 0, v60
	v_add_f32_e32 v61, 0, v61
	s_waitcnt vmcnt(6)
	v_fma_f32 v58, v58, v184, v216
	v_fma_f32 v59, v59, v185, v217
	v_fma_f32 v60, v60, v186, v218
	v_fma_f32 v71, v61, v187, v219
	v_cvt_pk_bf16_f32 v64, v58, v59
	v_cvt_pk_bf16_f32 v65, v60, v71
	v_lshl_add_u64 v[60:61], v[72:73], 1, s[20:21]
	s_nop 1
	v_permlane16_swap_b32 v62, v64
	v_permlane16_swap_b32 v63, v65
	v_lshl_add_u64 v[248:249], v[60:61], 0, v[246:247]
	s_nop 0
	global_store_dwordx4 v[248:249], v[62:65], off
	s_nop 1
	v_lshl_add_u64 v[68:69], v[66:67], 0, v[132:133]
	v_add_f32_e32 v54, 0, v54
	v_add_f32_e32 v55, 0, v55
	v_add_f32_e32 v56, 0, v56
	v_add_f32_e32 v57, 0, v57
	s_waitcnt vmcnt(6)
	v_fma_f32 v54, v54, v188, v220
	v_fma_f32 v55, v55, v189, v221
	v_fma_f32 v56, v56, v190, v222
	v_fma_f32 v65, v57, v191, v223
	v_cvt_pk_bf16_f32 v54, v54, v55
	v_cvt_pk_bf16_f32 v55, v56, v65
	v_lshl_add_u64 v[62:63], v[66:67], 0, v[132:133]
	v_add_f32_e32 v50, 0, v50
	v_add_f32_e32 v51, 0, v51
	v_add_f32_e32 v52, 0, v52
	v_add_f32_e32 v53, 0, v53
	s_waitcnt vmcnt(5)
	v_fma_f32 v50, v50, v192, v224
	v_fma_f32 v51, v51, v193, v225
	v_fma_f32 v52, v52, v194, v226
	v_fma_f32 v61, v53, v195, v227
	v_cvt_pk_bf16_f32 v56, v50, v51
	v_cvt_pk_bf16_f32 v57, v52, v61
	v_lshl_add_u64 v[52:53], v[62:63], 1, s[20:21]
	s_nop 1
	v_permlane16_swap_b32 v54, v56
	v_permlane16_swap_b32 v55, v57
	v_lshl_add_u64 v[248:249], v[52:53], 0, v[246:247]
	s_nop 0
	global_store_dwordx4 v[248:249], v[54:57], off offset:64
	s_nop 1
	v_lshl_add_u64 v[58:59], v[66:67], 0, v[132:133]
	v_add_f32_e32 v46, 0, v46
	v_add_f32_e32 v47, 0, v47
	v_add_f32_e32 v48, 0, v48
	v_add_f32_e32 v49, 0, v49
	s_waitcnt vmcnt(5)
	v_fma_f32 v46, v46, v196, v228
	v_fma_f32 v47, v47, v197, v229
	v_fma_f32 v48, v48, v198, v230
	v_fma_f32 v57, v49, v199, v231
	v_cvt_pk_bf16_f32 v46, v46, v47
	v_cvt_pk_bf16_f32 v47, v48, v57
	v_lshl_add_u64 v[54:55], v[66:67], 0, v[132:133]
	v_add_f32_e32 v42, 0, v42
	v_add_f32_e32 v43, 0, v43
	v_add_f32_e32 v44, 0, v44
	v_add_f32_e32 v45, 0, v45
	s_waitcnt vmcnt(4)
	v_fma_f32 v42, v42, v200, v232
	v_fma_f32 v43, v43, v201, v233
	v_fma_f32 v44, v44, v202, v234
	v_fma_f32 v53, v45, v203, v235
	v_cvt_pk_bf16_f32 v48, v42, v43
	v_cvt_pk_bf16_f32 v49, v44, v53
	v_lshl_add_u64 v[44:45], v[54:55], 1, s[20:21]
	s_nop 1
	v_permlane16_swap_b32 v46, v48
	v_permlane16_swap_b32 v47, v49
	v_lshl_add_u64 v[248:249], v[44:45], 0, v[246:247]
	s_nop 0
	global_store_dwordx4 v[248:249], v[46:49], off offset:128
	s_nop 1
	v_lshl_add_u64 v[50:51], v[66:67], 0, v[132:133]
	v_add_f32_e32 v38, 0, v38
	v_add_f32_e32 v39, 0, v39
	v_add_f32_e32 v40, 0, v40
	v_add_f32_e32 v41, 0, v41
	s_waitcnt vmcnt(4)
	v_fma_f32 v38, v38, v204, v236
	v_fma_f32 v39, v39, v205, v237
	v_fma_f32 v40, v40, v206, v238
	v_fma_f32 v49, v41, v207, v239
	v_cvt_pk_bf16_f32 v38, v38, v39
	v_cvt_pk_bf16_f32 v39, v40, v49
	v_lshl_add_u64 v[46:47], v[66:67], 0, v[132:133]
	v_add_f32_e32 v34, 0, v34
	v_add_f32_e32 v35, 0, v35
	v_add_f32_e32 v36, 0, v36
	v_add_f32_e32 v37, 0, v37
	s_waitcnt vmcnt(3)
; __device__ __forceinline__ unsigned pack2(float a, float b) { unsigned r; asm("v_cvt_pk_bf16_f32 %0, %1, %2" : "=v"(r) : "v"(a), "v"(b)); return r; }
; __device__ __forceinline__ float bf2f(bf16_t h) { return __uint_as_float(((unsigned)h) << 16); }
;   __device__ __forceinline__ void c4(int g, int rig, int col, f32x4 v) const {
;     const size_t o = ((size_t)g * 2048 + rig) * 1024 + col;
;     f32x4 bs;
;     if (BASE_F32) bs = __builtin_nontemporal_load((const f32x4*)((const float*)base + o));
;     else {
;       const uint2 u = *(const uint2*)((const bf16_t*)base + o);
;       bs[0] = bf2f((bf16_t)(u.x & 0xffff)); bs[1] = bf2f((bf16_t)(u.x >> 16)); bs[2] = bf2f((bf16_t)(u.y & 0xffff)); bs[3] = bf2f((bf16_t)(u.y >> 16));
;     }
;     const f32x4 gt = *(const f32x4*)(gate + (size_t)g * 6144 + col);
;     f32x4 bi = {0.f, 0.f, 0.f, 0.f};
;     if (bias) bi = *(const f32x4*)(bias + col);
;     f32x4 r;
; #pragma unroll
;     for (int j = 0; j < 4; ++j) r[j] = bs[j] + gt[j] * (v[j] + bi[j]);
;     uint2 w; w.x = pack2(r[0], r[1]); w.y = pack2(r[2], r[3]);
;     *(uint2*)(X16 + o) = w;
;   }
; template <bool SWAP, class Epi, bool THIN = false> ...
;     ...
;     if constexpr (Epi::KIND == 0) {
; #pragma unroll
;       for (int m = 0; m < 4; ++m) {
;         const int rig = rig0 + rw + m * 16 + fr_e;
;         if constexpr (Epi::ROWSUM) {
;           float ss = 0.f;
; #pragma unroll
;           for (int n = 0; n < 8; ++n) {
;             const int col = nt * 256 + wc_e * 128 + n * 16 + fq_e * 4;
;             if (col < N) ss += epi.c4(g, rig, col, acc[m][n]);
;           }
;           ss += __shfl_xor(ss, 16); ss += __shfl_xor(ss, 32);
;           if (fq_e == 0) epi.rowsum(g, rig, nt * 2 + wc_e, ss);
;         } else {
; #pragma unroll
;           for (int n = 0; n < 8; ++n) {
;             const int col = nt * 256 + wc_e * 128 + n * 16 + fq_e * 4;
;             if (col < N) epi.c4(g, rig, col, acc[m][n]);
;           }
;         }
	v_fma_f32 v34, v34, v208, v240
	v_fma_f32 v35, v35, v209, v241
	v_fma_f32 v36, v36, v210, v242
	v_fma_f32 v45, v37, v211, v243
	v_cvt_pk_bf16_f32 v40, v34, v35
	v_cvt_pk_bf16_f32 v41, v36, v45
	v_lshl_add_u64 v[36:37], v[46:47], 1, s[20:21]
	s_nop 1
	v_permlane16_swap_b32 v38, v40
	v_permlane16_swap_b32 v39, v41
	v_lshl_add_u64 v[248:249], v[36:37], 0, v[246:247]
	s_nop 0
	global_store_dwordx4 v[248:249], v[38:41], off offset:192
	s_nop 1
	v_or_b32_e32 v34, 48, v136
	v_ashrrev_i32_e32 v35, 31, v34
	v_lshlrev_b64 v[34:35], 10, v[34:35]
	v_lshl_add_u64 v[34:35], v[34:35], 0, v[138:139]
	v_lshl_add_u64 v[44:45], v[34:35], 0, v[132:133]
	v_lshl_add_u64 v[244:245], v[34:35], 0, v[132:133]
	v_lshl_add_u64 v[244:245], v[244:245], 2, s[22:23]
	global_load_dwordx4 v[212:215], v[244:245], off nt
	global_load_dwordx4 v[216:219], v[244:245], off offset:64 nt
	global_load_dwordx4 v[220:223], v[244:245], off offset:128 nt
	global_load_dwordx4 v[224:227], v[244:245], off offset:192 nt
	global_load_dwordx4 v[228:231], v[244:245], off offset:256 nt
	global_load_dwordx4 v[232:235], v[244:245], off offset:320 nt
	global_load_dwordx4 v[236:239], v[244:245], off offset:384 nt
	global_load_dwordx4 v[240:243], v[244:245], off offset:448 nt
	v_add_f32_e32 v30, 0, v30
	v_add_f32_e32 v31, 0, v31
	v_add_f32_e32 v32, 0, v32
	v_add_f32_e32 v33, 0, v33
	s_waitcnt vmcnt(7)
	v_fma_f32 v30, v30, v180, v212
	v_fma_f32 v31, v31, v181, v213
	v_fma_f32 v32, v32, v182, v214
	v_fma_f32 v43, v33, v183, v215
	v_cvt_pk_bf16_f32 v30, v30, v31
	v_cvt_pk_bf16_f32 v31, v32, v43
	v_lshl_add_u64 v[40:41], v[34:35], 0, v[132:133]
	v_add_f32_e32 v26, 0, v26
	v_add_f32_e32 v27, 0, v27
	v_add_f32_e32 v28, 0, v28
	v_add_f32_e32 v29, 0, v29
	s_waitcnt vmcnt(6)
	v_fma_f32 v26, v26, v184, v216
	v_fma_f32 v27, v27, v185, v217
	v_fma_f32 v28, v28, v186, v218
	v_fma_f32 v39, v29, v187, v219
	v_cvt_pk_bf16_f32 v32, v26, v27
	v_cvt_pk_bf16_f32 v33, v28, v39
	v_lshl_add_u64 v[28:29], v[40:41], 1, s[20:21]
	s_nop 1
	v_permlane16_swap_b32 v30, v32
	v_permlane16_swap_b32 v31, v33
	v_lshl_add_u64 v[248:249], v[28:29], 0, v[246:247]
	s_nop 0
	global_store_dwordx4 v[248:249], v[30:33], off
	s_nop 1
	v_lshl_add_u64 v[36:37], v[34:35], 0, v[132:133]
	v_add_f32_e32 v22, 0, v22
	v_add_f32_e32 v23, 0, v23
	v_add_f32_e32 v24, 0, v24
	v_add_f32_e32 v25, 0, v25
	s_waitcnt vmcnt(6)
	v_fma_f32 v22, v22, v188, v220
	v_fma_f32 v23, v23, v189, v221
	v_fma_f32 v24, v24, v190, v222
	v_fma_f32 v33, v25, v191, v223
	v_cvt_pk_bf16_f32 v22, v22, v23
	v_cvt_pk_bf16_f32 v23, v24, v33
	v_lshl_add_u64 v[30:31], v[34:35], 0, v[132:133]
	v_add_f32_e32 v18, 0, v18
	v_add_f32_e32 v19, 0, v19
	v_add_f32_e32 v20, 0, v20
	v_add_f32_e32 v21, 0, v21
	s_waitcnt vmcnt(5)
	v_fma_f32 v18, v18, v192, v224
	v_fma_f32 v19, v19, v193, v225
	v_fma_f32 v20, v20, v194, v226
	v_fma_f32 v29, v21, v195, v227
	v_cvt_pk_bf16_f32 v24, v18, v19
	v_cvt_pk_bf16_f32 v25, v20, v29
	v_lshl_add_u64 v[20:21], v[30:31], 1, s[20:21]
	s_nop 1
	v_permlane16_swap_b32 v22, v24
	v_permlane16_swap_b32 v23, v25
	v_lshl_add_u64 v[248:249], v[20:21], 0, v[246:247]
	s_nop 0
	global_store_dwordx4 v[248:249], v[22:25], off offset:64
	s_nop 1
	v_lshl_add_u64 v[26:27], v[34:35], 0, v[132:133]
	v_add_f32_e32 v14, 0, v14
	v_add_f32_e32 v15, 0, v15
	v_add_f32_e32 v16, 0, v16
	v_add_f32_e32 v17, 0, v17
	s_waitcnt vmcnt(5)
	v_fma_f32 v14, v14, v196, v228
	v_fma_f32 v15, v15, v197, v229
	v_fma_f32 v16, v16, v198, v230
	v_fma_f32 v25, v17, v199, v231
	v_cvt_pk_bf16_f32 v14, v14, v15
	v_cvt_pk_bf16_f32 v15, v16, v25
	v_lshl_add_u64 v[22:23], v[34:35], 0, v[132:133]
	v_add_f32_e32 v6, 0, v6
	v_add_f32_e32 v7, 0, v7
	v_add_f32_e32 v8, 0, v8
	v_add_f32_e32 v9, 0, v9
	s_waitcnt vmcnt(4)
	v_fma_f32 v6, v6, v200, v232
	v_fma_f32 v7, v7, v201, v233
	v_fma_f32 v8, v8, v202, v234
	v_fma_f32 v21, v9, v203, v235
	v_cvt_pk_bf16_f32 v16, v6, v7
	v_cvt_pk_bf16_f32 v17, v8, v21
	v_lshl_add_u64 v[8:9], v[22:23], 1, s[20:21]
	s_nop 1
	v_permlane16_swap_b32 v14, v16
	v_permlane16_swap_b32 v15, v17
	v_lshl_add_u64 v[248:249], v[8:9], 0, v[246:247]
	s_nop 0
	global_store_dwordx4 v[248:249], v[14:17], off offset:128
	s_nop 1
	v_lshl_add_u64 v[18:19], v[34:35], 0, v[132:133]
	v_add_f32_e32 v10, 0, v10
	v_add_f32_e32 v11, 0, v11
	v_add_f32_e32 v12, 0, v12
	v_add_f32_e32 v13, 0, v13
	s_waitcnt vmcnt(4)
	v_fma_f32 v6, v10, v204, v236
	v_fma_f32 v7, v11, v205, v237
	v_fma_f32 v8, v12, v206, v238
	v_fma_f32 v17, v13, v207, v239
	v_cvt_pk_bf16_f32 v6, v6, v7
	v_cvt_pk_bf16_f32 v7, v8, v17
	v_lshl_add_u64 v[14:15], v[34:35], 0, v[132:133]
	v_add_f32_e32 v2, 0, v2
	v_add_f32_e32 v3, 0, v3
	v_add_f32_e32 v4, 0, v4
	v_add_f32_e32 v5, 0, v5
	s_waitcnt vmcnt(3)
	v_fma_f32 v2, v2, v208, v240
	v_fma_f32 v3, v3, v209, v241
	v_fma_f32 v4, v4, v210, v242
	v_fma_f32 v13, v5, v211, v243
	v_cvt_pk_bf16_f32 v8, v2, v3
	v_cvt_pk_bf16_f32 v9, v4, v13
	v_lshl_add_u64 v[4:5], v[14:15], 1, s[20:21]
	s_nop 1
	v_permlane16_swap_b32 v6, v8
	v_permlane16_swap_b32 v7, v9
	v_lshl_add_u64 v[248:249], v[4:5], 0, v[246:247]
	s_nop 0
	global_store_dwordx4 v[248:249], v[6:9], off offset:192
	s_nop 1
	s_branch .LBB0_2114

; template <bool SWAP, class Epi, bool THIN = false> ...
;     ...
;     for (int st = 0; st < ns; ++st) {
;       asm volatile("s_waitcnt vmcnt(0)" ::: "memory");
;       __builtin_amdgcn_s_barrier();
;       asm volatile("" ::: "memory");
;       if (st + 1 < ns) {
;         char* nb = smem + ((st + 1) & 1) * 65536;
;         const int ko = (st + 1) * 64;
; #pragma unroll
;         for (int i = 0; i < 4; ++i) { GLDS16(A + (size_t)(ap[i] + ko), nb + tid * 16 + i * 8192); GLDS16(Bt + (size_t)(bp[i] + ko), nb + 32768 + tid * 16 + i * 8192); }
;       }
;       const char* sa = smem + (st & 1) * 65536 + (wr * 64 + fr) * 128;
;       const char* sb = smem + (st & 1) * 65536 + 32768 + (wc * 128 + fr) * 128;
;       if constexpr (THIN) {
;         if (wc == 0) {
; #pragma unroll
;           for (int ks = 0; ks < 2; ++ks) {
;             bf16x8 af[4], bf[2];
; #pragma unroll
;             for (int m = 0; m < 4; ++m) af[m] = *(const bf16x8*)(sa + m * 2048 + (((ks * 4 + fq) ^ swz) << 4));
; #pragma unroll
;             for (int n = 0; n < 2; ++n) bf[n] = *(const bf16x8*)(sb + n * 2048 + (((ks * 4 + fq) ^ swz) << 4));
; #pragma unroll
;             for (int m = 0; m < 4; ++m)
; #pragma unroll
;               for (int n = 0; n < 2; ++n)
;                 acc[m][n] = SWAP ? __builtin_amdgcn_mfma_f32_16x16x32_bf16(bf[n], af[m], acc[m][n], 0, 0, 0)
;                                  : __builtin_amdgcn_mfma_f32_16x16x32_bf16(af[m], bf[n], acc[m][n], 0, 0, 0);
;           }
;         }
;       } else {
;       bf16x8 afA[4], afB[4], bfb[2][2];
; #pragma unroll
;       for (int m = 0; m < 4; ++m) afA[m] = *(const bf16x8*)(sa + m * 2048 + ((fq ^ swz) << 4));
; #pragma unroll
;       for (int n = 0; n < 2; ++n) bfb[0][n] = *(const bf16x8*)(sb + n * 2048 + ((fq ^ swz) << 4));
; #pragma unroll
;       for (int gq = 0; gq < 8; ++gq) {
;         const int ks = gq >> 2, nh = gq & 3;
;         if (gq < 7) {
;           const int ks2 = (gq + 1) >> 2, nh2 = (gq + 1) & 3;
; #pragma unroll
;           for (int n = 0; n < 2; ++n) bfb[(gq + 1) & 1][n] = *(const bf16x8*)(sb + (nh2 * 2 + n) * 2048 + (((ks2 * 4 + fq) ^ swz) << 4));
;         }
;         if (gq == 3) {
; #pragma unroll
;           for (int m = 0; m < 4; ++m) afB[m] = *(const bf16x8*)(sa + m * 2048 + (((4 + fq) ^ swz) << 4));
;         }
;         __builtin_amdgcn_sched_barrier(0);
; #pragma unroll
.LBB0_2429:
	s_add_i32 s9, s7, 0x10000
	s_and_b32 s8, s9, 0x10000
	v_add_u32_e32 v139, s8, v144
	s_nop 0
	v_readfirstlane_b32 s10, v139
	s_waitcnt vmcnt(0)
	s_barrier
	s_and_b32 s7, s7, 0x10000
	v_add_u32_e32 v130, s7, v145
	v_add_u32_e32 v139, v130, v147
	ds_read_b128 v[168:171], v139
	ds_read_b128 v[172:175], v139 offset:2048
	ds_read_b128 v[176:179], v139 offset:4096
	ds_read_b128 v[180:183], v139 offset:6144
	v_or_b32_e32 v139, s7, v146
	v_add_u32_e32 v141, v139, v147
	ds_read_b128 v[184:187], v141 offset:32768
	ds_read_b128 v[188:191], v141 offset:34816
	ds_read_b128 v[192:195], v141 offset:36864
	ds_read_b128 v[196:199], v141 offset:38912
	v_add_u32_e32 v130, v130, v148
	s_waitcnt lgkmcnt(3)
	v_mfma_f32_16x16x32_bf16 v[126:129], v[184:187], v[168:171], v[126:129]
	s_mov_b32 m0, s10
	v_mfma_f32_16x16x32_bf16 v[110:113], v[184:187], v[172:175], v[110:113]
	global_load_lds_dwordx4 v138, s[22:23]
	v_add_u32_e32 v138, 0x80, v138
	v_mfma_f32_16x16x32_bf16 v[82:85], v[184:187], v[176:179], v[82:85]
	v_mfma_f32_16x16x32_bf16 v[50:53], v[184:187], v[180:183], v[50:53]
	ds_read_b128 v[184:187], v141 offset:40960
	ds_read_b128 v[200:203], v141 offset:43008
	s_waitcnt lgkmcnt(4)
	v_mfma_f32_16x16x32_bf16 v[122:125], v[188:191], v[168:171], v[122:125]
	s_add_u32 m0, s10, 0x8000
	v_mfma_f32_16x16x32_bf16 v[106:109], v[188:191], v[172:175], v[106:109]
	global_load_lds_dwordx4 v137, s[18:19]
	v_add_u32_e32 v137, 0x80, v137
	v_mfma_f32_16x16x32_bf16 v[78:81], v[188:191], v[176:179], v[78:81]
	v_mfma_f32_16x16x32_bf16 v[38:41], v[188:191], v[180:183], v[38:41]
	s_waitcnt lgkmcnt(3)
	v_mfma_f32_16x16x32_bf16 v[118:121], v[192:195], v[168:171], v[118:121]
	s_add_u32 m0, s10, 0x2000
	v_mfma_f32_16x16x32_bf16 v[94:97], v[192:195], v[172:175], v[94:97]
	global_load_lds_dwordx4 v136, s[22:23]
	v_add_u32_e32 v136, 0x80, v136
	v_mfma_f32_16x16x32_bf16 v[58:61], v[192:195], v[176:179], v[58:61]
	v_mfma_f32_16x16x32_bf16 v[26:29], v[192:195], v[180:183], v[26:29]
	ds_read_b128 v[188:191], v141 offset:45056
	ds_read_b128 v[192:195], v141 offset:47104
	s_waitcnt lgkmcnt(4)
	v_mfma_f32_16x16x32_bf16 v[114:117], v[196:199], v[168:171], v[114:117]
	s_add_u32 m0, s10, 0xa000
	v_mfma_f32_16x16x32_bf16 v[86:89], v[196:199], v[172:175], v[86:89]
	global_load_lds_dwordx4 v135, s[18:19]
	v_add_u32_e32 v135, 0x80, v135
	v_mfma_f32_16x16x32_bf16 v[54:57], v[196:199], v[176:179], v[54:57]
	v_mfma_f32_16x16x32_bf16 v[22:25], v[196:199], v[180:183], v[22:25]
	v_add_u32_e32 v139, v139, v148
	s_waitcnt lgkmcnt(3)
	v_mfma_f32_16x16x32_bf16 v[102:105], v[184:187], v[168:171], v[102:105]
	ds_read_b128 v[196:199], v139 offset:32768
	ds_read_b128 v[204:207], v139 offset:34816
	s_add_u32 m0, s10, 0x4000
	v_mfma_f32_16x16x32_bf16 v[74:77], v[184:187], v[172:175], v[74:77]
	global_load_lds_dwordx4 v134, s[22:23]
	v_add_u32_e32 v134, 0x80, v134
	v_mfma_f32_16x16x32_bf16 v[46:49], v[184:187], v[176:179], v[46:49]
	v_mfma_f32_16x16x32_bf16 v[10:13], v[184:187], v[180:183], v[10:13]
	ds_read_b128 v[184:187], v130
	ds_read_b128 v[208:211], v130 offset:2048
	ds_read_b128 v[212:215], v130 offset:4096
	ds_read_b128 v[216:219], v130 offset:6144
	s_waitcnt lgkmcnt(8)
	v_mfma_f32_16x16x32_bf16 v[98:101], v[200:203], v[168:171], v[98:101]
	s_add_u32 m0, s10, 0xc000
	v_mfma_f32_16x16x32_bf16 v[66:69], v[200:203], v[172:175], v[66:69]
	global_load_lds_dwordx4 v133, s[18:19]
	v_add_u32_e32 v133, 0x80, v133
	v_mfma_f32_16x16x32_bf16 v[34:37], v[200:203], v[176:179], v[34:37]
	v_mfma_f32_16x16x32_bf16 v[6:9], v[200:203], v[180:183], v[6:9]
	s_waitcnt lgkmcnt(7)
	v_mfma_f32_16x16x32_bf16 v[70:73], v[188:191], v[168:171], v[70:73]
	s_add_u32 m0, s10, 0x6000
	s_waitcnt lgkmcnt(6)
	v_mfma_f32_16x16x32_bf16 v[62:65], v[192:195], v[168:171], v[62:65]
	global_load_lds_dwordx4 v132, s[22:23]
	v_add_u32_e32 v132, 0x80, v132
	v_mfma_f32_16x16x32_bf16 v[42:45], v[188:191], v[172:175], v[42:45]
	v_mfma_f32_16x16x32_bf16 v[30:33], v[192:195], v[172:175], v[30:33]
	ds_read_b128 v[168:171], v139 offset:36864
	ds_read_b128 v[172:175], v139 offset:38912
	v_mfma_f32_16x16x32_bf16 v[18:21], v[188:191], v[176:179], v[18:21]
	s_add_u32 m0, s10, 0xe000
	v_mfma_f32_16x16x32_bf16 v[14:17], v[192:195], v[176:179], v[14:17]
	global_load_lds_dwordx4 v140, s[18:19]
	v_add_u32_e32 v140, 0x80, v140
	v_mfma_f32_16x16x32_bf16 v[2:5], v[188:191], v[180:183], v[2:5]
	v_mfma_f32_16x16x32_bf16 v[90:93], v[192:195], v[180:183], v[90:93]
	ds_read_b128 v[176:179], v139 offset:40960
	ds_read_b128 v[180:183], v139 offset:43008
	s_waitcnt lgkmcnt(7)
	v_mfma_f32_16x16x32_bf16 v[126:129], v[196:199], v[184:187], v[126:129]
	v_mfma_f32_16x16x32_bf16 v[122:125], v[204:207], v[184:187], v[122:125]
	s_waitcnt lgkmcnt(6)
	v_mfma_f32_16x16x32_bf16 v[110:113], v[196:199], v[208:211], v[110:113]
	v_mfma_f32_16x16x32_bf16 v[106:109], v[204:207], v[208:211], v[106:109]
	s_waitcnt lgkmcnt(5)
	v_mfma_f32_16x16x32_bf16 v[82:85], v[196:199], v[212:215], v[82:85]
	v_mfma_f32_16x16x32_bf16 v[78:81], v[204:207], v[212:215], v[78:81]
	s_waitcnt lgkmcnt(4)
	v_mfma_f32_16x16x32_bf16 v[50:53], v[196:199], v[216:219], v[50:53]
	v_mfma_f32_16x16x32_bf16 v[38:41], v[204:207], v[216:219], v[38:41]
	s_waitcnt lgkmcnt(3)
	v_mfma_f32_16x16x32_bf16 v[118:121], v[168:171], v[184:187], v[118:121]
	v_mfma_f32_16x16x32_bf16 v[94:97], v[168:171], v[208:211], v[94:97]
	v_mfma_f32_16x16x32_bf16 v[58:61], v[168:171], v[212:215], v[58:61]
	v_mfma_f32_16x16x32_bf16 v[26:29], v[168:171], v[216:219], v[26:29]
	ds_read_b128 v[168:171], v139 offset:45056
	ds_read_b128 v[188:191], v139 offset:47104
	s_waitcnt lgkmcnt(4)
; template <bool SWAP, class Epi, bool THIN = false> ...
;     ...
;     for (int st = 0; st < ns; ++st) {
;       asm volatile("s_waitcnt vmcnt(0)" ::: "memory");
;       __builtin_amdgcn_s_barrier();
;       asm volatile("" ::: "memory");
;       if (st + 1 < ns) {
;         char* nb = smem + ((st + 1) & 1) * 65536;
;         const int ko = (st + 1) * 64;
; #pragma unroll
;         for (int i = 0; i < 4; ++i) { GLDS16(A + (size_t)(ap[i] + ko), nb + tid * 16 + i * 8192); GLDS16(Bt + (size_t)(bp[i] + ko), nb + 32768 + tid * 16 + i * 8192); }
;       }
;       const char* sa = smem + (st & 1) * 65536 + (wr * 64 + fr) * 128;
;       const char* sb = smem + (st & 1) * 65536 + 32768 + (wc * 128 + fr) * 128;
;       if constexpr (THIN) {
;         if (wc == 0) {
; #pragma unroll
;           for (int ks = 0; ks < 2; ++ks) {
;             bf16x8 af[4], bf[2];
; #pragma unroll
;             for (int m = 0; m < 4; ++m) af[m] = *(const bf16x8*)(sa + m * 2048 + (((ks * 4 + fq) ^ swz) << 4));
; #pragma unroll
;             for (int n = 0; n < 2; ++n) bf[n] = *(const bf16x8*)(sb + n * 2048 + (((ks * 4 + fq) ^ swz) << 4));
; #pragma unroll
;             for (int m = 0; m < 4; ++m)
; #pragma unroll
;               for (int n = 0; n < 2; ++n)
;                 acc[m][n] = SWAP ? __builtin_amdgcn_mfma_f32_16x16x32_bf16(bf[n], af[m], acc[m][n], 0, 0, 0)
;                                  : __builtin_amdgcn_mfma_f32_16x16x32_bf16(af[m], bf[n], acc[m][n], 0, 0, 0);
;           }
;         }
;       } else {
;       bf16x8 afA[4], afB[4], bfb[2][2];
; #pragma unroll
;       for (int m = 0; m < 4; ++m) afA[m] = *(const bf16x8*)(sa + m * 2048 + ((fq ^ swz) << 4));
; #pragma unroll
;       for (int n = 0; n < 2; ++n) bfb[0][n] = *(const bf16x8*)(sb + n * 2048 + ((fq ^ swz) << 4));
; #pragma unroll
;       for (int gq = 0; gq < 8; ++gq) {
;         const int ks = gq >> 2, nh = gq & 3;
;         if (gq < 7) {
;           const int ks2 = (gq + 1) >> 2, nh2 = (gq + 1) & 3;
; #pragma unroll
;           for (int n = 0; n < 2; ++n) bfb[(gq + 1) & 1][n] = *(const bf16x8*)(sb + (nh2 * 2 + n) * 2048 + (((ks2 * 4 + fq) ^ swz) << 4));
;         }
;         if (gq == 3) {
; #pragma unroll
;           for (int m = 0; m < 4; ++m) afB[m] = *(const bf16x8*)(sa + m * 2048 + (((4 + fq) ^ swz) << 4));
;         }
;         __builtin_amdgcn_sched_barrier(0);
; #pragma unroll
	v_mfma_f32_16x16x32_bf16 v[114:117], v[172:175], v[184:187], v[114:117]
	v_mfma_f32_16x16x32_bf16 v[86:89], v[172:175], v[208:211], v[86:89]
	v_mfma_f32_16x16x32_bf16 v[54:57], v[172:175], v[212:215], v[54:57]
	v_mfma_f32_16x16x32_bf16 v[22:25], v[172:175], v[216:219], v[22:25]
	s_waitcnt lgkmcnt(3)
	v_mfma_f32_16x16x32_bf16 v[102:105], v[176:179], v[184:187], v[102:105]
	s_waitcnt lgkmcnt(2)
	v_mfma_f32_16x16x32_bf16 v[98:101], v[180:183], v[184:187], v[98:101]
	v_mfma_f32_16x16x32_bf16 v[74:77], v[176:179], v[208:211], v[74:77]
	v_mfma_f32_16x16x32_bf16 v[66:69], v[180:183], v[208:211], v[66:69]
	v_mfma_f32_16x16x32_bf16 v[46:49], v[176:179], v[212:215], v[46:49]
	v_mfma_f32_16x16x32_bf16 v[34:37], v[180:183], v[212:215], v[34:37]
	v_mfma_f32_16x16x32_bf16 v[10:13], v[176:179], v[216:219], v[10:13]
	v_mfma_f32_16x16x32_bf16 v[6:9], v[180:183], v[216:219], v[6:9]
	s_waitcnt lgkmcnt(1)
	v_mfma_f32_16x16x32_bf16 v[70:73], v[168:171], v[184:187], v[70:73]
	s_add_i32 s6, s6, 64
	s_cmpk_eq_i32 s6, 0xac0
	s_mov_b32 s7, s9
	s_waitcnt lgkmcnt(0)
	v_mfma_f32_16x16x32_bf16 v[62:65], v[188:191], v[184:187], v[62:65]
	v_mfma_f32_16x16x32_bf16 v[42:45], v[168:171], v[208:211], v[42:45]
	v_mfma_f32_16x16x32_bf16 v[30:33], v[188:191], v[208:211], v[30:33]
	v_mfma_f32_16x16x32_bf16 v[18:21], v[168:171], v[212:215], v[18:21]
	v_mfma_f32_16x16x32_bf16 v[14:17], v[188:191], v[212:215], v[14:17]
	v_mfma_f32_16x16x32_bf16 v[2:5], v[168:171], v[216:219], v[2:5]
	v_mfma_f32_16x16x32_bf16 v[90:93], v[188:191], v[216:219], v[90:93]
	s_cbranch_scc0 .LBB0_2429
	v_add_u32_e32 v130, s8, v145
	s_waitcnt vmcnt(0)
	s_barrier
	v_add_u32_e32 v140, v130, v147
	ds_read_b128 v[132:135], v140
	ds_read_b128 v[136:139], v140 offset:2048
	ds_read_b128 v[168:171], v140 offset:4096
	ds_read_b128 v[172:175], v140 offset:6144
	v_add_u32_e32 v140, s8, v146
	v_add_u32_e32 v141, v140, v147
	ds_read_b128 v[176:179], v141 offset:32768
	ds_read_b128 v[180:183], v141 offset:34816
	ds_read_b128 v[184:187], v141 offset:36864
	ds_read_b128 v[188:191], v141 offset:38912
	v_add_u32_e32 v130, v130, v148
	s_waitcnt lgkmcnt(0)
	v_mfma_f32_16x16x32_bf16 v[126:129], v[176:179], v[132:135], v[126:129]
	v_mfma_f32_16x16x32_bf16 v[110:113], v[176:179], v[136:139], v[110:113]
	v_mfma_f32_16x16x32_bf16 v[82:85], v[176:179], v[168:171], v[82:85]
	v_mfma_f32_16x16x32_bf16 v[50:53], v[176:179], v[172:175], v[50:53]
	ds_read_b128 v[176:179], v141 offset:40960
	ds_read_b128 v[192:195], v141 offset:43008
	v_mfma_f32_16x16x32_bf16 v[122:125], v[180:183], v[132:135], v[122:125]
	v_mfma_f32_16x16x32_bf16 v[106:109], v[180:183], v[136:139], v[106:109]
	v_mfma_f32_16x16x32_bf16 v[78:81], v[180:183], v[168:171], v[78:81]
	v_mfma_f32_16x16x32_bf16 v[38:41], v[180:183], v[172:175], v[38:41]
	v_mfma_f32_16x16x32_bf16 v[118:121], v[184:187], v[132:135], v[118:121]
	v_mfma_f32_16x16x32_bf16 v[180:183], v[184:187], v[136:139], v[94:97]
	v_mfma_f32_16x16x32_bf16 v[200:203], v[184:187], v[168:171], v[58:61]
	v_mfma_f32_16x16x32_bf16 v[204:207], v[188:191], v[168:171], v[54:57]
	v_mfma_f32_16x16x32_bf16 v[184:187], v[184:187], v[172:175], v[26:29]
	s_nop 2
	ds_read_b128 v[26:29], v141 offset:45056
	ds_read_b128 v[54:57], v141 offset:47104
	v_mfma_f32_16x16x32_bf16 v[114:117], v[188:191], v[132:135], v[114:117]
	v_mfma_f32_16x16x32_bf16 v[196:199], v[188:191], v[136:139], v[86:89]
	v_mfma_f32_16x16x32_bf16 v[188:191], v[188:191], v[172:175], v[22:25]
	v_add_u32_e32 v140, v140, v148
	s_waitcnt lgkmcnt(0)
	v_mfma_f32_16x16x32_bf16 v[102:105], v[176:179], v[132:135], v[102:105]
	ds_read_b128 v[22:25], v140 offset:32768
	ds_read_b128 v[86:89], v140 offset:34816
	v_mfma_f32_16x16x32_bf16 v[74:77], v[176:179], v[136:139], v[74:77]
	v_mfma_f32_16x16x32_bf16 v[46:49], v[176:179], v[168:171], v[46:49]
	v_mfma_f32_16x16x32_bf16 v[10:13], v[176:179], v[172:175], v[10:13]
	ds_read_b128 v[176:179], v130
	ds_read_b128 v[208:211], v130 offset:2048
	ds_read_b128 v[212:215], v130 offset:4096
	ds_read_b128 v[216:219], v130 offset:6144
	v_mfma_f32_16x16x32_bf16 v[98:101], v[192:195], v[132:135], v[98:101]
	v_mfma_f32_16x16x32_bf16 v[66:69], v[192:195], v[136:139], v[66:69]
	v_mfma_f32_16x16x32_bf16 v[34:37], v[192:195], v[168:171], v[34:37]
	v_mfma_f32_16x16x32_bf16 v[6:9], v[192:195], v[172:175], v[6:9]
	v_mfma_f32_16x16x32_bf16 v[220:223], v[26:29], v[168:171], v[18:21]
	v_mfma_f32_16x16x32_bf16 v[168:171], v[54:57], v[168:171], v[14:17]
	s_nop 2
	ds_read_b128 v[14:17], v140 offset:36864
	ds_read_b128 v[18:21], v140 offset:38912
	v_mfma_f32_16x16x32_bf16 v[70:73], v[26:29], v[132:135], v[70:73]
	v_mfma_f32_16x16x32_bf16 v[132:135], v[54:57], v[132:135], v[62:65]
	v_mfma_f32_16x16x32_bf16 v[192:195], v[26:29], v[136:139], v[42:45]
	v_mfma_f32_16x16x32_bf16 v[136:139], v[54:57], v[136:139], v[30:33]
	v_mfma_f32_16x16x32_bf16 v[2:5], v[26:29], v[172:175], v[2:5]
	v_mfma_f32_16x16x32_bf16 v[172:175], v[54:57], v[172:175], v[90:93]
	ds_read_b128 v[224:227], v140 offset:40960
	ds_read_b128 v[228:231], v140 offset:43008
	s_waitcnt lgkmcnt(0)
	v_mfma_f32_16x16x32_bf16 v[126:129], v[22:25], v[176:179], v[126:129]
	v_mfma_f32_16x16x32_bf16 v[122:125], v[86:89], v[176:179], v[122:125]
	v_mfma_f32_16x16x32_bf16 v[94:97], v[22:25], v[208:211], v[110:113]
	v_mfma_f32_16x16x32_bf16 v[90:93], v[86:89], v[208:211], v[106:109]
	v_mfma_f32_16x16x32_bf16 v[62:65], v[22:25], v[212:215], v[82:85]
	v_mfma_f32_16x16x32_bf16 v[58:61], v[86:89], v[212:215], v[78:81]
	v_mfma_f32_16x16x32_bf16 v[30:33], v[22:25], v[216:219], v[50:53]
	v_mfma_f32_16x16x32_bf16 v[26:29], v[86:89], v[216:219], v[38:41]
	v_mfma_f32_16x16x32_bf16 v[86:89], v[14:17], v[208:211], v[180:183]
	v_mfma_f32_16x16x32_bf16 v[22:25], v[14:17], v[216:219], v[184:187]
	s_nop 1
	ds_read_b128 v[180:183], v140 offset:45056
	ds_read_b128 v[184:187], v140 offset:47104
	v_mfma_f32_16x16x32_bf16 v[118:121], v[14:17], v[176:179], v[118:121]
	v_mfma_f32_16x16x32_bf16 v[114:117], v[18:21], v[176:179], v[114:117]
	v_mfma_f32_16x16x32_bf16 v[82:85], v[18:21], v[208:211], v[196:199]
	v_mfma_f32_16x16x32_bf16 v[54:57], v[14:17], v[212:215], v[200:203]
	v_mfma_f32_16x16x32_bf16 v[50:53], v[18:21], v[212:215], v[204:207]
	v_mfma_f32_16x16x32_bf16 v[18:21], v[18:21], v[216:219], v[188:191]
	v_mfma_f32_16x16x32_bf16 v[110:113], v[224:227], v[176:179], v[102:105]
	v_mfma_f32_16x16x32_bf16 v[106:109], v[228:231], v[176:179], v[98:101]
	v_mfma_f32_16x16x32_bf16 v[78:81], v[224:227], v[208:211], v[74:77]
	v_mfma_f32_16x16x32_bf16 v[74:77], v[228:231], v[208:211], v[66:69]
	v_mfma_f32_16x16x32_bf16 v[46:49], v[224:227], v[212:215], v[46:49]
	v_mfma_f32_16x16x32_bf16 v[42:45], v[228:231], v[212:215], v[34:37]
	v_mfma_f32_16x16x32_bf16 v[14:17], v[224:227], v[216:219], v[10:13]
	v_mfma_f32_16x16x32_bf16 v[10:13], v[228:231], v[216:219], v[6:9]
	v_mov_b32_e32 v130, v1
	s_waitcnt vmcnt(0) lgkmcnt(0)
	s_barrier
; __device__ __forceinline__ unsigned pack2(float a, float b) { unsigned r; asm("v_cvt_pk_bf16_f32 %0, %1, %2" : "=v"(r) : "v"(a), "v"(b)); return r; }
; __device__ __forceinline__ float bf2f(bf16_t h) { return __uint_as_float(((unsigned)h) << 16); }
;   __device__ __forceinline__ void c4(int g, int rig, int col, f32x4 v) const {
;     const size_t o = ((size_t)g * 2048 + rig) * 1024 + col;
;     f32x4 bs;
;     if (BASE_F32) bs = __builtin_nontemporal_load((const f32x4*)((const float*)base + o));
;     else {
;       const uint2 u = *(const uint2*)((const bf16_t*)base + o);
;       bs[0] = bf2f((bf16_t)(u.x & 0xffff)); bs[1] = bf2f((bf16_t)(u.x >> 16)); bs[2] = bf2f((bf16_t)(u.y & 0xffff)); bs[3] = bf2f((bf16_t)(u.y >> 16));
;     }
;     const f32x4 gt = *(const f32x4*)(gate + (size_t)g * 6144 + col);
;     f32x4 bi = {0.f, 0.f, 0.f, 0.f};
;     if (bias) bi = *(const f32x4*)(bias + col);
;     f32x4 r;
; #pragma unroll
;     for (int j = 0; j < 4; ++j) r[j] = bs[j] + gt[j] * (v[j] + bi[j]);
;     uint2 w; w.x = pack2(r[0], r[1]); w.y = pack2(r[2], r[3]);
;     *(uint2*)(X16 + o) = w;
;   }
; template <bool SWAP, class Epi, bool THIN = false> ...
;     ...
;     if constexpr (Epi::KIND == 0) {
; #pragma unroll
;       for (int m = 0; m < 4; ++m) {
;         const int rig = rig0 + rw + m * 16 + fr_e;
;         if constexpr (Epi::ROWSUM) {
;           float ss = 0.f;
; #pragma unroll
;           for (int n = 0; n < 8; ++n) {
;             const int col = nt * 256 + wc_e * 128 + n * 16 + fq_e * 4;
;             if (col < N) ss += epi.c4(g, rig, col, acc[m][n]);
;           }
;           ss += __shfl_xor(ss, 16); ss += __shfl_xor(ss, 32);
;           if (fq_e == 0) epi.rowsum(g, rig, nt * 2 + wc_e, ss);
;         } else {
; #pragma unroll
;           for (int n = 0; n < 8; ++n) {
;             const int col = nt * 256 + wc_e * 128 + n * 16 + fq_e * 4;
;             if (col < N) epi.c4(g, rig, col, acc[m][n]);
;           }
;         }
	v_mfma_f32_16x16x32_bf16 v[98:101], v[184:187], v[176:179], v[132:135]
	v_ashrrev_i32_e32 v7, 8, v130
	v_add_u32_e32 v7, s5, v7
	v_ashrrev_i32_e32 v8, 31, v7
	v_lshrrev_b32_e32 v8, 28, v8
	v_add_u32_e32 v8, v7, v8
	v_ashrrev_i32_e32 v134, 4, v8
	v_lshlrev_b32_e32 v8, 11, v134
	v_lshlrev_b32_e32 v7, 7, v7
	v_sub_u32_e32 v7, v7, v8
	v_lshrrev_b32_e32 v8, 1, v130
	v_and_b32_e32 v6, 15, v130
	v_and_b32_e32 v8, 64, v8
	v_mfma_f32_16x16x32_bf16 v[66:69], v[184:187], v[208:211], v[136:139]
	v_ashrrev_i32_e32 v135, 31, v134
	s_nop 1
	v_or3_b32 v136, v7, v8, v6
	v_lshlrev_b32_e32 v6, 1, v130
	v_and_b32_e32 v132, 0x80, v6
	v_mfma_f32_16x16x32_bf16 v[6:9], v[180:183], v[216:219], v[2:5]
	v_ashrrev_i32_e32 v137, 31, v136
	v_lshlrev_b64 v[138:139], 21, v[134:135]
	v_lshlrev_b64 v[140:141], 10, v[136:137]
	v_lshrrev_b32_e32 v2, 2, v130
	v_and_b32_e32 v2, 12, v2
	v_mfma_f32_16x16x32_bf16 v[102:105], v[180:183], v[176:179], v[70:73]
	v_or3_b32 v132, v2, v132, s4
	v_mad_i64_i32 v[134:135], s[4:5], v134, s31, 0
	v_mfma_f32_16x16x32_bf16 v[70:73], v[180:183], v[208:211], v[192:195]
	v_lshl_add_u64 v[140:141], v[140:141], 0, v[138:139]
	v_cmp_gt_i32_e32 vcc, s34, v132
	v_ashrrev_i32_e32 v133, 31, v132
	v_bfe_u32 v246, v130, 4, 1
	v_mul_u32_u24_e32 v246, 24, v246
	v_mov_b32_e32 v247, 0
	v_mfma_f32_16x16x32_bf16 v[38:41], v[180:183], v[212:215], v[220:223]
	v_lshl_add_u64 v[134:135], s[24:25], 0, v[134:135]
	v_lshl_add_u64 v[140:141], v[140:141], 1, s[20:21]
	v_mfma_f32_16x16x32_bf16 v[34:37], v[184:187], v[212:215], v[168:171]
	v_mfma_f32_16x16x32_bf16 v[2:5], v[184:187], v[216:219], v[172:175]
	v_lshl_add_u64 v[218:219], v[132:133], 2, v[134:135]
	global_load_dwordx4 v[198:201], v[218:219], off
	global_load_dwordx4 v[202:205], v[218:219], off offset:64
	global_load_dwordx4 v[206:209], v[218:219], off offset:128
	global_load_dwordx4 v[210:213], v[218:219], off offset:192
	global_load_dwordx4 v[214:217], v[218:219], off offset:256
	global_load_dwordx4 v[224:227], v[218:219], off offset:320
	global_load_dwordx4 v[228:231], v[218:219], off offset:384
	global_load_dwordx4 v[232:235], v[218:219], off offset:448
	s_nop 0
	v_lshl_add_u64 v[172:173], v[132:133], 1, v[140:141]
	v_lshl_add_u64 v[196:197], v[132:133], 1, v[140:141]
	global_load_dwordx2 v[176:177], v[196:197], off
	global_load_dwordx2 v[178:179], v[196:197], off offset:32
	global_load_dwordx2 v[180:181], v[196:197], off offset:64
	global_load_dwordx2 v[182:183], v[196:197], off offset:96
	global_load_dwordx2 v[184:185], v[196:197], off offset:128
	global_load_dwordx2 v[186:187], v[196:197], off offset:160
	global_load_dwordx2 v[188:189], v[196:197], off offset:192
	global_load_dwordx2 v[190:191], v[196:197], off offset:224
	v_add_f32_e32 v126, 0, v126
	v_add_f32_e32 v127, 0, v127
	v_add_f32_e32 v128, 0, v128
	v_add_f32_e32 v129, 0, v129
	s_waitcnt vmcnt(7)
	v_lshlrev_b32_e32 v130, 16, v176
	v_and_b32_e32 v137, 0xffff0000, v176
	v_lshlrev_b32_e32 v167, 16, v177
	v_and_b32_e32 v174, 0xffff0000, v177
	v_fmac_f32_e32 v130, v126, v198
	v_fmac_f32_e32 v137, v127, v199
	v_fmac_f32_e32 v167, v128, v200
	v_fmac_f32_e32 v174, v129, v201
	v_cvt_pk_bf16_f32 v126, v130, v137
	v_cvt_pk_bf16_f32 v127, v167, v174
	v_lshl_add_u64 v[168:169], v[132:133], 1, v[140:141]
	v_add_f32_e32 v122, 0, v122
	v_add_f32_e32 v123, 0, v123
	v_add_f32_e32 v124, 0, v124
	v_add_f32_e32 v125, 0, v125
	s_waitcnt vmcnt(6)
	v_lshlrev_b32_e32 v130, 16, v178
	v_and_b32_e32 v137, 0xffff0000, v178
	v_lshlrev_b32_e32 v167, 16, v179
	v_and_b32_e32 v170, 0xffff0000, v179
	v_fmac_f32_e32 v130, v122, v202
	v_fmac_f32_e32 v137, v123, v203
	v_fmac_f32_e32 v167, v124, v204
	v_fmac_f32_e32 v170, v125, v205
	v_cvt_pk_bf16_f32 v128, v130, v137
	v_cvt_pk_bf16_f32 v129, v167, v170
	s_nop 1
	v_permlane16_swap_b32 v126, v128
	v_permlane16_swap_b32 v127, v129
	v_lshl_add_u64 v[248:249], v[168:169], 0, v[246:247]
	s_nop 0
	global_store_dwordx4 v[248:249], v[126:129], off
	s_nop 1
	v_or_b32_e32 v122, 32, v132
	v_lshl_add_u64 v[126:127], v[132:133], 1, v[140:141]
	v_add_f32_e32 v118, 0, v118
	v_add_f32_e32 v119, 0, v119
	v_add_f32_e32 v120, 0, v120
	v_add_f32_e32 v121, 0, v121
	s_waitcnt vmcnt(6)
	v_lshlrev_b32_e32 v130, 16, v180
	v_and_b32_e32 v128, 0xffff0000, v180
	v_lshlrev_b32_e32 v137, 16, v181
	v_and_b32_e32 v129, 0xffff0000, v181
	v_fmac_f32_e32 v130, v118, v206
	v_fmac_f32_e32 v128, v119, v207
	v_fmac_f32_e32 v137, v120, v208
	v_fmac_f32_e32 v129, v121, v209
	v_cvt_pk_bf16_f32 v118, v130, v128
	v_cvt_pk_bf16_f32 v119, v137, v129
	v_lshl_add_u64 v[122:123], v[132:133], 1, v[140:141]
	v_add_f32_e32 v114, 0, v114
	v_add_f32_e32 v115, 0, v115
	v_add_f32_e32 v116, 0, v116
	v_add_f32_e32 v117, 0, v117
	s_waitcnt vmcnt(5)
	v_lshlrev_b32_e32 v126, 16, v182
	v_and_b32_e32 v124, 0xffff0000, v182
	v_lshlrev_b32_e32 v127, 16, v183
	v_and_b32_e32 v125, 0xffff0000, v183
	v_fmac_f32_e32 v126, v114, v210
	v_fmac_f32_e32 v124, v115, v211
	v_fmac_f32_e32 v127, v116, v212
	v_fmac_f32_e32 v125, v117, v213
	v_cvt_pk_bf16_f32 v120, v126, v124
	v_cvt_pk_bf16_f32 v121, v127, v125
	s_nop 1
	v_permlane16_swap_b32 v118, v120
	v_permlane16_swap_b32 v119, v121
	v_lshl_add_u64 v[248:249], v[122:123], 0, v[246:247]
	s_nop 0
	global_store_dwordx4 v[248:249], v[118:121], off offset:64
	s_nop 1
	v_or_b32_e32 v114, 64, v132
	v_lshl_add_u64 v[118:119], v[132:133], 1, v[140:141]
	v_add_f32_e32 v110, 0, v110
	v_add_f32_e32 v111, 0, v111
	v_add_f32_e32 v112, 0, v112
	v_add_f32_e32 v113, 0, v113
	s_waitcnt vmcnt(5)
; __device__ __forceinline__ unsigned pack2(float a, float b) { unsigned r; asm("v_cvt_pk_bf16_f32 %0, %1, %2" : "=v"(r) : "v"(a), "v"(b)); return r; }
; __device__ __forceinline__ float bf2f(bf16_t h) { return __uint_as_float(((unsigned)h) << 16); }
;   __device__ __forceinline__ void c4(int g, int rig, int col, f32x4 v) const {
;     const size_t o = ((size_t)g * 2048 + rig) * 1024 + col;
;     f32x4 bs;
;     if (BASE_F32) bs = __builtin_nontemporal_load((const f32x4*)((const float*)base + o));
;     else {
;       const uint2 u = *(const uint2*)((const bf16_t*)base + o);
;       bs[0] = bf2f((bf16_t)(u.x & 0xffff)); bs[1] = bf2f((bf16_t)(u.x >> 16)); bs[2] = bf2f((bf16_t)(u.y & 0xffff)); bs[3] = bf2f((bf16_t)(u.y >> 16));
;     }
;     const f32x4 gt = *(const f32x4*)(gate + (size_t)g * 6144 + col);
;     f32x4 bi = {0.f, 0.f, 0.f, 0.f};
;     if (bias) bi = *(const f32x4*)(bias + col);
;     f32x4 r;
; #pragma unroll
;     for (int j = 0; j < 4; ++j) r[j] = bs[j] + gt[j] * (v[j] + bi[j]);
;     uint2 w; w.x = pack2(r[0], r[1]); w.y = pack2(r[2], r[3]);
;     *(uint2*)(X16 + o) = w;
;   }
; template <bool SWAP, class Epi, bool THIN = false> ...
;     ...
;     if constexpr (Epi::KIND == 0) {
; #pragma unroll
;       for (int m = 0; m < 4; ++m) {
;         const int rig = rig0 + rw + m * 16 + fr_e;
;         if constexpr (Epi::ROWSUM) {
;           float ss = 0.f;
; #pragma unroll
;           for (int n = 0; n < 8; ++n) {
;             const int col = nt * 256 + wc_e * 128 + n * 16 + fq_e * 4;
;             if (col < N) ss += epi.c4(g, rig, col, acc[m][n]);
;           }
;           ss += __shfl_xor(ss, 16); ss += __shfl_xor(ss, 32);
;           if (fq_e == 0) epi.rowsum(g, rig, nt * 2 + wc_e, ss);
;         } else {
; #pragma unroll
;           for (int n = 0; n < 8; ++n) {
;             const int col = nt * 256 + wc_e * 128 + n * 16 + fq_e * 4;
;             if (col < N) epi.c4(g, rig, col, acc[m][n]);
;           }
;         }
	v_lshlrev_b32_e32 v122, 16, v184
	v_and_b32_e32 v120, 0xffff0000, v184
	v_lshlrev_b32_e32 v123, 16, v185
	v_and_b32_e32 v121, 0xffff0000, v185
	v_fmac_f32_e32 v122, v110, v214
	v_fmac_f32_e32 v120, v111, v215
	v_fmac_f32_e32 v123, v112, v216
	v_fmac_f32_e32 v121, v113, v217
	v_cvt_pk_bf16_f32 v110, v122, v120
	v_cvt_pk_bf16_f32 v111, v123, v121
	v_lshl_add_u64 v[114:115], v[132:133], 1, v[140:141]
	v_add_f32_e32 v106, 0, v106
	v_add_f32_e32 v107, 0, v107
	v_add_f32_e32 v108, 0, v108
	v_add_f32_e32 v109, 0, v109
	s_waitcnt vmcnt(4)
	v_lshlrev_b32_e32 v118, 16, v186
	v_and_b32_e32 v116, 0xffff0000, v186
	v_lshlrev_b32_e32 v119, 16, v187
	v_and_b32_e32 v117, 0xffff0000, v187
	v_fmac_f32_e32 v118, v106, v224
	v_fmac_f32_e32 v116, v107, v225
	v_fmac_f32_e32 v119, v108, v226
	v_fmac_f32_e32 v117, v109, v227
	v_cvt_pk_bf16_f32 v112, v118, v116
	v_cvt_pk_bf16_f32 v113, v119, v117
	s_nop 1
	v_permlane16_swap_b32 v110, v112
	v_permlane16_swap_b32 v111, v113
	v_lshl_add_u64 v[248:249], v[114:115], 0, v[246:247]
	s_nop 0
	global_store_dwordx4 v[248:249], v[110:113], off offset:128
	s_nop 1
	v_or_b32_e32 v106, 0x60, v132
	v_lshl_add_u64 v[110:111], v[132:133], 1, v[140:141]
	v_add_f32_e32 v102, 0, v102
	v_add_f32_e32 v103, 0, v103
	v_add_f32_e32 v104, 0, v104
	v_add_f32_e32 v105, 0, v105
	s_waitcnt vmcnt(4)
	v_lshlrev_b32_e32 v114, 16, v188
	v_and_b32_e32 v112, 0xffff0000, v188
	v_lshlrev_b32_e32 v115, 16, v189
	v_and_b32_e32 v113, 0xffff0000, v189
	v_fmac_f32_e32 v114, v102, v228
	v_fmac_f32_e32 v112, v103, v229
	v_fmac_f32_e32 v115, v104, v230
	v_fmac_f32_e32 v113, v105, v231
	v_cvt_pk_bf16_f32 v102, v114, v112
	v_cvt_pk_bf16_f32 v103, v115, v113
	v_lshl_add_u64 v[106:107], v[132:133], 1, v[140:141]
	v_add_f32_e32 v98, 0, v98
	v_add_f32_e32 v99, 0, v99
	v_add_f32_e32 v100, 0, v100
	v_add_f32_e32 v101, 0, v101
	s_waitcnt vmcnt(3)
	v_lshlrev_b32_e32 v110, 16, v190
	v_and_b32_e32 v108, 0xffff0000, v190
	v_lshlrev_b32_e32 v111, 16, v191
	v_and_b32_e32 v109, 0xffff0000, v191
	v_fmac_f32_e32 v110, v98, v232
	v_fmac_f32_e32 v108, v99, v233
	v_fmac_f32_e32 v111, v100, v234
	v_fmac_f32_e32 v109, v101, v235
	v_cvt_pk_bf16_f32 v104, v110, v108
	v_cvt_pk_bf16_f32 v105, v111, v109
	s_nop 1
	v_permlane16_swap_b32 v102, v104
	v_permlane16_swap_b32 v103, v105
	v_lshl_add_u64 v[248:249], v[106:107], 0, v[246:247]
	s_nop 0
	global_store_dwordx4 v[248:249], v[102:105], off offset:192
	s_nop 1
	v_or_b32_e32 v98, 16, v136
	v_ashrrev_i32_e32 v99, 31, v98
	v_lshlrev_b64 v[98:99], 10, v[98:99]
	v_lshl_add_u64 v[98:99], v[98:99], 0, v[138:139]
	v_lshl_add_u64 v[98:99], v[98:99], 1, s[20:21]
	v_lshl_add_u64 v[104:105], v[132:133], 1, v[98:99]
	v_lshl_add_u64 v[196:197], v[132:133], 1, v[98:99]
	global_load_dwordx2 v[176:177], v[196:197], off
	global_load_dwordx2 v[178:179], v[196:197], off offset:32
	global_load_dwordx2 v[180:181], v[196:197], off offset:64
	global_load_dwordx2 v[182:183], v[196:197], off offset:96
	global_load_dwordx2 v[184:185], v[196:197], off offset:128
	global_load_dwordx2 v[186:187], v[196:197], off offset:160
	global_load_dwordx2 v[188:189], v[196:197], off offset:192
	global_load_dwordx2 v[190:191], v[196:197], off offset:224
	v_add_f32_e32 v94, 0, v94
	v_add_f32_e32 v95, 0, v95
	v_add_f32_e32 v96, 0, v96
	v_add_f32_e32 v97, 0, v97
	s_waitcnt vmcnt(7)
	v_lshlrev_b32_e32 v108, 16, v176
	v_and_b32_e32 v106, 0xffff0000, v176
	v_lshlrev_b32_e32 v109, 16, v177
	v_and_b32_e32 v107, 0xffff0000, v177
	v_fmac_f32_e32 v108, v94, v198
	v_fmac_f32_e32 v106, v95, v199
	v_fmac_f32_e32 v109, v96, v200
	v_fmac_f32_e32 v107, v97, v201
	v_cvt_pk_bf16_f32 v94, v108, v106
	v_cvt_pk_bf16_f32 v95, v109, v107
	v_lshl_add_u64 v[100:101], v[132:133], 1, v[98:99]
	v_add_f32_e32 v90, 0, v90
	v_add_f32_e32 v91, 0, v91
	v_add_f32_e32 v92, 0, v92
	v_add_f32_e32 v93, 0, v93
	s_waitcnt vmcnt(6)
	v_lshlrev_b32_e32 v104, 16, v178
	v_and_b32_e32 v102, 0xffff0000, v178
	v_lshlrev_b32_e32 v105, 16, v179
	v_and_b32_e32 v103, 0xffff0000, v179
	v_fmac_f32_e32 v104, v90, v202
	v_fmac_f32_e32 v102, v91, v203
	v_fmac_f32_e32 v105, v92, v204
	v_fmac_f32_e32 v103, v93, v205
	v_cvt_pk_bf16_f32 v96, v104, v102
	v_cvt_pk_bf16_f32 v97, v105, v103
	s_nop 1
	v_permlane16_swap_b32 v94, v96
	v_permlane16_swap_b32 v95, v97
	v_lshl_add_u64 v[248:249], v[100:101], 0, v[246:247]
	s_nop 0
	global_store_dwordx4 v[248:249], v[94:97], off
	s_nop 1
	v_lshl_add_u64 v[94:95], v[132:133], 1, v[98:99]
	v_add_f32_e32 v86, 0, v86
	v_add_f32_e32 v87, 0, v87
	v_add_f32_e32 v88, 0, v88
	v_add_f32_e32 v89, 0, v89
	s_waitcnt vmcnt(6)
	v_lshlrev_b32_e32 v100, 16, v180
	v_and_b32_e32 v96, 0xffff0000, v180
	v_lshlrev_b32_e32 v101, 16, v181
	v_and_b32_e32 v97, 0xffff0000, v181
	v_fmac_f32_e32 v100, v86, v206
	v_fmac_f32_e32 v96, v87, v207
	v_fmac_f32_e32 v101, v88, v208
	v_fmac_f32_e32 v97, v89, v209
	v_cvt_pk_bf16_f32 v86, v100, v96
	v_cvt_pk_bf16_f32 v87, v101, v97
	v_lshl_add_u64 v[90:91], v[132:133], 1, v[98:99]
	v_add_f32_e32 v82, 0, v82
	v_add_f32_e32 v83, 0, v83
	v_add_f32_e32 v84, 0, v84
	v_add_f32_e32 v85, 0, v85
	s_waitcnt vmcnt(5)
	v_lshlrev_b32_e32 v94, 16, v182
	v_and_b32_e32 v92, 0xffff0000, v182
	v_lshlrev_b32_e32 v95, 16, v183
	v_and_b32_e32 v93, 0xffff0000, v183
	v_fmac_f32_e32 v94, v82, v210
	v_fmac_f32_e32 v92, v83, v211
	v_fmac_f32_e32 v95, v84, v212
	v_fmac_f32_e32 v93, v85, v213
	v_cvt_pk_bf16_f32 v88, v94, v92
	v_cvt_pk_bf16_f32 v89, v95, v93
	s_nop 1
	v_permlane16_swap_b32 v86, v88
	v_permlane16_swap_b32 v87, v89
	v_lshl_add_u64 v[248:249], v[90:91], 0, v[246:247]
	s_nop 0
	global_store_dwordx4 v[248:249], v[86:89], off offset:64
	s_nop 1
	v_lshl_add_u64 v[86:87], v[132:133], 1, v[98:99]
	v_add_f32_e32 v78, 0, v78
	v_add_f32_e32 v79, 0, v79
	v_add_f32_e32 v80, 0, v80
	v_add_f32_e32 v81, 0, v81
	s_waitcnt vmcnt(5)
; __device__ __forceinline__ unsigned pack2(float a, float b) { unsigned r; asm("v_cvt_pk_bf16_f32 %0, %1, %2" : "=v"(r) : "v"(a), "v"(b)); return r; }
; __device__ __forceinline__ float bf2f(bf16_t h) { return __uint_as_float(((unsigned)h) << 16); }
;   __device__ __forceinline__ void c4(int g, int rig, int col, f32x4 v) const {
;     const size_t o = ((size_t)g * 2048 + rig) * 1024 + col;
;     f32x4 bs;
;     if (BASE_F32) bs = __builtin_nontemporal_load((const f32x4*)((const float*)base + o));
;     else {
;       const uint2 u = *(const uint2*)((const bf16_t*)base + o);
;       bs[0] = bf2f((bf16_t)(u.x & 0xffff)); bs[1] = bf2f((bf16_t)(u.x >> 16)); bs[2] = bf2f((bf16_t)(u.y & 0xffff)); bs[3] = bf2f((bf16_t)(u.y >> 16));
;     }
;     const f32x4 gt = *(const f32x4*)(gate + (size_t)g * 6144 + col);
;     f32x4 bi = {0.f, 0.f, 0.f, 0.f};
;     if (bias) bi = *(const f32x4*)(bias + col);
;     f32x4 r;
; #pragma unroll
;     for (int j = 0; j < 4; ++j) r[j] = bs[j] + gt[j] * (v[j] + bi[j]);
;     uint2 w; w.x = pack2(r[0], r[1]); w.y = pack2(r[2], r[3]);
;     *(uint2*)(X16 + o) = w;
;   }
; template <bool SWAP, class Epi, bool THIN = false> ...
;     ...
;     if constexpr (Epi::KIND == 0) {
; #pragma unroll
;       for (int m = 0; m < 4; ++m) {
;         const int rig = rig0 + rw + m * 16 + fr_e;
;         if constexpr (Epi::ROWSUM) {
;           float ss = 0.f;
; #pragma unroll
;           for (int n = 0; n < 8; ++n) {
;             const int col = nt * 256 + wc_e * 128 + n * 16 + fq_e * 4;
;             if (col < N) ss += epi.c4(g, rig, col, acc[m][n]);
;           }
;           ss += __shfl_xor(ss, 16); ss += __shfl_xor(ss, 32);
;           if (fq_e == 0) epi.rowsum(g, rig, nt * 2 + wc_e, ss);
;         } else {
; #pragma unroll
;           for (int n = 0; n < 8; ++n) {
;             const int col = nt * 256 + wc_e * 128 + n * 16 + fq_e * 4;
;             if (col < N) epi.c4(g, rig, col, acc[m][n]);
;           }
;         }
	v_lshlrev_b32_e32 v90, 16, v184
	v_and_b32_e32 v88, 0xffff0000, v184
	v_lshlrev_b32_e32 v91, 16, v185
	v_and_b32_e32 v89, 0xffff0000, v185
	v_fmac_f32_e32 v90, v78, v214
	v_fmac_f32_e32 v88, v79, v215
	v_fmac_f32_e32 v91, v80, v216
	v_fmac_f32_e32 v89, v81, v217
	v_cvt_pk_bf16_f32 v78, v90, v88
	v_cvt_pk_bf16_f32 v79, v91, v89
	v_lshl_add_u64 v[82:83], v[132:133], 1, v[98:99]
	v_add_f32_e32 v74, 0, v74
	v_add_f32_e32 v75, 0, v75
	v_add_f32_e32 v76, 0, v76
	v_add_f32_e32 v77, 0, v77
	s_waitcnt vmcnt(4)
	v_lshlrev_b32_e32 v86, 16, v186
	v_and_b32_e32 v84, 0xffff0000, v186
	v_lshlrev_b32_e32 v87, 16, v187
	v_and_b32_e32 v85, 0xffff0000, v187
	v_fmac_f32_e32 v86, v74, v224
	v_fmac_f32_e32 v84, v75, v225
	v_fmac_f32_e32 v87, v76, v226
	v_fmac_f32_e32 v85, v77, v227
	v_cvt_pk_bf16_f32 v80, v86, v84
	v_cvt_pk_bf16_f32 v81, v87, v85
	s_nop 1
	v_permlane16_swap_b32 v78, v80
	v_permlane16_swap_b32 v79, v81
	v_lshl_add_u64 v[248:249], v[82:83], 0, v[246:247]
	s_nop 0
	global_store_dwordx4 v[248:249], v[78:81], off offset:128
	s_nop 1
	v_lshl_add_u64 v[78:79], v[132:133], 1, v[98:99]
	v_add_f32_e32 v70, 0, v70
	v_add_f32_e32 v71, 0, v71
	v_add_f32_e32 v72, 0, v72
	v_add_f32_e32 v73, 0, v73
	s_waitcnt vmcnt(4)
	v_lshlrev_b32_e32 v82, 16, v188
	v_and_b32_e32 v80, 0xffff0000, v188
	v_lshlrev_b32_e32 v83, 16, v189
	v_and_b32_e32 v81, 0xffff0000, v189
	v_fmac_f32_e32 v82, v70, v228
	v_fmac_f32_e32 v80, v71, v229
	v_fmac_f32_e32 v83, v72, v230
	v_fmac_f32_e32 v81, v73, v231
	v_cvt_pk_bf16_f32 v70, v82, v80
	v_cvt_pk_bf16_f32 v71, v83, v81
	v_lshl_add_u64 v[74:75], v[132:133], 1, v[98:99]
	v_add_f32_e32 v66, 0, v66
	v_add_f32_e32 v67, 0, v67
	v_add_f32_e32 v68, 0, v68
	v_add_f32_e32 v69, 0, v69
	s_waitcnt vmcnt(3)
	v_lshlrev_b32_e32 v78, 16, v190
	v_and_b32_e32 v76, 0xffff0000, v190
	v_lshlrev_b32_e32 v79, 16, v191
	v_and_b32_e32 v77, 0xffff0000, v191
	v_fmac_f32_e32 v78, v66, v232
	v_fmac_f32_e32 v76, v67, v233
	v_fmac_f32_e32 v79, v68, v234
	v_fmac_f32_e32 v77, v69, v235
	v_cvt_pk_bf16_f32 v72, v78, v76
	v_cvt_pk_bf16_f32 v73, v79, v77
	s_nop 1
	v_permlane16_swap_b32 v70, v72
	v_permlane16_swap_b32 v71, v73
	v_lshl_add_u64 v[248:249], v[74:75], 0, v[246:247]
	s_nop 0
	global_store_dwordx4 v[248:249], v[70:73], off offset:192
	s_nop 1
	v_or_b32_e32 v66, 32, v136
	v_ashrrev_i32_e32 v67, 31, v66
	v_lshlrev_b64 v[66:67], 10, v[66:67]
	v_lshl_add_u64 v[66:67], v[66:67], 0, v[138:139]
	v_lshl_add_u64 v[66:67], v[66:67], 1, s[20:21]
	v_lshl_add_u64 v[72:73], v[132:133], 1, v[66:67]
	v_lshl_add_u64 v[196:197], v[132:133], 1, v[66:67]
	global_load_dwordx2 v[176:177], v[196:197], off
	global_load_dwordx2 v[178:179], v[196:197], off offset:32
	global_load_dwordx2 v[180:181], v[196:197], off offset:64
	global_load_dwordx2 v[182:183], v[196:197], off offset:96
	global_load_dwordx2 v[184:185], v[196:197], off offset:128
	global_load_dwordx2 v[186:187], v[196:197], off offset:160
	global_load_dwordx2 v[188:189], v[196:197], off offset:192
	global_load_dwordx2 v[190:191], v[196:197], off offset:224
	v_add_f32_e32 v62, 0, v62
	v_add_f32_e32 v63, 0, v63
	v_add_f32_e32 v64, 0, v64
	v_add_f32_e32 v65, 0, v65
	s_waitcnt vmcnt(7)
	v_lshlrev_b32_e32 v76, 16, v176
	v_and_b32_e32 v74, 0xffff0000, v176
	v_lshlrev_b32_e32 v77, 16, v177
	v_and_b32_e32 v75, 0xffff0000, v177
	v_fmac_f32_e32 v76, v62, v198
	v_fmac_f32_e32 v74, v63, v199
	v_fmac_f32_e32 v77, v64, v200
	v_fmac_f32_e32 v75, v65, v201
	v_cvt_pk_bf16_f32 v62, v76, v74
	v_cvt_pk_bf16_f32 v63, v77, v75
	v_lshl_add_u64 v[68:69], v[132:133], 1, v[66:67]
	v_add_f32_e32 v58, 0, v58
	v_add_f32_e32 v59, 0, v59
	v_add_f32_e32 v60, 0, v60
	v_add_f32_e32 v61, 0, v61
	s_waitcnt vmcnt(6)
	v_lshlrev_b32_e32 v72, 16, v178
	v_and_b32_e32 v70, 0xffff0000, v178
	v_lshlrev_b32_e32 v73, 16, v179
	v_and_b32_e32 v71, 0xffff0000, v179
	v_fmac_f32_e32 v72, v58, v202
	v_fmac_f32_e32 v70, v59, v203
	v_fmac_f32_e32 v73, v60, v204
	v_fmac_f32_e32 v71, v61, v205
	v_cvt_pk_bf16_f32 v64, v72, v70
	v_cvt_pk_bf16_f32 v65, v73, v71
	s_nop 1
	v_permlane16_swap_b32 v62, v64
	v_permlane16_swap_b32 v63, v65
	v_lshl_add_u64 v[248:249], v[68:69], 0, v[246:247]
	s_nop 0
	global_store_dwordx4 v[248:249], v[62:65], off
	s_nop 1
	v_lshl_add_u64 v[62:63], v[132:133], 1, v[66:67]
	v_add_f32_e32 v54, 0, v54
	v_add_f32_e32 v55, 0, v55
	v_add_f32_e32 v56, 0, v56
	v_add_f32_e32 v57, 0, v57
	s_waitcnt vmcnt(6)
	v_lshlrev_b32_e32 v68, 16, v180
	v_and_b32_e32 v64, 0xffff0000, v180
	v_lshlrev_b32_e32 v69, 16, v181
	v_and_b32_e32 v65, 0xffff0000, v181
	v_fmac_f32_e32 v68, v54, v206
	v_fmac_f32_e32 v64, v55, v207
	v_fmac_f32_e32 v69, v56, v208
	v_fmac_f32_e32 v65, v57, v209
	v_cvt_pk_bf16_f32 v54, v68, v64
	v_cvt_pk_bf16_f32 v55, v69, v65
	v_lshl_add_u64 v[58:59], v[132:133], 1, v[66:67]
	v_add_f32_e32 v50, 0, v50
	v_add_f32_e32 v51, 0, v51
	v_add_f32_e32 v52, 0, v52
	v_add_f32_e32 v53, 0, v53
	s_waitcnt vmcnt(5)
	v_lshlrev_b32_e32 v62, 16, v182
	v_and_b32_e32 v60, 0xffff0000, v182
	v_lshlrev_b32_e32 v63, 16, v183
	v_and_b32_e32 v61, 0xffff0000, v183
	v_fmac_f32_e32 v62, v50, v210
	v_fmac_f32_e32 v60, v51, v211
	v_fmac_f32_e32 v63, v52, v212
	v_fmac_f32_e32 v61, v53, v213
	v_cvt_pk_bf16_f32 v56, v62, v60
	v_cvt_pk_bf16_f32 v57, v63, v61
	s_nop 1
	v_permlane16_swap_b32 v54, v56
	v_permlane16_swap_b32 v55, v57
	v_lshl_add_u64 v[248:249], v[58:59], 0, v[246:247]
	s_nop 0
	global_store_dwordx4 v[248:249], v[54:57], off offset:64
	s_nop 1
	v_lshl_add_u64 v[54:55], v[132:133], 1, v[66:67]
	v_add_f32_e32 v46, 0, v46
	v_add_f32_e32 v47, 0, v47
	v_add_f32_e32 v48, 0, v48
	v_add_f32_e32 v49, 0, v49
	s_waitcnt vmcnt(5)
; __device__ __forceinline__ unsigned pack2(float a, float b) { unsigned r; asm("v_cvt_pk_bf16_f32 %0, %1, %2" : "=v"(r) : "v"(a), "v"(b)); return r; }
; __device__ __forceinline__ float bf2f(bf16_t h) { return __uint_as_float(((unsigned)h) << 16); }
;   __device__ __forceinline__ void c4(int g, int rig, int col, f32x4 v) const {
;     const size_t o = ((size_t)g * 2048 + rig) * 1024 + col;
;     f32x4 bs;
;     if (BASE_F32) bs = __builtin_nontemporal_load((const f32x4*)((const float*)base + o));
;     else {
;       const uint2 u = *(const uint2*)((const bf16_t*)base + o);
;       bs[0] = bf2f((bf16_t)(u.x & 0xffff)); bs[1] = bf2f((bf16_t)(u.x >> 16)); bs[2] = bf2f((bf16_t)(u.y & 0xffff)); bs[3] = bf2f((bf16_t)(u.y >> 16));
;     }
;     const f32x4 gt = *(const f32x4*)(gate + (size_t)g * 6144 + col);
;     f32x4 bi = {0.f, 0.f, 0.f, 0.f};
;     if (bias) bi = *(const f32x4*)(bias + col);
;     f32x4 r;
; #pragma unroll
;     for (int j = 0; j < 4; ++j) r[j] = bs[j] + gt[j] * (v[j] + bi[j]);
;     uint2 w; w.x = pack2(r[0], r[1]); w.y = pack2(r[2], r[3]);
;     *(uint2*)(X16 + o) = w;
;   }
; template <bool SWAP, class Epi, bool THIN = false> ...
;     ...
;     if constexpr (Epi::KIND == 0) {
; #pragma unroll
;       for (int m = 0; m < 4; ++m) {
;         const int rig = rig0 + rw + m * 16 + fr_e;
;         if constexpr (Epi::ROWSUM) {
;           float ss = 0.f;
; #pragma unroll
;           for (int n = 0; n < 8; ++n) {
;             const int col = nt * 256 + wc_e * 128 + n * 16 + fq_e * 4;
;             if (col < N) ss += epi.c4(g, rig, col, acc[m][n]);
;           }
;           ss += __shfl_xor(ss, 16); ss += __shfl_xor(ss, 32);
;           if (fq_e == 0) epi.rowsum(g, rig, nt * 2 + wc_e, ss);
;         } else {
; #pragma unroll
;           for (int n = 0; n < 8; ++n) {
;             const int col = nt * 256 + wc_e * 128 + n * 16 + fq_e * 4;
;             if (col < N) epi.c4(g, rig, col, acc[m][n]);
;           }
;         }
	v_lshlrev_b32_e32 v58, 16, v184
	v_and_b32_e32 v56, 0xffff0000, v184
	v_lshlrev_b32_e32 v59, 16, v185
	v_and_b32_e32 v57, 0xffff0000, v185
	v_fmac_f32_e32 v58, v46, v214
	v_fmac_f32_e32 v56, v47, v215
	v_fmac_f32_e32 v59, v48, v216
	v_fmac_f32_e32 v57, v49, v217
	v_cvt_pk_bf16_f32 v46, v58, v56
	v_cvt_pk_bf16_f32 v47, v59, v57
	v_lshl_add_u64 v[50:51], v[132:133], 1, v[66:67]
	v_add_f32_e32 v42, 0, v42
	v_add_f32_e32 v43, 0, v43
	v_add_f32_e32 v44, 0, v44
	v_add_f32_e32 v45, 0, v45
	s_waitcnt vmcnt(4)
	v_lshlrev_b32_e32 v54, 16, v186
	v_and_b32_e32 v52, 0xffff0000, v186
	v_lshlrev_b32_e32 v55, 16, v187
	v_and_b32_e32 v53, 0xffff0000, v187
	v_fmac_f32_e32 v54, v42, v224
	v_fmac_f32_e32 v52, v43, v225
	v_fmac_f32_e32 v55, v44, v226
	v_fmac_f32_e32 v53, v45, v227
	v_cvt_pk_bf16_f32 v48, v54, v52
	v_cvt_pk_bf16_f32 v49, v55, v53
	s_nop 1
	v_permlane16_swap_b32 v46, v48
	v_permlane16_swap_b32 v47, v49
	v_lshl_add_u64 v[248:249], v[50:51], 0, v[246:247]
	s_nop 0
	global_store_dwordx4 v[248:249], v[46:49], off offset:128
	s_nop 1
	v_lshl_add_u64 v[46:47], v[132:133], 1, v[66:67]
	v_add_f32_e32 v38, 0, v38
	v_add_f32_e32 v39, 0, v39
	v_add_f32_e32 v40, 0, v40
	v_add_f32_e32 v41, 0, v41
	s_waitcnt vmcnt(4)
	v_lshlrev_b32_e32 v50, 16, v188
	v_and_b32_e32 v48, 0xffff0000, v188
	v_lshlrev_b32_e32 v51, 16, v189
	v_and_b32_e32 v49, 0xffff0000, v189
	v_fmac_f32_e32 v50, v38, v228
	v_fmac_f32_e32 v48, v39, v229
	v_fmac_f32_e32 v51, v40, v230
	v_fmac_f32_e32 v49, v41, v231
	v_cvt_pk_bf16_f32 v38, v50, v48
	v_cvt_pk_bf16_f32 v39, v51, v49
	v_lshl_add_u64 v[42:43], v[132:133], 1, v[66:67]
	v_add_f32_e32 v34, 0, v34
	v_add_f32_e32 v35, 0, v35
	v_add_f32_e32 v36, 0, v36
	v_add_f32_e32 v37, 0, v37
	s_waitcnt vmcnt(3)
	v_lshlrev_b32_e32 v46, 16, v190
	v_and_b32_e32 v44, 0xffff0000, v190
	v_lshlrev_b32_e32 v47, 16, v191
	v_and_b32_e32 v45, 0xffff0000, v191
	v_fmac_f32_e32 v46, v34, v232
	v_fmac_f32_e32 v44, v35, v233
	v_fmac_f32_e32 v47, v36, v234
	v_fmac_f32_e32 v45, v37, v235
	v_cvt_pk_bf16_f32 v40, v46, v44
	v_cvt_pk_bf16_f32 v41, v47, v45
	s_nop 1
	v_permlane16_swap_b32 v38, v40
	v_permlane16_swap_b32 v39, v41
	v_lshl_add_u64 v[248:249], v[42:43], 0, v[246:247]
	s_nop 0
	global_store_dwordx4 v[248:249], v[38:41], off offset:192
	s_nop 1
	v_or_b32_e32 v34, 48, v136
	v_ashrrev_i32_e32 v35, 31, v34
	v_lshlrev_b64 v[34:35], 10, v[34:35]
	v_lshl_add_u64 v[34:35], v[34:35], 0, v[138:139]
	v_lshl_add_u64 v[34:35], v[34:35], 1, s[20:21]
	v_lshl_add_u64 v[40:41], v[132:133], 1, v[34:35]
	v_lshl_add_u64 v[196:197], v[132:133], 1, v[34:35]
	global_load_dwordx2 v[176:177], v[196:197], off
	global_load_dwordx2 v[178:179], v[196:197], off offset:32
	global_load_dwordx2 v[180:181], v[196:197], off offset:64
	global_load_dwordx2 v[182:183], v[196:197], off offset:96
	global_load_dwordx2 v[184:185], v[196:197], off offset:128
	global_load_dwordx2 v[186:187], v[196:197], off offset:160
	global_load_dwordx2 v[188:189], v[196:197], off offset:192
	global_load_dwordx2 v[190:191], v[196:197], off offset:224
	v_add_f32_e32 v30, 0, v30
	v_add_f32_e32 v31, 0, v31
	v_add_f32_e32 v32, 0, v32
	v_add_f32_e32 v33, 0, v33
	s_waitcnt vmcnt(7)
	v_lshlrev_b32_e32 v44, 16, v176
	v_and_b32_e32 v42, 0xffff0000, v176
	v_lshlrev_b32_e32 v45, 16, v177
	v_and_b32_e32 v43, 0xffff0000, v177
	v_fmac_f32_e32 v44, v30, v198
	v_fmac_f32_e32 v42, v31, v199
	v_fmac_f32_e32 v45, v32, v200
	v_fmac_f32_e32 v43, v33, v201
	v_cvt_pk_bf16_f32 v30, v44, v42
	v_cvt_pk_bf16_f32 v31, v45, v43
	v_lshl_add_u64 v[36:37], v[132:133], 1, v[34:35]
	v_add_f32_e32 v26, 0, v26
	v_add_f32_e32 v27, 0, v27
	v_add_f32_e32 v28, 0, v28
	v_add_f32_e32 v29, 0, v29
	s_waitcnt vmcnt(6)
; __device__ __forceinline__ unsigned pack2(float a, float b) { unsigned r; asm("v_cvt_pk_bf16_f32 %0, %1, %2" : "=v"(r) : "v"(a), "v"(b)); return r; }
; __device__ __forceinline__ float bf2f(bf16_t h) { return __uint_as_float(((unsigned)h) << 16); }
;   __device__ __forceinline__ void c4(int g, int rig, int col, f32x4 v) const {
;     const size_t o = ((size_t)g * 2048 + rig) * 1024 + col;
;     f32x4 bs;
;     if (BASE_F32) bs = __builtin_nontemporal_load((const f32x4*)((const float*)base + o));
;     else {
;       const uint2 u = *(const uint2*)((const bf16_t*)base + o);
;       bs[0] = bf2f((bf16_t)(u.x & 0xffff)); bs[1] = bf2f((bf16_t)(u.x >> 16)); bs[2] = bf2f((bf16_t)(u.y & 0xffff)); bs[3] = bf2f((bf16_t)(u.y >> 16));
;     }
;     const f32x4 gt = *(const f32x4*)(gate + (size_t)g * 6144 + col);
;     f32x4 bi = {0.f, 0.f, 0.f, 0.f};
;     if (bias) bi = *(const f32x4*)(bias + col);
;     f32x4 r;
; #pragma unroll
;     for (int j = 0; j < 4; ++j) r[j] = bs[j] + gt[j] * (v[j] + bi[j]);
;     uint2 w; w.x = pack2(r[0], r[1]); w.y = pack2(r[2], r[3]);
;     *(uint2*)(X16 + o) = w;
;   }
; template <bool SWAP, class Epi, bool THIN = false> ...
;     ...
;     if constexpr (Epi::KIND == 0) {
; #pragma unroll
;       for (int m = 0; m < 4; ++m) {
;         const int rig = rig0 + rw + m * 16 + fr_e;
;         if constexpr (Epi::ROWSUM) {
;           float ss = 0.f;
; #pragma unroll
;           for (int n = 0; n < 8; ++n) {
;             const int col = nt * 256 + wc_e * 128 + n * 16 + fq_e * 4;
;             if (col < N) ss += epi.c4(g, rig, col, acc[m][n]);
;           }
;           ss += __shfl_xor(ss, 16); ss += __shfl_xor(ss, 32);
;           if (fq_e == 0) epi.rowsum(g, rig, nt * 2 + wc_e, ss);
;         } else {
; #pragma unroll
;           for (int n = 0; n < 8; ++n) {
;             const int col = nt * 256 + wc_e * 128 + n * 16 + fq_e * 4;
;             if (col < N) epi.c4(g, rig, col, acc[m][n]);
;           }
;         }
	v_lshlrev_b32_e32 v40, 16, v178
	v_and_b32_e32 v38, 0xffff0000, v178
	v_lshlrev_b32_e32 v41, 16, v179
	v_and_b32_e32 v39, 0xffff0000, v179
	v_fmac_f32_e32 v40, v26, v202
	v_fmac_f32_e32 v38, v27, v203
	v_fmac_f32_e32 v41, v28, v204
	v_fmac_f32_e32 v39, v29, v205
	v_cvt_pk_bf16_f32 v32, v40, v38
	v_cvt_pk_bf16_f32 v33, v41, v39
	s_nop 1
	v_permlane16_swap_b32 v30, v32
	v_permlane16_swap_b32 v31, v33
	v_lshl_add_u64 v[248:249], v[36:37], 0, v[246:247]
	s_nop 0
	global_store_dwordx4 v[248:249], v[30:33], off
	s_nop 1
	v_lshl_add_u64 v[30:31], v[132:133], 1, v[34:35]
	v_add_f32_e32 v22, 0, v22
	v_add_f32_e32 v23, 0, v23
	v_add_f32_e32 v24, 0, v24
	v_add_f32_e32 v25, 0, v25
	s_waitcnt vmcnt(6)
	v_lshlrev_b32_e32 v36, 16, v180
	v_and_b32_e32 v32, 0xffff0000, v180
	v_lshlrev_b32_e32 v37, 16, v181
	v_and_b32_e32 v33, 0xffff0000, v181
	v_fmac_f32_e32 v36, v22, v206
	v_fmac_f32_e32 v32, v23, v207
	v_fmac_f32_e32 v37, v24, v208
	v_fmac_f32_e32 v33, v25, v209
	v_cvt_pk_bf16_f32 v22, v36, v32
	v_cvt_pk_bf16_f32 v23, v37, v33
	v_lshl_add_u64 v[26:27], v[132:133], 1, v[34:35]
	v_add_f32_e32 v18, 0, v18
	v_add_f32_e32 v19, 0, v19
	v_add_f32_e32 v20, 0, v20
	v_add_f32_e32 v21, 0, v21
	s_waitcnt vmcnt(5)
	v_lshlrev_b32_e32 v30, 16, v182
	v_and_b32_e32 v28, 0xffff0000, v182
	v_lshlrev_b32_e32 v31, 16, v183
	v_and_b32_e32 v29, 0xffff0000, v183
	v_fmac_f32_e32 v30, v18, v210
	v_fmac_f32_e32 v28, v19, v211
	v_fmac_f32_e32 v31, v20, v212
	v_fmac_f32_e32 v29, v21, v213
	v_cvt_pk_bf16_f32 v24, v30, v28
	v_cvt_pk_bf16_f32 v25, v31, v29
	s_nop 1
	v_permlane16_swap_b32 v22, v24
	v_permlane16_swap_b32 v23, v25
	v_lshl_add_u64 v[248:249], v[26:27], 0, v[246:247]
	s_nop 0
	global_store_dwordx4 v[248:249], v[22:25], off offset:64
	s_nop 1
	v_lshl_add_u64 v[22:23], v[132:133], 1, v[34:35]
	v_add_f32_e32 v14, 0, v14
	v_add_f32_e32 v15, 0, v15
	v_add_f32_e32 v16, 0, v16
	v_add_f32_e32 v17, 0, v17
	s_waitcnt vmcnt(5)
	v_lshlrev_b32_e32 v26, 16, v184
	v_and_b32_e32 v24, 0xffff0000, v184
	v_lshlrev_b32_e32 v27, 16, v185
	v_and_b32_e32 v25, 0xffff0000, v185
	v_fmac_f32_e32 v26, v14, v214
	v_fmac_f32_e32 v24, v15, v215
	v_fmac_f32_e32 v27, v16, v216
	v_fmac_f32_e32 v25, v17, v217
	v_cvt_pk_bf16_f32 v14, v26, v24
	v_cvt_pk_bf16_f32 v15, v27, v25
	v_lshl_add_u64 v[18:19], v[132:133], 1, v[34:35]
	v_add_f32_e32 v10, 0, v10
	v_add_f32_e32 v11, 0, v11
	v_add_f32_e32 v12, 0, v12
	v_add_f32_e32 v13, 0, v13
	s_waitcnt vmcnt(4)
	v_lshlrev_b32_e32 v22, 16, v186
	v_and_b32_e32 v20, 0xffff0000, v186
	v_lshlrev_b32_e32 v23, 16, v187
	v_and_b32_e32 v21, 0xffff0000, v187
	v_fmac_f32_e32 v22, v10, v224
	v_fmac_f32_e32 v20, v11, v225
	v_fmac_f32_e32 v23, v12, v226
	v_fmac_f32_e32 v21, v13, v227
	v_cvt_pk_bf16_f32 v16, v22, v20
	v_cvt_pk_bf16_f32 v17, v23, v21
	s_nop 1
	v_permlane16_swap_b32 v14, v16
	v_permlane16_swap_b32 v15, v17
	v_lshl_add_u64 v[248:249], v[18:19], 0, v[246:247]
	s_nop 0
	global_store_dwordx4 v[248:249], v[14:17], off offset:128
	s_nop 1
	v_lshl_add_u64 v[14:15], v[132:133], 1, v[34:35]
	v_add_f32_e32 v6, 0, v6
	v_add_f32_e32 v7, 0, v7
	v_add_f32_e32 v8, 0, v8
	v_add_f32_e32 v9, 0, v9
	s_waitcnt vmcnt(4)
	v_lshlrev_b32_e32 v18, 16, v188
	v_and_b32_e32 v16, 0xffff0000, v188
	v_lshlrev_b32_e32 v19, 16, v189
	v_and_b32_e32 v17, 0xffff0000, v189
	v_fmac_f32_e32 v18, v6, v228
	v_fmac_f32_e32 v16, v7, v229
	v_fmac_f32_e32 v19, v8, v230
	v_fmac_f32_e32 v17, v9, v231
	v_cvt_pk_bf16_f32 v6, v18, v16
	v_cvt_pk_bf16_f32 v7, v19, v17
	v_lshl_add_u64 v[10:11], v[132:133], 1, v[34:35]
	v_add_f32_e32 v2, 0, v2
	v_add_f32_e32 v3, 0, v3
	v_add_f32_e32 v4, 0, v4
	v_add_f32_e32 v5, 0, v5
	s_waitcnt vmcnt(3)
	v_lshlrev_b32_e32 v14, 16, v190
	v_and_b32_e32 v12, 0xffff0000, v190
	v_lshlrev_b32_e32 v15, 16, v191
	v_and_b32_e32 v13, 0xffff0000, v191
	v_fmac_f32_e32 v14, v2, v232
	v_fmac_f32_e32 v12, v3, v233
	v_fmac_f32_e32 v15, v4, v234
	v_fmac_f32_e32 v13, v5, v235
	v_cvt_pk_bf16_f32 v8, v14, v12
	v_cvt_pk_bf16_f32 v9, v15, v13
	s_nop 1
	v_permlane16_swap_b32 v6, v8
	v_permlane16_swap_b32 v7, v9
	v_lshl_add_u64 v[248:249], v[10:11], 0, v[246:247]
	s_nop 0
	global_store_dwordx4 v[248:249], v[6:9], off offset:192
	s_nop 1
	s_branch .LBB0_2427

; template <bool SWAP, class Epi, bool THIN = false> ...
;     ...
;     for (int st = 0; st < ns; ++st) {
;       asm volatile("s_waitcnt vmcnt(0)" ::: "memory");
;       __builtin_amdgcn_s_barrier();
;       asm volatile("" ::: "memory");
;       if (st + 1 < ns) {
;         char* nb = smem + ((st + 1) & 1) * 65536;
;         const int ko = (st + 1) * 64;
; #pragma unroll
;         for (int i = 0; i < 4; ++i) { GLDS16(A + (size_t)(ap[i] + ko), nb + tid * 16 + i * 8192); GLDS16(Bt + (size_t)(bp[i] + ko), nb + 32768 + tid * 16 + i * 8192); }
;       }
;       const char* sa = smem + (st & 1) * 65536 + (wr * 64 + fr) * 128;
;       const char* sb = smem + (st & 1) * 65536 + 32768 + (wc * 128 + fr) * 128;
;       if constexpr (THIN) {
;         if (wc == 0) {
; #pragma unroll
;           for (int ks = 0; ks < 2; ++ks) {
;             bf16x8 af[4], bf[2];
; #pragma unroll
;             for (int m = 0; m < 4; ++m) af[m] = *(const bf16x8*)(sa + m * 2048 + (((ks * 4 + fq) ^ swz) << 4));
; #pragma unroll
;             for (int n = 0; n < 2; ++n) bf[n] = *(const bf16x8*)(sb + n * 2048 + (((ks * 4 + fq) ^ swz) << 4));
; #pragma unroll
;             for (int m = 0; m < 4; ++m)
; #pragma unroll
;               for (int n = 0; n < 2; ++n)
;                 acc[m][n] = SWAP ? __builtin_amdgcn_mfma_f32_16x16x32_bf16(bf[n], af[m], acc[m][n], 0, 0, 0)
;                                  : __builtin_amdgcn_mfma_f32_16x16x32_bf16(af[m], bf[n], acc[m][n], 0, 0, 0);
;           }
;         }
;       } else {
;       bf16x8 afA[4], afB[4], bfb[2][2];
; #pragma unroll
;       for (int m = 0; m < 4; ++m) afA[m] = *(const bf16x8*)(sa + m * 2048 + ((fq ^ swz) << 4));
; #pragma unroll
;       for (int n = 0; n < 2; ++n) bfb[0][n] = *(const bf16x8*)(sb + n * 2048 + ((fq ^ swz) << 4));
; #pragma unroll
;       for (int gq = 0; gq < 8; ++gq) {
;         const int ks = gq >> 2, nh = gq & 3;
;         if (gq < 7) {
;           const int ks2 = (gq + 1) >> 2, nh2 = (gq + 1) & 3;
; #pragma unroll
;           for (int n = 0; n < 2; ++n) bfb[(gq + 1) & 1][n] = *(const bf16x8*)(sb + (nh2 * 2 + n) * 2048 + (((ks2 * 4 + fq) ^ swz) << 4));
;         }
;         if (gq == 3) {
; #pragma unroll
;           for (int m = 0; m < 4; ++m) afB[m] = *(const bf16x8*)(sa + m * 2048 + (((4 + fq) ^ swz) << 4));
;         }
;         __builtin_amdgcn_sched_barrier(0);
; #pragma unroll
.LBB0_2643:
	s_add_i32 s8, s7, 0x10000
	s_and_b32 s9, s8, 0x10000
	v_add_u32_e32 v167, s9, v142
	s_nop 0
	v_readfirstlane_b32 s9, v167
	s_waitcnt vmcnt(0)
	s_barrier
	s_and_b32 s7, s7, 0x10000
	v_add_u32_e32 v130, s7, v143
	v_add_u32_e32 v167, v130, v145
	ds_read_b128 v[168:171], v167
	ds_read_b128 v[172:175], v167 offset:2048
	ds_read_b128 v[176:179], v167 offset:4096
	ds_read_b128 v[180:183], v167 offset:6144
	v_or_b32_e32 v167, s7, v144
	v_add_u32_e32 v204, v167, v145
	ds_read_b128 v[184:187], v204 offset:32768
	ds_read_b128 v[188:191], v204 offset:34816
	ds_read_b128 v[192:195], v204 offset:36864
	ds_read_b128 v[196:199], v204 offset:38912
	v_add_u32_e32 v130, v130, v146
	s_waitcnt lgkmcnt(3)
	v_mfma_f32_16x16x32_bf16 v[126:129], v[184:187], v[168:171], v[126:129]
	s_mov_b32 m0, s9
	v_mfma_f32_16x16x32_bf16 v[110:113], v[184:187], v[172:175], v[110:113]
	global_load_lds_dwordx4 v139, s[18:19]
	v_add_u32_e32 v139, 0x80, v139
	v_mfma_f32_16x16x32_bf16 v[82:85], v[184:187], v[176:179], v[82:85]
	v_mfma_f32_16x16x32_bf16 v[50:53], v[184:187], v[180:183], v[50:53]
	ds_read_b128 v[184:187], v204 offset:40960
	ds_read_b128 v[200:203], v204 offset:43008
	s_waitcnt lgkmcnt(4)
	v_mfma_f32_16x16x32_bf16 v[122:125], v[188:191], v[168:171], v[122:125]
	s_add_u32 m0, s9, 0x8000
	v_mfma_f32_16x16x32_bf16 v[106:109], v[188:191], v[172:175], v[106:109]
	global_load_lds_dwordx4 v138, s[24:25]
	v_add_u32_e32 v138, 0x80, v138
	v_mfma_f32_16x16x32_bf16 v[78:81], v[188:191], v[176:179], v[78:81]
	v_mfma_f32_16x16x32_bf16 v[42:45], v[188:191], v[180:183], v[42:45]
	s_waitcnt lgkmcnt(3)
	v_mfma_f32_16x16x32_bf16 v[118:121], v[192:195], v[168:171], v[118:121]
	s_add_u32 m0, s9, 0x2000
	v_mfma_f32_16x16x32_bf16 v[94:97], v[192:195], v[172:175], v[94:97]
	global_load_lds_dwordx4 v137, s[18:19]
	v_add_u32_e32 v137, 0x80, v137
	v_mfma_f32_16x16x32_bf16 v[58:61], v[192:195], v[176:179], v[58:61]
	v_mfma_f32_16x16x32_bf16 v[26:29], v[192:195], v[180:183], v[26:29]
	ds_read_b128 v[188:191], v204 offset:45056
	ds_read_b128 v[192:195], v204 offset:47104
	s_waitcnt lgkmcnt(4)
	v_mfma_f32_16x16x32_bf16 v[114:117], v[196:199], v[168:171], v[114:117]
	s_add_u32 m0, s9, 0xa000
	v_mfma_f32_16x16x32_bf16 v[86:89], v[196:199], v[172:175], v[86:89]
	global_load_lds_dwordx4 v136, s[24:25]
	v_add_u32_e32 v136, 0x80, v136
	v_mfma_f32_16x16x32_bf16 v[54:57], v[196:199], v[176:179], v[54:57]
	v_mfma_f32_16x16x32_bf16 v[22:25], v[196:199], v[180:183], v[22:25]
	v_add_u32_e32 v167, v167, v146
	s_waitcnt lgkmcnt(3)
	v_mfma_f32_16x16x32_bf16 v[102:105], v[184:187], v[168:171], v[102:105]
	ds_read_b128 v[196:199], v167 offset:32768
	ds_read_b128 v[204:207], v167 offset:34816
	s_add_u32 m0, s9, 0x4000
	v_mfma_f32_16x16x32_bf16 v[74:77], v[184:187], v[172:175], v[74:77]
	global_load_lds_dwordx4 v135, s[18:19]
	v_add_u32_e32 v135, 0x80, v135
	v_mfma_f32_16x16x32_bf16 v[46:49], v[184:187], v[176:179], v[46:49]
	v_mfma_f32_16x16x32_bf16 v[10:13], v[184:187], v[180:183], v[10:13]
	ds_read_b128 v[184:187], v130
	ds_read_b128 v[208:211], v130 offset:2048
	ds_read_b128 v[212:215], v130 offset:4096
	ds_read_b128 v[216:219], v130 offset:6144
	s_waitcnt lgkmcnt(8)
	v_mfma_f32_16x16x32_bf16 v[98:101], v[200:203], v[168:171], v[98:101]
	s_add_u32 m0, s9, 0xc000
	v_mfma_f32_16x16x32_bf16 v[66:69], v[200:203], v[172:175], v[66:69]
	global_load_lds_dwordx4 v134, s[24:25]
	v_add_u32_e32 v134, 0x80, v134
	v_mfma_f32_16x16x32_bf16 v[30:33], v[200:203], v[176:179], v[30:33]
	v_mfma_f32_16x16x32_bf16 v[6:9], v[200:203], v[180:183], v[6:9]
	s_waitcnt lgkmcnt(7)
	v_mfma_f32_16x16x32_bf16 v[70:73], v[188:191], v[168:171], v[70:73]
	s_add_u32 m0, s9, 0x6000
	s_waitcnt lgkmcnt(6)
	v_mfma_f32_16x16x32_bf16 v[62:65], v[192:195], v[168:171], v[62:65]
	global_load_lds_dwordx4 v133, s[18:19]
	v_add_u32_e32 v133, 0x80, v133
	v_mfma_f32_16x16x32_bf16 v[38:41], v[188:191], v[172:175], v[38:41]
	v_mfma_f32_16x16x32_bf16 v[34:37], v[192:195], v[172:175], v[34:37]
	ds_read_b128 v[168:171], v167 offset:36864
	ds_read_b128 v[172:175], v167 offset:38912
	v_mfma_f32_16x16x32_bf16 v[18:21], v[188:191], v[176:179], v[18:21]
	s_add_u32 m0, s9, 0xe000
	v_mfma_f32_16x16x32_bf16 v[14:17], v[192:195], v[176:179], v[14:17]
	global_load_lds_dwordx4 v132, s[24:25]
	v_add_u32_e32 v132, 0x80, v132
	v_mfma_f32_16x16x32_bf16 v[2:5], v[188:191], v[180:183], v[2:5]
	v_mfma_f32_16x16x32_bf16 v[90:93], v[192:195], v[180:183], v[90:93]
	ds_read_b128 v[176:179], v167 offset:40960
	ds_read_b128 v[180:183], v167 offset:43008
	s_waitcnt lgkmcnt(7)
	v_mfma_f32_16x16x32_bf16 v[126:129], v[196:199], v[184:187], v[126:129]
	v_mfma_f32_16x16x32_bf16 v[122:125], v[204:207], v[184:187], v[122:125]
	s_waitcnt lgkmcnt(6)
	v_mfma_f32_16x16x32_bf16 v[110:113], v[196:199], v[208:211], v[110:113]
	v_mfma_f32_16x16x32_bf16 v[106:109], v[204:207], v[208:211], v[106:109]
	s_waitcnt lgkmcnt(5)
	v_mfma_f32_16x16x32_bf16 v[82:85], v[196:199], v[212:215], v[82:85]
	v_mfma_f32_16x16x32_bf16 v[78:81], v[204:207], v[212:215], v[78:81]
	s_waitcnt lgkmcnt(4)
	v_mfma_f32_16x16x32_bf16 v[50:53], v[196:199], v[216:219], v[50:53]
	v_mfma_f32_16x16x32_bf16 v[42:45], v[204:207], v[216:219], v[42:45]
	s_waitcnt lgkmcnt(3)
	v_mfma_f32_16x16x32_bf16 v[118:121], v[168:171], v[184:187], v[118:121]
	v_mfma_f32_16x16x32_bf16 v[94:97], v[168:171], v[208:211], v[94:97]
	v_mfma_f32_16x16x32_bf16 v[58:61], v[168:171], v[212:215], v[58:61]
	v_mfma_f32_16x16x32_bf16 v[26:29], v[168:171], v[216:219], v[26:29]
	ds_read_b128 v[168:171], v167 offset:45056
	ds_read_b128 v[188:191], v167 offset:47104
	s_waitcnt lgkmcnt(4)
; template <bool SWAP, class Epi, bool THIN = false> ...
;     ...
;     for (int st = 0; st < ns; ++st) {
;       asm volatile("s_waitcnt vmcnt(0)" ::: "memory");
;       __builtin_amdgcn_s_barrier();
;       asm volatile("" ::: "memory");
;       if (st + 1 < ns) {
;         char* nb = smem + ((st + 1) & 1) * 65536;
;         const int ko = (st + 1) * 64;
; #pragma unroll
;         for (int i = 0; i < 4; ++i) { GLDS16(A + (size_t)(ap[i] + ko), nb + tid * 16 + i * 8192); GLDS16(Bt + (size_t)(bp[i] + ko), nb + 32768 + tid * 16 + i * 8192); }
;       }
;       const char* sa = smem + (st & 1) * 65536 + (wr * 64 + fr) * 128;
;       const char* sb = smem + (st & 1) * 65536 + 32768 + (wc * 128 + fr) * 128;
;       if constexpr (THIN) {
;         if (wc == 0) {
; #pragma unroll
;           for (int ks = 0; ks < 2; ++ks) {
;             bf16x8 af[4], bf[2];
; #pragma unroll
;             for (int m = 0; m < 4; ++m) af[m] = *(const bf16x8*)(sa + m * 2048 + (((ks * 4 + fq) ^ swz) << 4));
; #pragma unroll
;             for (int n = 0; n < 2; ++n) bf[n] = *(const bf16x8*)(sb + n * 2048 + (((ks * 4 + fq) ^ swz) << 4));
; #pragma unroll
;             for (int m = 0; m < 4; ++m)
; #pragma unroll
;               for (int n = 0; n < 2; ++n)
;                 acc[m][n] = SWAP ? __builtin_amdgcn_mfma_f32_16x16x32_bf16(bf[n], af[m], acc[m][n], 0, 0, 0)
;                                  : __builtin_amdgcn_mfma_f32_16x16x32_bf16(af[m], bf[n], acc[m][n], 0, 0, 0);
;           }
;         }
;       } else {
;       bf16x8 afA[4], afB[4], bfb[2][2];
; #pragma unroll
;       for (int m = 0; m < 4; ++m) afA[m] = *(const bf16x8*)(sa + m * 2048 + ((fq ^ swz) << 4));
; #pragma unroll
;       for (int n = 0; n < 2; ++n) bfb[0][n] = *(const bf16x8*)(sb + n * 2048 + ((fq ^ swz) << 4));
; #pragma unroll
;       for (int gq = 0; gq < 8; ++gq) {
;         const int ks = gq >> 2, nh = gq & 3;
;         if (gq < 7) {
;           const int ks2 = (gq + 1) >> 2, nh2 = (gq + 1) & 3;
; #pragma unroll
;           for (int n = 0; n < 2; ++n) bfb[(gq + 1) & 1][n] = *(const bf16x8*)(sb + (nh2 * 2 + n) * 2048 + (((ks2 * 4 + fq) ^ swz) << 4));
;         }
;         if (gq == 3) {
; #pragma unroll
;           for (int m = 0; m < 4; ++m) afB[m] = *(const bf16x8*)(sa + m * 2048 + (((4 + fq) ^ swz) << 4));
;         }
;         __builtin_amdgcn_sched_barrier(0);
; #pragma unroll
	v_mfma_f32_16x16x32_bf16 v[114:117], v[172:175], v[184:187], v[114:117]
	v_mfma_f32_16x16x32_bf16 v[86:89], v[172:175], v[208:211], v[86:89]
	v_mfma_f32_16x16x32_bf16 v[54:57], v[172:175], v[212:215], v[54:57]
	v_mfma_f32_16x16x32_bf16 v[22:25], v[172:175], v[216:219], v[22:25]
	s_waitcnt lgkmcnt(3)
	v_mfma_f32_16x16x32_bf16 v[102:105], v[176:179], v[184:187], v[102:105]
	s_waitcnt lgkmcnt(2)
	v_mfma_f32_16x16x32_bf16 v[98:101], v[180:183], v[184:187], v[98:101]
	v_mfma_f32_16x16x32_bf16 v[74:77], v[176:179], v[208:211], v[74:77]
	v_mfma_f32_16x16x32_bf16 v[66:69], v[180:183], v[208:211], v[66:69]
	v_mfma_f32_16x16x32_bf16 v[46:49], v[176:179], v[212:215], v[46:49]
	v_mfma_f32_16x16x32_bf16 v[30:33], v[180:183], v[212:215], v[30:33]
	v_mfma_f32_16x16x32_bf16 v[10:13], v[176:179], v[216:219], v[10:13]
	v_mfma_f32_16x16x32_bf16 v[6:9], v[180:183], v[216:219], v[6:9]
	s_waitcnt lgkmcnt(1)
	v_mfma_f32_16x16x32_bf16 v[70:73], v[168:171], v[184:187], v[70:73]
	s_add_i32 s6, s6, 64
	s_cmpk_eq_i32 s6, 0x3c0
	s_mov_b32 s7, s8
	s_waitcnt lgkmcnt(0)
	v_mfma_f32_16x16x32_bf16 v[62:65], v[188:191], v[184:187], v[62:65]
	v_mfma_f32_16x16x32_bf16 v[38:41], v[168:171], v[208:211], v[38:41]
	v_mfma_f32_16x16x32_bf16 v[34:37], v[188:191], v[208:211], v[34:37]
	v_mfma_f32_16x16x32_bf16 v[18:21], v[168:171], v[212:215], v[18:21]
	v_mfma_f32_16x16x32_bf16 v[14:17], v[188:191], v[212:215], v[14:17]
	v_mfma_f32_16x16x32_bf16 v[2:5], v[168:171], v[216:219], v[2:5]
	v_mfma_f32_16x16x32_bf16 v[90:93], v[188:191], v[216:219], v[90:93]
	s_cbranch_scc0 .LBB0_2643
	s_waitcnt vmcnt(0)
	s_barrier
	v_add_u32_e32 v130, v157, v145
	ds_read_b128 v[132:135], v130
	ds_read_b128 v[136:139], v130 offset:2048
	ds_read_b128 v[168:171], v130 offset:4096
	ds_read_b128 v[172:175], v130 offset:6144
	v_add_u32_e32 v130, v158, v145
	ds_read_b128 v[176:179], v130
	ds_read_b128 v[180:183], v130 offset:2048
	ds_read_b128 v[184:187], v130 offset:4096
	ds_read_b128 v[188:191], v130 offset:6144
	s_waitcnt lgkmcnt(0)
	v_mfma_f32_16x16x32_bf16 v[126:129], v[176:179], v[132:135], v[126:129]
	v_mfma_f32_16x16x32_bf16 v[110:113], v[176:179], v[136:139], v[110:113]
	v_mfma_f32_16x16x32_bf16 v[82:85], v[176:179], v[168:171], v[82:85]
	v_mfma_f32_16x16x32_bf16 v[50:53], v[176:179], v[172:175], v[50:53]
	ds_read_b128 v[176:179], v130 offset:8192
	ds_read_b128 v[192:195], v130 offset:10240
	v_mfma_f32_16x16x32_bf16 v[122:125], v[180:183], v[132:135], v[122:125]
	v_mfma_f32_16x16x32_bf16 v[106:109], v[180:183], v[136:139], v[106:109]
	v_mfma_f32_16x16x32_bf16 v[78:81], v[180:183], v[168:171], v[78:81]
	v_mfma_f32_16x16x32_bf16 v[42:45], v[180:183], v[172:175], v[42:45]
	v_mfma_f32_16x16x32_bf16 v[118:121], v[184:187], v[132:135], v[118:121]
	v_mfma_f32_16x16x32_bf16 v[180:183], v[184:187], v[136:139], v[94:97]
	v_mfma_f32_16x16x32_bf16 v[200:203], v[184:187], v[168:171], v[58:61]
	v_mfma_f32_16x16x32_bf16 v[204:207], v[188:191], v[168:171], v[54:57]
	v_mfma_f32_16x16x32_bf16 v[184:187], v[184:187], v[172:175], v[26:29]
	s_nop 2
	ds_read_b128 v[26:29], v130 offset:12288
	ds_read_b128 v[54:57], v130 offset:14336
	v_mfma_f32_16x16x32_bf16 v[114:117], v[188:191], v[132:135], v[114:117]
	v_mfma_f32_16x16x32_bf16 v[196:199], v[188:191], v[136:139], v[86:89]
	v_mfma_f32_16x16x32_bf16 v[188:191], v[188:191], v[172:175], v[22:25]
	v_add_u32_e32 v130, v158, v146
	s_waitcnt lgkmcnt(0)
	v_mfma_f32_16x16x32_bf16 v[208:211], v[192:195], v[168:171], v[30:33]
	ds_read_b128 v[22:25], v130
	ds_read_b128 v[86:89], v130 offset:2048
	s_nop 0
	v_add_u32_e32 v30, v157, v146
	v_mfma_f32_16x16x32_bf16 v[102:105], v[176:179], v[132:135], v[102:105]
	v_mfma_f32_16x16x32_bf16 v[74:77], v[176:179], v[136:139], v[74:77]
	v_mfma_f32_16x16x32_bf16 v[46:49], v[176:179], v[168:171], v[46:49]
	v_mfma_f32_16x16x32_bf16 v[10:13], v[176:179], v[172:175], v[10:13]
	ds_read_b128 v[176:179], v30
	ds_read_b128 v[212:215], v30 offset:2048
	ds_read_b128 v[216:219], v30 offset:4096
	ds_read_b128 v[220:223], v30 offset:6144
	v_mfma_f32_16x16x32_bf16 v[98:101], v[192:195], v[132:135], v[98:101]
	v_mfma_f32_16x16x32_bf16 v[66:69], v[192:195], v[136:139], v[66:69]
	v_mfma_f32_16x16x32_bf16 v[6:9], v[192:195], v[172:175], v[6:9]
	v_mfma_f32_16x16x32_bf16 v[224:227], v[26:29], v[136:139], v[38:41]
	v_mfma_f32_16x16x32_bf16 v[34:37], v[54:57], v[136:139], v[34:37]
	v_mfma_f32_16x16x32_bf16 v[136:139], v[26:29], v[168:171], v[18:21]
	v_mfma_f32_16x16x32_bf16 v[168:171], v[54:57], v[168:171], v[14:17]
	s_nop 2
	ds_read_b128 v[14:17], v130 offset:4096
	ds_read_b128 v[18:21], v130 offset:6144
	v_mfma_f32_16x16x32_bf16 v[192:195], v[26:29], v[132:135], v[70:73]
	v_mfma_f32_16x16x32_bf16 v[132:135], v[54:57], v[132:135], v[62:65]
	v_mfma_f32_16x16x32_bf16 v[2:5], v[26:29], v[172:175], v[2:5]
	v_mfma_f32_16x16x32_bf16 v[172:175], v[54:57], v[172:175], v[90:93]
	ds_read_b128 v[228:231], v130 offset:8192
	ds_read_b128 v[232:235], v130 offset:10240
	s_waitcnt lgkmcnt(0)
	v_mfma_f32_16x16x32_bf16 v[126:129], v[22:25], v[176:179], v[126:129]
	v_mfma_f32_16x16x32_bf16 v[122:125], v[86:89], v[176:179], v[122:125]
	v_mfma_f32_16x16x32_bf16 v[94:97], v[22:25], v[212:215], v[110:113]
	v_mfma_f32_16x16x32_bf16 v[90:93], v[86:89], v[212:215], v[106:109]
	v_mfma_f32_16x16x32_bf16 v[62:65], v[22:25], v[216:219], v[82:85]
	v_mfma_f32_16x16x32_bf16 v[58:61], v[86:89], v[216:219], v[78:81]
	v_mfma_f32_16x16x32_bf16 v[30:33], v[22:25], v[220:223], v[50:53]
	v_mfma_f32_16x16x32_bf16 v[26:29], v[86:89], v[220:223], v[42:45]
	v_mfma_f32_16x16x32_bf16 v[86:89], v[14:17], v[212:215], v[180:183]
	v_mfma_f32_16x16x32_bf16 v[22:25], v[14:17], v[220:223], v[184:187]
	s_nop 1
	ds_read_b128 v[180:183], v130 offset:12288
	ds_read_b128 v[184:187], v130 offset:14336
	v_mfma_f32_16x16x32_bf16 v[118:121], v[14:17], v[176:179], v[118:121]
	v_mfma_f32_16x16x32_bf16 v[114:117], v[18:21], v[176:179], v[114:117]
	v_mfma_f32_16x16x32_bf16 v[82:85], v[18:21], v[212:215], v[196:199]
	v_mfma_f32_16x16x32_bf16 v[54:57], v[14:17], v[216:219], v[200:203]
	v_mfma_f32_16x16x32_bf16 v[50:53], v[18:21], v[216:219], v[204:207]
	v_mfma_f32_16x16x32_bf16 v[18:21], v[18:21], v[220:223], v[188:191]
	v_mfma_f32_16x16x32_bf16 v[110:113], v[228:231], v[176:179], v[102:105]
	v_mfma_f32_16x16x32_bf16 v[106:109], v[232:235], v[176:179], v[98:101]
	v_mfma_f32_16x16x32_bf16 v[78:81], v[228:231], v[212:215], v[74:77]
	v_mfma_f32_16x16x32_bf16 v[70:73], v[232:235], v[212:215], v[66:69]
	v_mfma_f32_16x16x32_bf16 v[46:49], v[228:231], v[216:219], v[46:49]
	v_mfma_f32_16x16x32_bf16 v[38:41], v[232:235], v[216:219], v[208:211]
	v_mfma_f32_16x16x32_bf16 v[14:17], v[228:231], v[220:223], v[10:13]
	v_mfma_f32_16x16x32_bf16 v[6:9], v[232:235], v[220:223], v[6:9]
	v_mov_b32_e32 v130, v1
	s_waitcnt vmcnt(0) lgkmcnt(0)
	s_barrier
; __device__ __forceinline__ unsigned pack2(float a, float b) { unsigned r; asm("v_cvt_pk_bf16_f32 %0, %1, %2" : "=v"(r) : "v"(a), "v"(b)); return r; }
;   __device__ __forceinline__ void c4(int g, int rig, int col, f32x4 v) const {
;     const size_t row = (size_t)g * 2048 + rig;
;     const f32x4 b4 = *(const f32x4*)(bias + col);
;     uint2 u; u.x = pack2(v[0] + b4[0], v[1] + b4[1]); u.y = pack2(v[2] + b4[2], v[3] + b4[3]);
;     *(uint2*)(out + row * ld + col) = u;
;   }
; template <bool SWAP, class Epi, bool THIN = false> ...
;     ...
;         } else {
; #pragma unroll
;           for (int n = 0; n < 8; ++n) {
;             const int col = nt * 256 + wc_e * 128 + n * 16 + fq_e * 4;
;             if (col < N) epi.c4(g, rig, col, acc[m][n]);
;           }
;         }
	v_mfma_f32_16x16x32_bf16 v[102:105], v[180:183], v[176:179], v[192:195]
	v_ashrrev_i32_e32 v11, 8, v130
	v_add_u32_e32 v11, s5, v11
	v_ashrrev_i32_e32 v12, 31, v11
	v_lshrrev_b32_e32 v12, 28, v12
	v_add_u32_e32 v12, v11, v12
	v_mfma_f32_16x16x32_bf16 v[98:101], v[184:187], v[176:179], v[132:135]
	v_ashrrev_i32_e32 v176, 4, v12
	v_lshlrev_b32_e32 v12, 11, v176
	v_lshlrev_b32_e32 v11, 7, v11
	v_sub_u32_e32 v11, v11, v12
	v_lshrrev_b32_e32 v12, 1, v130
	v_and_b32_e32 v10, 15, v130
	v_bfe_u32 v246, v130, 4, 1
	v_mul_u32_u24_e32 v246, 24, v246
	v_mov_b32_e32 v247, 0
	v_and_b32_e32 v12, 64, v12
	v_or3_b32 v134, v11, v12, v10
	v_lshlrev_b32_e32 v10, 1, v130
	v_and_b32_e32 v132, 0x80, v10
	v_mfma_f32_16x16x32_bf16 v[10:13], v[180:183], v[220:223], v[2:5]
	v_ashrrev_i32_e32 v177, 31, v176
	v_ashrrev_i32_e32 v135, 31, v134
	s_nop 0
	v_lshrrev_b32_e32 v2, 2, v130
	v_and_b32_e32 v2, 12, v2
	v_mfma_f32_16x16x32_bf16 v[74:77], v[180:183], v[212:215], v[224:227]
	v_or3_b32 v132, v2, v132, s4
	v_cmp_gt_i32_e32 vcc, s31, v132
	v_ashrrev_i32_e32 v133, 31, v132
	v_mfma_f32_16x16x32_bf16 v[66:69], v[184:187], v[212:215], v[34:37]
	v_mfma_f32_16x16x32_bf16 v[42:45], v[180:183], v[216:219], v[136:139]
	v_mfma_f32_16x16x32_bf16 v[34:37], v[184:187], v[216:219], v[168:171]
	s_nop 1
	v_lshlrev_b64 v[136:137], 11, v[176:177]
	v_lshl_add_u64 v[138:139], v[136:137], 0, v[134:135]
	v_lshlrev_b64 v[138:139], 11, v[138:139]
	v_mfma_f32_16x16x32_bf16 v[2:5], v[184:187], v[220:223], v[172:175]
	v_lshl_add_u64 v[138:139], s[20:21], 0, v[138:139]
	v_lshl_add_u64 v[188:189], v[132:133], 2, s[22:23]
	global_load_dwordx4 v[196:199], v[188:189], off
	global_load_dwordx4 v[200:203], v[188:189], off offset:64
	global_load_dwordx4 v[204:207], v[188:189], off offset:128
	global_load_dwordx4 v[208:211], v[188:189], off offset:192
	global_load_dwordx4 v[228:231], v[188:189], off offset:256
	global_load_dwordx4 v[232:235], v[188:189], off offset:320
	global_load_dwordx4 v[236:239], v[188:189], off offset:384
	global_load_dwordx4 v[240:243], v[188:189], off offset:448
	s_waitcnt vmcnt(0)
	v_add_f32_e32 v126, v126, v196
	v_add_f32_e32 v127, v127, v197
	v_add_f32_e32 v128, v128, v198
	v_add_f32_e32 v129, v129, v199
	v_cvt_pk_bf16_f32 v126, v126, v127
	v_cvt_pk_bf16_f32 v127, v128, v129
	v_add_f32_e32 v122, v122, v200
	v_add_f32_e32 v123, v123, v201
	v_add_f32_e32 v124, v124, v202
	v_add_f32_e32 v125, v125, v203
	v_cvt_pk_bf16_f32 v128, v122, v123
	v_cvt_pk_bf16_f32 v129, v124, v125
	v_lshl_add_u64 v[124:125], v[132:133], 1, v[138:139]
	s_nop 1
	v_permlane16_swap_b32 v126, v128
	v_permlane16_swap_b32 v127, v129
	v_lshl_add_u64 v[248:249], v[124:125], 0, v[246:247]
	s_nop 0
	global_store_dwordx4 v[248:249], v[126:129], off
	s_nop 1
	v_or_b32_e32 v122, 32, v132
	v_add_f32_e32 v118, v118, v204
	v_add_f32_e32 v119, v119, v205
	v_add_f32_e32 v120, v120, v206
	v_add_f32_e32 v121, v121, v207
	v_cvt_pk_bf16_f32 v118, v118, v119
	v_cvt_pk_bf16_f32 v119, v120, v121
	v_add_f32_e32 v114, v114, v208
	v_add_f32_e32 v115, v115, v209
	v_add_f32_e32 v116, v116, v210
	v_add_f32_e32 v117, v117, v211
	v_cvt_pk_bf16_f32 v120, v114, v115
	v_cvt_pk_bf16_f32 v121, v116, v117
	v_lshl_add_u64 v[116:117], v[132:133], 1, v[138:139]
	s_nop 1
	v_permlane16_swap_b32 v118, v120
	v_permlane16_swap_b32 v119, v121
	v_lshl_add_u64 v[248:249], v[116:117], 0, v[246:247]
	s_nop 0
	global_store_dwordx4 v[248:249], v[118:121], off offset:64
	s_nop 1
	v_or_b32_e32 v114, 64, v132
	v_add_f32_e32 v110, v110, v228
	v_add_f32_e32 v111, v111, v229
	v_add_f32_e32 v112, v112, v230
	v_add_f32_e32 v113, v113, v231
	v_cvt_pk_bf16_f32 v110, v110, v111
	v_cvt_pk_bf16_f32 v111, v112, v113
	v_add_f32_e32 v106, v106, v232
	v_add_f32_e32 v107, v107, v233
	v_add_f32_e32 v108, v108, v234
	v_add_f32_e32 v109, v109, v235
	v_cvt_pk_bf16_f32 v112, v106, v107
	v_cvt_pk_bf16_f32 v113, v108, v109
	v_lshl_add_u64 v[108:109], v[132:133], 1, v[138:139]
	s_nop 1
	v_permlane16_swap_b32 v110, v112
	v_permlane16_swap_b32 v111, v113
	v_lshl_add_u64 v[248:249], v[108:109], 0, v[246:247]
	s_nop 0
	global_store_dwordx4 v[248:249], v[110:113], off offset:128
	s_nop 1
	v_or_b32_e32 v106, 0x60, v132
	v_add_f32_e32 v102, v102, v236
	v_add_f32_e32 v103, v103, v237
	v_add_f32_e32 v104, v104, v238
	v_add_f32_e32 v105, v105, v239
	v_cvt_pk_bf16_f32 v102, v102, v103
	v_cvt_pk_bf16_f32 v103, v104, v105
	v_add_f32_e32 v98, v98, v240
	v_add_f32_e32 v99, v99, v241
	v_add_f32_e32 v100, v100, v242
	v_add_f32_e32 v101, v101, v243
	v_cvt_pk_bf16_f32 v104, v98, v99
	v_cvt_pk_bf16_f32 v105, v100, v101
	v_lshl_add_u64 v[100:101], v[132:133], 1, v[138:139]
	s_nop 1
	v_permlane16_swap_b32 v102, v104
	v_permlane16_swap_b32 v103, v105
	v_lshl_add_u64 v[248:249], v[100:101], 0, v[246:247]
	s_nop 0
	global_store_dwordx4 v[248:249], v[102:105], off offset:192
	s_nop 1
	v_or_b32_e32 v98, 16, v134
	v_ashrrev_i32_e32 v99, 31, v98
	v_lshl_add_u64 v[98:99], v[136:137], 0, v[98:99]
	v_lshlrev_b64 v[98:99], 11, v[98:99]
	v_lshl_add_u64 v[98:99], s[20:21], 0, v[98:99]
	v_add_f32_e32 v94, v94, v196
	v_add_f32_e32 v95, v95, v197
	v_add_f32_e32 v96, v96, v198
	v_add_f32_e32 v97, v97, v199
	v_cvt_pk_bf16_f32 v94, v94, v95
	v_cvt_pk_bf16_f32 v95, v96, v97
	v_add_f32_e32 v90, v90, v200
	v_add_f32_e32 v91, v91, v201
	v_add_f32_e32 v92, v92, v202
	v_add_f32_e32 v93, v93, v203
	v_cvt_pk_bf16_f32 v96, v90, v91
	v_cvt_pk_bf16_f32 v97, v92, v93
	v_lshl_add_u64 v[92:93], v[132:133], 1, v[98:99]
	s_nop 1
	v_permlane16_swap_b32 v94, v96
	v_permlane16_swap_b32 v95, v97
	v_lshl_add_u64 v[248:249], v[92:93], 0, v[246:247]
	s_nop 0
	global_store_dwordx4 v[248:249], v[94:97], off
	s_nop 1
	v_add_f32_e32 v86, v86, v204
; __device__ __forceinline__ unsigned pack2(float a, float b) { unsigned r; asm("v_cvt_pk_bf16_f32 %0, %1, %2" : "=v"(r) : "v"(a), "v"(b)); return r; }
;   __device__ __forceinline__ void c4(int g, int rig, int col, f32x4 v) const {
;     const size_t row = (size_t)g * 2048 + rig;
;     const f32x4 b4 = *(const f32x4*)(bias + col);
;     uint2 u; u.x = pack2(v[0] + b4[0], v[1] + b4[1]); u.y = pack2(v[2] + b4[2], v[3] + b4[3]);
;     *(uint2*)(out + row * ld + col) = u;
;   }
; template <bool SWAP, class Epi, bool THIN = false> ...
;     ...
;         } else {
; #pragma unroll
;           for (int n = 0; n < 8; ++n) {
;             const int col = nt * 256 + wc_e * 128 + n * 16 + fq_e * 4;
;             if (col < N) epi.c4(g, rig, col, acc[m][n]);
;           }
;         }
	v_add_f32_e32 v87, v87, v205
	v_add_f32_e32 v88, v88, v206
	v_add_f32_e32 v89, v89, v207
	v_cvt_pk_bf16_f32 v86, v86, v87
	v_cvt_pk_bf16_f32 v87, v88, v89
	v_add_f32_e32 v82, v82, v208
	v_add_f32_e32 v83, v83, v209
	v_add_f32_e32 v84, v84, v210
	v_add_f32_e32 v85, v85, v211
	v_cvt_pk_bf16_f32 v88, v82, v83
	v_cvt_pk_bf16_f32 v89, v84, v85
	v_lshl_add_u64 v[84:85], v[132:133], 1, v[98:99]
	s_nop 1
	v_permlane16_swap_b32 v86, v88
	v_permlane16_swap_b32 v87, v89
	v_lshl_add_u64 v[248:249], v[84:85], 0, v[246:247]
	s_nop 0
	global_store_dwordx4 v[248:249], v[86:89], off offset:64
	s_nop 1
	v_add_f32_e32 v78, v78, v228
	v_add_f32_e32 v79, v79, v229
	v_add_f32_e32 v80, v80, v230
	v_add_f32_e32 v81, v81, v231
	v_cvt_pk_bf16_f32 v78, v78, v79
	v_cvt_pk_bf16_f32 v79, v80, v81
	v_add_f32_e32 v70, v70, v232
	v_add_f32_e32 v71, v71, v233
	v_add_f32_e32 v72, v72, v234
	v_add_f32_e32 v73, v73, v235
	v_cvt_pk_bf16_f32 v80, v70, v71
	v_cvt_pk_bf16_f32 v81, v72, v73
	v_lshl_add_u64 v[72:73], v[132:133], 1, v[98:99]
	s_nop 1
	v_permlane16_swap_b32 v78, v80
	v_permlane16_swap_b32 v79, v81
	v_lshl_add_u64 v[248:249], v[72:73], 0, v[246:247]
	s_nop 0
	global_store_dwordx4 v[248:249], v[78:81], off offset:128
	s_nop 1
	v_add_f32_e32 v70, v74, v236
	v_add_f32_e32 v71, v75, v237
	v_add_f32_e32 v72, v76, v238
	v_add_f32_e32 v73, v77, v239
	v_cvt_pk_bf16_f32 v70, v70, v71
	v_cvt_pk_bf16_f32 v71, v72, v73
	v_add_f32_e32 v66, v66, v240
	v_add_f32_e32 v67, v67, v241
	v_add_f32_e32 v68, v68, v242
	v_add_f32_e32 v69, v69, v243
	v_cvt_pk_bf16_f32 v72, v66, v67
	v_cvt_pk_bf16_f32 v73, v68, v69
	v_lshl_add_u64 v[68:69], v[132:133], 1, v[98:99]
	s_nop 1
	v_permlane16_swap_b32 v70, v72
	v_permlane16_swap_b32 v71, v73
	v_lshl_add_u64 v[248:249], v[68:69], 0, v[246:247]
	s_nop 0
	global_store_dwordx4 v[248:249], v[70:73], off offset:192
	s_nop 1
	v_or_b32_e32 v66, 32, v134
	v_ashrrev_i32_e32 v67, 31, v66
	v_lshl_add_u64 v[66:67], v[136:137], 0, v[66:67]
	v_lshlrev_b64 v[66:67], 11, v[66:67]
	v_lshl_add_u64 v[66:67], s[20:21], 0, v[66:67]
	v_add_f32_e32 v62, v62, v196
	v_add_f32_e32 v63, v63, v197
	v_add_f32_e32 v64, v64, v198
	v_add_f32_e32 v65, v65, v199
	v_cvt_pk_bf16_f32 v62, v62, v63
	v_cvt_pk_bf16_f32 v63, v64, v65
	v_add_f32_e32 v58, v58, v200
	v_add_f32_e32 v59, v59, v201
	v_add_f32_e32 v60, v60, v202
	v_add_f32_e32 v61, v61, v203
	v_cvt_pk_bf16_f32 v64, v58, v59
	v_cvt_pk_bf16_f32 v65, v60, v61
	v_lshl_add_u64 v[60:61], v[132:133], 1, v[66:67]
	s_nop 1
	v_permlane16_swap_b32 v62, v64
	v_permlane16_swap_b32 v63, v65
	v_lshl_add_u64 v[248:249], v[60:61], 0, v[246:247]
	s_nop 0
	global_store_dwordx4 v[248:249], v[62:65], off
	s_nop 1
	v_add_f32_e32 v54, v54, v204
	v_add_f32_e32 v55, v55, v205
	v_add_f32_e32 v56, v56, v206
	v_add_f32_e32 v57, v57, v207
	v_cvt_pk_bf16_f32 v54, v54, v55
	v_cvt_pk_bf16_f32 v55, v56, v57
	v_add_f32_e32 v50, v50, v208
	v_add_f32_e32 v51, v51, v209
	v_add_f32_e32 v52, v52, v210
	v_add_f32_e32 v53, v53, v211
	v_cvt_pk_bf16_f32 v56, v50, v51
	v_cvt_pk_bf16_f32 v57, v52, v53
	v_lshl_add_u64 v[52:53], v[132:133], 1, v[66:67]
	s_nop 1
	v_permlane16_swap_b32 v54, v56
	v_permlane16_swap_b32 v55, v57
	v_lshl_add_u64 v[248:249], v[52:53], 0, v[246:247]
	s_nop 0
	global_store_dwordx4 v[248:249], v[54:57], off offset:64
	s_nop 1
	v_add_f32_e32 v46, v46, v228
	v_add_f32_e32 v47, v47, v229
	v_add_f32_e32 v48, v48, v230
	v_add_f32_e32 v49, v49, v231
	v_cvt_pk_bf16_f32 v46, v46, v47
	v_cvt_pk_bf16_f32 v47, v48, v49
	v_add_f32_e32 v38, v38, v232
	v_add_f32_e32 v39, v39, v233
	v_add_f32_e32 v40, v40, v234
	v_add_f32_e32 v41, v41, v235
; __device__ __forceinline__ unsigned pack2(float a, float b) { unsigned r; asm("v_cvt_pk_bf16_f32 %0, %1, %2" : "=v"(r) : "v"(a), "v"(b)); return r; }
;   __device__ __forceinline__ void c4(int g, int rig, int col, f32x4 v) const {
;     const size_t row = (size_t)g * 2048 + rig;
;     const f32x4 b4 = *(const f32x4*)(bias + col);
;     uint2 u; u.x = pack2(v[0] + b4[0], v[1] + b4[1]); u.y = pack2(v[2] + b4[2], v[3] + b4[3]);
;     *(uint2*)(out + row * ld + col) = u;
;   }
; template <bool SWAP, class Epi, bool THIN = false> ...
;     ...
;         } else {
; #pragma unroll
;           for (int n = 0; n < 8; ++n) {
;             const int col = nt * 256 + wc_e * 128 + n * 16 + fq_e * 4;
;             if (col < N) epi.c4(g, rig, col, acc[m][n]);
;           }
;         }
	v_cvt_pk_bf16_f32 v48, v38, v39
	v_cvt_pk_bf16_f32 v49, v40, v41
	v_lshl_add_u64 v[40:41], v[132:133], 1, v[66:67]
	s_nop 1
	v_permlane16_swap_b32 v46, v48
	v_permlane16_swap_b32 v47, v49
	v_lshl_add_u64 v[248:249], v[40:41], 0, v[246:247]
	s_nop 0
	global_store_dwordx4 v[248:249], v[46:49], off offset:128
	s_nop 1
	v_add_f32_e32 v38, v42, v236
	v_add_f32_e32 v39, v43, v237
	v_add_f32_e32 v40, v44, v238
	v_add_f32_e32 v41, v45, v239
	v_cvt_pk_bf16_f32 v38, v38, v39
	v_cvt_pk_bf16_f32 v39, v40, v41
	v_add_f32_e32 v34, v34, v240
	v_add_f32_e32 v35, v35, v241
	v_add_f32_e32 v36, v36, v242
	v_add_f32_e32 v37, v37, v243
	v_cvt_pk_bf16_f32 v40, v34, v35
	v_cvt_pk_bf16_f32 v41, v36, v37
	v_lshl_add_u64 v[36:37], v[132:133], 1, v[66:67]
	s_nop 1
	v_permlane16_swap_b32 v38, v40
	v_permlane16_swap_b32 v39, v41
	v_lshl_add_u64 v[248:249], v[36:37], 0, v[246:247]
	s_nop 0
	global_store_dwordx4 v[248:249], v[38:41], off offset:192
	s_nop 1
	v_or_b32_e32 v34, 48, v134
	v_ashrrev_i32_e32 v35, 31, v34
	v_lshl_add_u64 v[34:35], v[136:137], 0, v[34:35]
	v_lshlrev_b64 v[34:35], 11, v[34:35]
	v_lshl_add_u64 v[34:35], s[20:21], 0, v[34:35]
	v_add_f32_e32 v30, v30, v196
	v_add_f32_e32 v31, v31, v197
	v_add_f32_e32 v32, v32, v198
	v_add_f32_e32 v33, v33, v199
	v_cvt_pk_bf16_f32 v30, v30, v31
	v_cvt_pk_bf16_f32 v31, v32, v33
	v_add_f32_e32 v26, v26, v200
	v_add_f32_e32 v27, v27, v201
	v_add_f32_e32 v28, v28, v202
	v_add_f32_e32 v29, v29, v203
	v_cvt_pk_bf16_f32 v32, v26, v27
	v_cvt_pk_bf16_f32 v33, v28, v29
	v_lshl_add_u64 v[28:29], v[132:133], 1, v[34:35]
	s_nop 1
	v_permlane16_swap_b32 v30, v32
	v_permlane16_swap_b32 v31, v33
	v_lshl_add_u64 v[248:249], v[28:29], 0, v[246:247]
	s_nop 0
	global_store_dwordx4 v[248:249], v[30:33], off
	s_nop 1
	v_add_f32_e32 v22, v22, v204
	v_add_f32_e32 v23, v23, v205
	v_add_f32_e32 v24, v24, v206
	v_add_f32_e32 v25, v25, v207
	v_cvt_pk_bf16_f32 v22, v22, v23
	v_cvt_pk_bf16_f32 v23, v24, v25
	v_add_f32_e32 v18, v18, v208
	v_add_f32_e32 v19, v19, v209
	v_add_f32_e32 v20, v20, v210
	v_add_f32_e32 v21, v21, v211
	v_cvt_pk_bf16_f32 v24, v18, v19
	v_cvt_pk_bf16_f32 v25, v20, v21
	v_lshl_add_u64 v[20:21], v[132:133], 1, v[34:35]
	s_nop 1
	v_permlane16_swap_b32 v22, v24
	v_permlane16_swap_b32 v23, v25
	v_lshl_add_u64 v[248:249], v[20:21], 0, v[246:247]
	s_nop 0
	global_store_dwordx4 v[248:249], v[22:25], off offset:64
	s_nop 1
	v_add_f32_e32 v14, v14, v228
	v_add_f32_e32 v15, v15, v229
	v_add_f32_e32 v16, v16, v230
	v_add_f32_e32 v17, v17, v231
	v_cvt_pk_bf16_f32 v14, v14, v15
	v_cvt_pk_bf16_f32 v15, v16, v17
	v_add_f32_e32 v6, v6, v232
	v_add_f32_e32 v7, v7, v233
	v_add_f32_e32 v8, v8, v234
	v_add_f32_e32 v9, v9, v235
	v_cvt_pk_bf16_f32 v16, v6, v7
	v_cvt_pk_bf16_f32 v17, v8, v9
	v_lshl_add_u64 v[8:9], v[132:133], 1, v[34:35]
	s_nop 1
	v_permlane16_swap_b32 v14, v16
	v_permlane16_swap_b32 v15, v17
	v_lshl_add_u64 v[248:249], v[8:9], 0, v[246:247]
	s_nop 0
	global_store_dwordx4 v[248:249], v[14:17], off offset:128
	s_nop 1
	v_add_f32_e32 v6, v10, v236
	v_add_f32_e32 v7, v11, v237
	v_add_f32_e32 v8, v12, v238
	v_add_f32_e32 v9, v13, v239
	v_cvt_pk_bf16_f32 v6, v6, v7
	v_cvt_pk_bf16_f32 v7, v8, v9
	v_add_f32_e32 v2, v2, v240
	v_add_f32_e32 v3, v3, v241
	v_add_f32_e32 v4, v4, v242
	v_add_f32_e32 v5, v5, v243
	v_cvt_pk_bf16_f32 v8, v2, v3
	v_cvt_pk_bf16_f32 v9, v4, v5
	v_lshl_add_u64 v[4:5], v[132:133], 1, v[34:35]
	s_nop 1
	v_permlane16_swap_b32 v6, v8
	v_permlane16_swap_b32 v7, v9
	v_lshl_add_u64 v[248:249], v[4:5], 0, v[246:247]
	s_nop 0
	global_store_dwordx4 v[248:249], v[6:9], off offset:192
	s_nop 1
	s_branch .LBB0_2641

; template <bool SWAP, class Epi, bool THIN = false> ...
;     ...
;     for (int st = 0; st < ns; ++st) {
;       asm volatile("s_waitcnt vmcnt(0)" ::: "memory");
;       __builtin_amdgcn_s_barrier();
;       asm volatile("" ::: "memory");
;       if (st + 1 < ns) {
;         char* nb = smem + ((st + 1) & 1) * 65536;
;         const int ko = (st + 1) * 64;
; #pragma unroll
;         for (int i = 0; i < 4; ++i) { GLDS16(A + (size_t)(ap[i] + ko), nb + tid * 16 + i * 8192); GLDS16(Bt + (size_t)(bp[i] + ko), nb + 32768 + tid * 16 + i * 8192); }
;       }
;       const char* sa = smem + (st & 1) * 65536 + (wr * 64 + fr) * 128;
;       const char* sb = smem + (st & 1) * 65536 + 32768 + (wc * 128 + fr) * 128;
;       if constexpr (THIN) {
;         if (wc == 0) {
; #pragma unroll
;           for (int ks = 0; ks < 2; ++ks) {
;             bf16x8 af[4], bf[2];
; #pragma unroll
;             for (int m = 0; m < 4; ++m) af[m] = *(const bf16x8*)(sa + m * 2048 + (((ks * 4 + fq) ^ swz) << 4));
; #pragma unroll
;             for (int n = 0; n < 2; ++n) bf[n] = *(const bf16x8*)(sb + n * 2048 + (((ks * 4 + fq) ^ swz) << 4));
; #pragma unroll
;             for (int m = 0; m < 4; ++m)
; #pragma unroll
;               for (int n = 0; n < 2; ++n)
;                 acc[m][n] = SWAP ? __builtin_amdgcn_mfma_f32_16x16x32_bf16(bf[n], af[m], acc[m][n], 0, 0, 0)
;                                  : __builtin_amdgcn_mfma_f32_16x16x32_bf16(af[m], bf[n], acc[m][n], 0, 0, 0);
;           }
;         }
;       } else {
;       bf16x8 afA[4], afB[4], bfb[2][2];
; #pragma unroll
;       for (int m = 0; m < 4; ++m) afA[m] = *(const bf16x8*)(sa + m * 2048 + ((fq ^ swz) << 4));
; #pragma unroll
;       for (int n = 0; n < 2; ++n) bfb[0][n] = *(const bf16x8*)(sb + n * 2048 + ((fq ^ swz) << 4));
; #pragma unroll
;       for (int gq = 0; gq < 8; ++gq) {
;         const int ks = gq >> 2, nh = gq & 3;
;         if (gq < 7) {
;           const int ks2 = (gq + 1) >> 2, nh2 = (gq + 1) & 3;
; #pragma unroll
;           for (int n = 0; n < 2; ++n) bfb[(gq + 1) & 1][n] = *(const bf16x8*)(sb + (nh2 * 2 + n) * 2048 + (((ks2 * 4 + fq) ^ swz) << 4));
;         }
;         if (gq == 3) {
; #pragma unroll
;           for (int m = 0; m < 4; ++m) afB[m] = *(const bf16x8*)(sa + m * 2048 + (((4 + fq) ^ swz) << 4));
;         }
;         __builtin_amdgcn_sched_barrier(0);
; #pragma unroll
.LBB0_3516:
	s_add_i32 s9, s7, 0x10000
	s_and_b32 s8, s9, 0x10000
	v_add_u32_e32 v139, s8, v144
	s_nop 0
	v_readfirstlane_b32 s10, v139
	s_waitcnt vmcnt(0)
	s_barrier
	s_and_b32 s7, s7, 0x10000
	v_add_u32_e32 v130, s7, v145
	v_add_u32_e32 v139, v130, v147
	ds_read_b128 v[168:171], v139
	ds_read_b128 v[172:175], v139 offset:2048
	ds_read_b128 v[176:179], v139 offset:4096
	ds_read_b128 v[180:183], v139 offset:6144
	v_or_b32_e32 v139, s7, v146
	v_add_u32_e32 v141, v139, v147
	ds_read_b128 v[184:187], v141 offset:32768
	ds_read_b128 v[188:191], v141 offset:34816
	ds_read_b128 v[192:195], v141 offset:36864
	ds_read_b128 v[196:199], v141 offset:38912
	v_add_u32_e32 v130, v130, v148
	s_waitcnt lgkmcnt(3)
	v_mfma_f32_16x16x32_bf16 v[126:129], v[184:187], v[168:171], v[126:129]
	s_mov_b32 m0, s10
	v_mfma_f32_16x16x32_bf16 v[110:113], v[184:187], v[172:175], v[110:113]
	global_load_lds_dwordx4 v138, s[24:25]
	v_add_u32_e32 v138, 0x80, v138
	v_mfma_f32_16x16x32_bf16 v[82:85], v[184:187], v[176:179], v[82:85]
	v_mfma_f32_16x16x32_bf16 v[50:53], v[184:187], v[180:183], v[50:53]
	ds_read_b128 v[184:187], v141 offset:40960
	ds_read_b128 v[200:203], v141 offset:43008
	s_waitcnt lgkmcnt(4)
	v_mfma_f32_16x16x32_bf16 v[122:125], v[188:191], v[168:171], v[122:125]
	s_add_u32 m0, s10, 0x8000
	v_mfma_f32_16x16x32_bf16 v[106:109], v[188:191], v[172:175], v[106:109]
	global_load_lds_dwordx4 v137, s[20:21]
	v_add_u32_e32 v137, 0x80, v137
	v_mfma_f32_16x16x32_bf16 v[78:81], v[188:191], v[176:179], v[78:81]
	v_mfma_f32_16x16x32_bf16 v[38:41], v[188:191], v[180:183], v[38:41]
	s_waitcnt lgkmcnt(3)
	v_mfma_f32_16x16x32_bf16 v[118:121], v[192:195], v[168:171], v[118:121]
	s_add_u32 m0, s10, 0x2000
	v_mfma_f32_16x16x32_bf16 v[94:97], v[192:195], v[172:175], v[94:97]
	global_load_lds_dwordx4 v136, s[24:25]
	v_add_u32_e32 v136, 0x80, v136
	v_mfma_f32_16x16x32_bf16 v[58:61], v[192:195], v[176:179], v[58:61]
	v_mfma_f32_16x16x32_bf16 v[26:29], v[192:195], v[180:183], v[26:29]
	ds_read_b128 v[188:191], v141 offset:45056
	ds_read_b128 v[192:195], v141 offset:47104
	s_waitcnt lgkmcnt(4)
	v_mfma_f32_16x16x32_bf16 v[114:117], v[196:199], v[168:171], v[114:117]
	s_add_u32 m0, s10, 0xa000
	v_mfma_f32_16x16x32_bf16 v[86:89], v[196:199], v[172:175], v[86:89]
	global_load_lds_dwordx4 v135, s[20:21]
	v_add_u32_e32 v135, 0x80, v135
	v_mfma_f32_16x16x32_bf16 v[54:57], v[196:199], v[176:179], v[54:57]
	v_mfma_f32_16x16x32_bf16 v[22:25], v[196:199], v[180:183], v[22:25]
	v_add_u32_e32 v139, v139, v148
	s_waitcnt lgkmcnt(3)
	v_mfma_f32_16x16x32_bf16 v[102:105], v[184:187], v[168:171], v[102:105]
	ds_read_b128 v[196:199], v139 offset:32768
	ds_read_b128 v[204:207], v139 offset:34816
	s_add_u32 m0, s10, 0x4000
	v_mfma_f32_16x16x32_bf16 v[74:77], v[184:187], v[172:175], v[74:77]
	global_load_lds_dwordx4 v134, s[24:25]
	v_add_u32_e32 v134, 0x80, v134
	v_mfma_f32_16x16x32_bf16 v[46:49], v[184:187], v[176:179], v[46:49]
	v_mfma_f32_16x16x32_bf16 v[10:13], v[184:187], v[180:183], v[10:13]
	ds_read_b128 v[184:187], v130
	ds_read_b128 v[208:211], v130 offset:2048
	ds_read_b128 v[212:215], v130 offset:4096
	ds_read_b128 v[216:219], v130 offset:6144
	s_waitcnt lgkmcnt(8)
	v_mfma_f32_16x16x32_bf16 v[98:101], v[200:203], v[168:171], v[98:101]
	s_add_u32 m0, s10, 0xc000
	v_mfma_f32_16x16x32_bf16 v[66:69], v[200:203], v[172:175], v[66:69]
	global_load_lds_dwordx4 v133, s[20:21]
	v_add_u32_e32 v133, 0x80, v133
	v_mfma_f32_16x16x32_bf16 v[34:37], v[200:203], v[176:179], v[34:37]
	v_mfma_f32_16x16x32_bf16 v[6:9], v[200:203], v[180:183], v[6:9]
	s_waitcnt lgkmcnt(7)
	v_mfma_f32_16x16x32_bf16 v[70:73], v[188:191], v[168:171], v[70:73]
	s_add_u32 m0, s10, 0x6000
	s_waitcnt lgkmcnt(6)
	v_mfma_f32_16x16x32_bf16 v[62:65], v[192:195], v[168:171], v[62:65]
	global_load_lds_dwordx4 v132, s[24:25]
	v_add_u32_e32 v132, 0x80, v132
	v_mfma_f32_16x16x32_bf16 v[42:45], v[188:191], v[172:175], v[42:45]
	v_mfma_f32_16x16x32_bf16 v[30:33], v[192:195], v[172:175], v[30:33]
	ds_read_b128 v[168:171], v139 offset:36864
	ds_read_b128 v[172:175], v139 offset:38912
	v_mfma_f32_16x16x32_bf16 v[18:21], v[188:191], v[176:179], v[18:21]
	s_add_u32 m0, s10, 0xe000
	v_mfma_f32_16x16x32_bf16 v[14:17], v[192:195], v[176:179], v[14:17]
	global_load_lds_dwordx4 v140, s[20:21]
	v_add_u32_e32 v140, 0x80, v140
	v_mfma_f32_16x16x32_bf16 v[2:5], v[188:191], v[180:183], v[2:5]
	v_mfma_f32_16x16x32_bf16 v[90:93], v[192:195], v[180:183], v[90:93]
	ds_read_b128 v[176:179], v139 offset:40960
	ds_read_b128 v[180:183], v139 offset:43008
	s_waitcnt lgkmcnt(7)
	v_mfma_f32_16x16x32_bf16 v[126:129], v[196:199], v[184:187], v[126:129]
	v_mfma_f32_16x16x32_bf16 v[122:125], v[204:207], v[184:187], v[122:125]
	s_waitcnt lgkmcnt(6)
	v_mfma_f32_16x16x32_bf16 v[110:113], v[196:199], v[208:211], v[110:113]
	v_mfma_f32_16x16x32_bf16 v[106:109], v[204:207], v[208:211], v[106:109]
	s_waitcnt lgkmcnt(5)
	v_mfma_f32_16x16x32_bf16 v[82:85], v[196:199], v[212:215], v[82:85]
	v_mfma_f32_16x16x32_bf16 v[78:81], v[204:207], v[212:215], v[78:81]
	s_waitcnt lgkmcnt(4)
	v_mfma_f32_16x16x32_bf16 v[50:53], v[196:199], v[216:219], v[50:53]
	v_mfma_f32_16x16x32_bf16 v[38:41], v[204:207], v[216:219], v[38:41]
	s_waitcnt lgkmcnt(3)
	v_mfma_f32_16x16x32_bf16 v[118:121], v[168:171], v[184:187], v[118:121]
	v_mfma_f32_16x16x32_bf16 v[94:97], v[168:171], v[208:211], v[94:97]
	v_mfma_f32_16x16x32_bf16 v[58:61], v[168:171], v[212:215], v[58:61]
	v_mfma_f32_16x16x32_bf16 v[26:29], v[168:171], v[216:219], v[26:29]
	ds_read_b128 v[168:171], v139 offset:45056
	ds_read_b128 v[188:191], v139 offset:47104
	s_waitcnt lgkmcnt(4)
; template <bool SWAP, class Epi, bool THIN = false> ...
;     ...
;     for (int st = 0; st < ns; ++st) {
;       asm volatile("s_waitcnt vmcnt(0)" ::: "memory");
;       __builtin_amdgcn_s_barrier();
;       asm volatile("" ::: "memory");
;       if (st + 1 < ns) {
;         char* nb = smem + ((st + 1) & 1) * 65536;
;         const int ko = (st + 1) * 64;
; #pragma unroll
;         for (int i = 0; i < 4; ++i) { GLDS16(A + (size_t)(ap[i] + ko), nb + tid * 16 + i * 8192); GLDS16(Bt + (size_t)(bp[i] + ko), nb + 32768 + tid * 16 + i * 8192); }
;       }
;       const char* sa = smem + (st & 1) * 65536 + (wr * 64 + fr) * 128;
;       const char* sb = smem + (st & 1) * 65536 + 32768 + (wc * 128 + fr) * 128;
;       if constexpr (THIN) {
;         if (wc == 0) {
; #pragma unroll
;           for (int ks = 0; ks < 2; ++ks) {
;             bf16x8 af[4], bf[2];
; #pragma unroll
;             for (int m = 0; m < 4; ++m) af[m] = *(const bf16x8*)(sa + m * 2048 + (((ks * 4 + fq) ^ swz) << 4));
; #pragma unroll
;             for (int n = 0; n < 2; ++n) bf[n] = *(const bf16x8*)(sb + n * 2048 + (((ks * 4 + fq) ^ swz) << 4));
; #pragma unroll
;             for (int m = 0; m < 4; ++m)
; #pragma unroll
;               for (int n = 0; n < 2; ++n)
;                 acc[m][n] = SWAP ? __builtin_amdgcn_mfma_f32_16x16x32_bf16(bf[n], af[m], acc[m][n], 0, 0, 0)
;                                  : __builtin_amdgcn_mfma_f32_16x16x32_bf16(af[m], bf[n], acc[m][n], 0, 0, 0);
;           }
;         }
;       } else {
;       bf16x8 afA[4], afB[4], bfb[2][2];
; #pragma unroll
;       for (int m = 0; m < 4; ++m) afA[m] = *(const bf16x8*)(sa + m * 2048 + ((fq ^ swz) << 4));
; #pragma unroll
;       for (int n = 0; n < 2; ++n) bfb[0][n] = *(const bf16x8*)(sb + n * 2048 + ((fq ^ swz) << 4));
; #pragma unroll
;       for (int gq = 0; gq < 8; ++gq) {
;         const int ks = gq >> 2, nh = gq & 3;
;         if (gq < 7) {
;           const int ks2 = (gq + 1) >> 2, nh2 = (gq + 1) & 3;
; #pragma unroll
;           for (int n = 0; n < 2; ++n) bfb[(gq + 1) & 1][n] = *(const bf16x8*)(sb + (nh2 * 2 + n) * 2048 + (((ks2 * 4 + fq) ^ swz) << 4));
;         }
;         if (gq == 3) {
; #pragma unroll
;           for (int m = 0; m < 4; ++m) afB[m] = *(const bf16x8*)(sa + m * 2048 + (((4 + fq) ^ swz) << 4));
;         }
;         __builtin_amdgcn_sched_barrier(0);
; #pragma unroll
	v_mfma_f32_16x16x32_bf16 v[114:117], v[172:175], v[184:187], v[114:117]
	v_mfma_f32_16x16x32_bf16 v[86:89], v[172:175], v[208:211], v[86:89]
	v_mfma_f32_16x16x32_bf16 v[54:57], v[172:175], v[212:215], v[54:57]
	v_mfma_f32_16x16x32_bf16 v[22:25], v[172:175], v[216:219], v[22:25]
	s_waitcnt lgkmcnt(3)
	v_mfma_f32_16x16x32_bf16 v[102:105], v[176:179], v[184:187], v[102:105]
	s_waitcnt lgkmcnt(2)
	v_mfma_f32_16x16x32_bf16 v[98:101], v[180:183], v[184:187], v[98:101]
	v_mfma_f32_16x16x32_bf16 v[74:77], v[176:179], v[208:211], v[74:77]
	v_mfma_f32_16x16x32_bf16 v[66:69], v[180:183], v[208:211], v[66:69]
	v_mfma_f32_16x16x32_bf16 v[46:49], v[176:179], v[212:215], v[46:49]
	v_mfma_f32_16x16x32_bf16 v[34:37], v[180:183], v[212:215], v[34:37]
	v_mfma_f32_16x16x32_bf16 v[10:13], v[176:179], v[216:219], v[10:13]
	v_mfma_f32_16x16x32_bf16 v[6:9], v[180:183], v[216:219], v[6:9]
	s_waitcnt lgkmcnt(1)
	v_mfma_f32_16x16x32_bf16 v[70:73], v[168:171], v[184:187], v[70:73]
	s_add_i32 s6, s6, 64
	s_cmpk_eq_i32 s6, 0xac0
	s_mov_b32 s7, s9
	s_waitcnt lgkmcnt(0)
	v_mfma_f32_16x16x32_bf16 v[62:65], v[188:191], v[184:187], v[62:65]
	v_mfma_f32_16x16x32_bf16 v[42:45], v[168:171], v[208:211], v[42:45]
	v_mfma_f32_16x16x32_bf16 v[30:33], v[188:191], v[208:211], v[30:33]
	v_mfma_f32_16x16x32_bf16 v[18:21], v[168:171], v[212:215], v[18:21]
	v_mfma_f32_16x16x32_bf16 v[14:17], v[188:191], v[212:215], v[14:17]
	v_mfma_f32_16x16x32_bf16 v[2:5], v[168:171], v[216:219], v[2:5]
	v_mfma_f32_16x16x32_bf16 v[90:93], v[188:191], v[216:219], v[90:93]
	s_cbranch_scc0 .LBB0_3516
	v_add_u32_e32 v130, s8, v145
	s_waitcnt vmcnt(0)
	s_barrier
	v_add_u32_e32 v140, v130, v147
	ds_read_b128 v[132:135], v140
	ds_read_b128 v[136:139], v140 offset:2048
	ds_read_b128 v[168:171], v140 offset:4096
	ds_read_b128 v[172:175], v140 offset:6144
	v_add_u32_e32 v140, s8, v146
	v_add_u32_e32 v141, v140, v147
	ds_read_b128 v[176:179], v141 offset:32768
	ds_read_b128 v[180:183], v141 offset:34816
	ds_read_b128 v[184:187], v141 offset:36864
	ds_read_b128 v[188:191], v141 offset:38912
	v_add_u32_e32 v130, v130, v148
	s_waitcnt lgkmcnt(0)
	v_mfma_f32_16x16x32_bf16 v[126:129], v[176:179], v[132:135], v[126:129]
	v_mfma_f32_16x16x32_bf16 v[110:113], v[176:179], v[136:139], v[110:113]
	v_mfma_f32_16x16x32_bf16 v[82:85], v[176:179], v[168:171], v[82:85]
	v_mfma_f32_16x16x32_bf16 v[50:53], v[176:179], v[172:175], v[50:53]
	ds_read_b128 v[176:179], v141 offset:40960
	ds_read_b128 v[192:195], v141 offset:43008
	v_mfma_f32_16x16x32_bf16 v[122:125], v[180:183], v[132:135], v[122:125]
	v_mfma_f32_16x16x32_bf16 v[106:109], v[180:183], v[136:139], v[106:109]
	v_mfma_f32_16x16x32_bf16 v[78:81], v[180:183], v[168:171], v[78:81]
	v_mfma_f32_16x16x32_bf16 v[38:41], v[180:183], v[172:175], v[38:41]
	v_mfma_f32_16x16x32_bf16 v[118:121], v[184:187], v[132:135], v[118:121]
	v_mfma_f32_16x16x32_bf16 v[180:183], v[184:187], v[136:139], v[94:97]
	v_mfma_f32_16x16x32_bf16 v[200:203], v[184:187], v[168:171], v[58:61]
	v_mfma_f32_16x16x32_bf16 v[204:207], v[188:191], v[168:171], v[54:57]
	v_mfma_f32_16x16x32_bf16 v[184:187], v[184:187], v[172:175], v[26:29]
	s_nop 2
	ds_read_b128 v[26:29], v141 offset:45056
	ds_read_b128 v[54:57], v141 offset:47104
	v_mfma_f32_16x16x32_bf16 v[114:117], v[188:191], v[132:135], v[114:117]
	v_mfma_f32_16x16x32_bf16 v[196:199], v[188:191], v[136:139], v[86:89]
	v_mfma_f32_16x16x32_bf16 v[188:191], v[188:191], v[172:175], v[22:25]
	v_add_u32_e32 v140, v140, v148
	s_waitcnt lgkmcnt(0)
	v_mfma_f32_16x16x32_bf16 v[102:105], v[176:179], v[132:135], v[102:105]
	ds_read_b128 v[22:25], v140 offset:32768
	ds_read_b128 v[86:89], v140 offset:34816
	v_mfma_f32_16x16x32_bf16 v[74:77], v[176:179], v[136:139], v[74:77]
	v_mfma_f32_16x16x32_bf16 v[46:49], v[176:179], v[168:171], v[46:49]
	v_mfma_f32_16x16x32_bf16 v[10:13], v[176:179], v[172:175], v[10:13]
	ds_read_b128 v[176:179], v130
	ds_read_b128 v[208:211], v130 offset:2048
	ds_read_b128 v[212:215], v130 offset:4096
	ds_read_b128 v[216:219], v130 offset:6144
	v_mfma_f32_16x16x32_bf16 v[98:101], v[192:195], v[132:135], v[98:101]
	v_mfma_f32_16x16x32_bf16 v[66:69], v[192:195], v[136:139], v[66:69]
	v_mfma_f32_16x16x32_bf16 v[34:37], v[192:195], v[168:171], v[34:37]
	v_mfma_f32_16x16x32_bf16 v[6:9], v[192:195], v[172:175], v[6:9]
	v_mfma_f32_16x16x32_bf16 v[220:223], v[26:29], v[168:171], v[18:21]
	v_mfma_f32_16x16x32_bf16 v[168:171], v[54:57], v[168:171], v[14:17]
	s_nop 2
	ds_read_b128 v[14:17], v140 offset:36864
	ds_read_b128 v[18:21], v140 offset:38912
	v_mfma_f32_16x16x32_bf16 v[70:73], v[26:29], v[132:135], v[70:73]
	v_mfma_f32_16x16x32_bf16 v[132:135], v[54:57], v[132:135], v[62:65]
	v_mfma_f32_16x16x32_bf16 v[192:195], v[26:29], v[136:139], v[42:45]
	v_mfma_f32_16x16x32_bf16 v[136:139], v[54:57], v[136:139], v[30:33]
	v_mfma_f32_16x16x32_bf16 v[2:5], v[26:29], v[172:175], v[2:5]
	v_mfma_f32_16x16x32_bf16 v[172:175], v[54:57], v[172:175], v[90:93]
	ds_read_b128 v[224:227], v140 offset:40960
	ds_read_b128 v[228:231], v140 offset:43008
	s_waitcnt lgkmcnt(0)
	v_mfma_f32_16x16x32_bf16 v[126:129], v[22:25], v[176:179], v[126:129]
	v_mfma_f32_16x16x32_bf16 v[122:125], v[86:89], v[176:179], v[122:125]
	v_mfma_f32_16x16x32_bf16 v[94:97], v[22:25], v[208:211], v[110:113]
	v_mfma_f32_16x16x32_bf16 v[90:93], v[86:89], v[208:211], v[106:109]
	v_mfma_f32_16x16x32_bf16 v[62:65], v[22:25], v[212:215], v[82:85]
	v_mfma_f32_16x16x32_bf16 v[58:61], v[86:89], v[212:215], v[78:81]
	v_mfma_f32_16x16x32_bf16 v[30:33], v[22:25], v[216:219], v[50:53]
	v_mfma_f32_16x16x32_bf16 v[26:29], v[86:89], v[216:219], v[38:41]
	v_mfma_f32_16x16x32_bf16 v[86:89], v[14:17], v[208:211], v[180:183]
	v_mfma_f32_16x16x32_bf16 v[22:25], v[14:17], v[216:219], v[184:187]
	s_nop 1
	ds_read_b128 v[180:183], v140 offset:45056
	ds_read_b128 v[184:187], v140 offset:47104
	v_mfma_f32_16x16x32_bf16 v[118:121], v[14:17], v[176:179], v[118:121]
	v_mfma_f32_16x16x32_bf16 v[114:117], v[18:21], v[176:179], v[114:117]
	v_mfma_f32_16x16x32_bf16 v[82:85], v[18:21], v[208:211], v[196:199]
	v_mfma_f32_16x16x32_bf16 v[54:57], v[14:17], v[212:215], v[200:203]
	v_mfma_f32_16x16x32_bf16 v[50:53], v[18:21], v[212:215], v[204:207]
	v_mfma_f32_16x16x32_bf16 v[18:21], v[18:21], v[216:219], v[188:191]
	v_mfma_f32_16x16x32_bf16 v[110:113], v[224:227], v[176:179], v[102:105]
	v_mfma_f32_16x16x32_bf16 v[106:109], v[228:231], v[176:179], v[98:101]
	v_mfma_f32_16x16x32_bf16 v[78:81], v[224:227], v[208:211], v[74:77]
	v_mfma_f32_16x16x32_bf16 v[74:77], v[228:231], v[208:211], v[66:69]
	v_mfma_f32_16x16x32_bf16 v[46:49], v[224:227], v[212:215], v[46:49]
	v_mfma_f32_16x16x32_bf16 v[42:45], v[228:231], v[212:215], v[34:37]
	v_mfma_f32_16x16x32_bf16 v[14:17], v[224:227], v[216:219], v[10:13]
	v_mfma_f32_16x16x32_bf16 v[10:13], v[228:231], v[216:219], v[6:9]
	v_mov_b32_e32 v130, v1
	s_waitcnt vmcnt(0) lgkmcnt(0)
	s_barrier
; __device__ __forceinline__ unsigned pack2(float a, float b) { unsigned r; asm("v_cvt_pk_bf16_f32 %0, %1, %2" : "=v"(r) : "v"(a), "v"(b)); return r; }
; __device__ __forceinline__ float bf2f(bf16_t h) { return __uint_as_float(((unsigned)h) << 16); }
;   __device__ __forceinline__ void c4(int g, int rig, int col, f32x4 v) const {
;     const size_t o = ((size_t)g * 2048 + rig) * 1024 + col;
;     f32x4 bs;
;     if (BASE_F32) bs = __builtin_nontemporal_load((const f32x4*)((const float*)base + o));
;     else {
;       const uint2 u = *(const uint2*)((const bf16_t*)base + o);
;       bs[0] = bf2f((bf16_t)(u.x & 0xffff)); bs[1] = bf2f((bf16_t)(u.x >> 16)); bs[2] = bf2f((bf16_t)(u.y & 0xffff)); bs[3] = bf2f((bf16_t)(u.y >> 16));
;     }
;     const f32x4 gt = *(const f32x4*)(gate + (size_t)g * 6144 + col);
;     f32x4 bi = {0.f, 0.f, 0.f, 0.f};
;     if (bias) bi = *(const f32x4*)(bias + col);
;     f32x4 r;
; #pragma unroll
;     for (int j = 0; j < 4; ++j) r[j] = bs[j] + gt[j] * (v[j] + bi[j]);
;     uint2 w; w.x = pack2(r[0], r[1]); w.y = pack2(r[2], r[3]);
;     *(uint2*)(X16 + o) = w;
;   }
; template <bool SWAP, class Epi, bool THIN = false> ...
;     ...
;     if constexpr (Epi::KIND == 0) {
; #pragma unroll
;       for (int m = 0; m < 4; ++m) {
;         const int rig = rig0 + rw + m * 16 + fr_e;
;         if constexpr (Epi::ROWSUM) {
;           float ss = 0.f;
; #pragma unroll
;           for (int n = 0; n < 8; ++n) {
;             const int col = nt * 256 + wc_e * 128 + n * 16 + fq_e * 4;
;             if (col < N) ss += epi.c4(g, rig, col, acc[m][n]);
;           }
;           ss += __shfl_xor(ss, 16); ss += __shfl_xor(ss, 32);
;           if (fq_e == 0) epi.rowsum(g, rig, nt * 2 + wc_e, ss);
;         } else {
; #pragma unroll
;           for (int n = 0; n < 8; ++n) {
;             const int col = nt * 256 + wc_e * 128 + n * 16 + fq_e * 4;
;             if (col < N) epi.c4(g, rig, col, acc[m][n]);
;           }
;         }
	v_mfma_f32_16x16x32_bf16 v[98:101], v[184:187], v[176:179], v[132:135]
	v_ashrrev_i32_e32 v7, 8, v130
	v_add_u32_e32 v7, s5, v7
	v_ashrrev_i32_e32 v8, 31, v7
	v_lshrrev_b32_e32 v8, 28, v8
	v_add_u32_e32 v8, v7, v8
	v_ashrrev_i32_e32 v134, 4, v8
	v_lshlrev_b32_e32 v8, 11, v134
	v_lshlrev_b32_e32 v7, 7, v7
	v_sub_u32_e32 v7, v7, v8
	v_lshrrev_b32_e32 v8, 1, v130
	v_and_b32_e32 v6, 15, v130
	v_and_b32_e32 v8, 64, v8
	v_mfma_f32_16x16x32_bf16 v[66:69], v[184:187], v[208:211], v[136:139]
	v_ashrrev_i32_e32 v135, 31, v134
	s_nop 1
	v_or3_b32 v136, v7, v8, v6
	v_lshlrev_b32_e32 v6, 1, v130
	v_and_b32_e32 v132, 0x80, v6
	v_mfma_f32_16x16x32_bf16 v[6:9], v[180:183], v[216:219], v[2:5]
	v_ashrrev_i32_e32 v137, 31, v136
	v_lshlrev_b64 v[138:139], 21, v[134:135]
	v_lshlrev_b64 v[140:141], 10, v[136:137]
	v_lshrrev_b32_e32 v2, 2, v130
	v_and_b32_e32 v2, 12, v2
	v_mfma_f32_16x16x32_bf16 v[102:105], v[180:183], v[176:179], v[70:73]
	v_or3_b32 v132, v2, v132, s4
	v_mad_i64_i32 v[134:135], s[4:5], v134, s31, 0
	v_mfma_f32_16x16x32_bf16 v[70:73], v[180:183], v[208:211], v[192:195]
	v_lshl_add_u64 v[140:141], v[140:141], 0, v[138:139]
	v_cmp_gt_i32_e32 vcc, s34, v132
	v_ashrrev_i32_e32 v133, 31, v132
	v_bfe_u32 v246, v130, 4, 1
	v_mul_u32_u24_e32 v246, 24, v246
	v_mov_b32_e32 v247, 0
	v_mfma_f32_16x16x32_bf16 v[38:41], v[180:183], v[212:215], v[220:223]
	v_lshl_add_u64 v[134:135], s[22:23], 0, v[134:135]
	v_lshl_add_u64 v[140:141], v[140:141], 1, s[18:19]
	v_mfma_f32_16x16x32_bf16 v[34:37], v[184:187], v[212:215], v[168:171]
	v_mfma_f32_16x16x32_bf16 v[2:5], v[184:187], v[216:219], v[172:175]
	v_lshl_add_u64 v[218:219], v[132:133], 2, v[134:135]
	global_load_dwordx4 v[198:201], v[218:219], off
	global_load_dwordx4 v[202:205], v[218:219], off offset:64
	global_load_dwordx4 v[206:209], v[218:219], off offset:128
	global_load_dwordx4 v[210:213], v[218:219], off offset:192
	global_load_dwordx4 v[214:217], v[218:219], off offset:256
	global_load_dwordx4 v[224:227], v[218:219], off offset:320
	global_load_dwordx4 v[228:231], v[218:219], off offset:384
	global_load_dwordx4 v[232:235], v[218:219], off offset:448
	s_nop 0
	v_lshl_add_u64 v[172:173], v[132:133], 1, v[140:141]
	v_lshl_add_u64 v[196:197], v[132:133], 1, v[140:141]
	global_load_dwordx2 v[176:177], v[196:197], off
	global_load_dwordx2 v[178:179], v[196:197], off offset:32
	global_load_dwordx2 v[180:181], v[196:197], off offset:64
	global_load_dwordx2 v[182:183], v[196:197], off offset:96
	global_load_dwordx2 v[184:185], v[196:197], off offset:128
	global_load_dwordx2 v[186:187], v[196:197], off offset:160
	global_load_dwordx2 v[188:189], v[196:197], off offset:192
	global_load_dwordx2 v[190:191], v[196:197], off offset:224
	v_add_f32_e32 v126, 0, v126
	v_add_f32_e32 v127, 0, v127
	v_add_f32_e32 v128, 0, v128
	v_add_f32_e32 v129, 0, v129
	s_waitcnt vmcnt(7)
	v_lshlrev_b32_e32 v130, 16, v176
	v_and_b32_e32 v137, 0xffff0000, v176
	v_lshlrev_b32_e32 v167, 16, v177
	v_and_b32_e32 v174, 0xffff0000, v177
	v_fmac_f32_e32 v130, v126, v198
	v_fmac_f32_e32 v137, v127, v199
	v_fmac_f32_e32 v167, v128, v200
	v_fmac_f32_e32 v174, v129, v201
	v_cvt_pk_bf16_f32 v126, v130, v137
	v_cvt_pk_bf16_f32 v127, v167, v174
	v_lshl_add_u64 v[168:169], v[132:133], 1, v[140:141]
	v_add_f32_e32 v122, 0, v122
	v_add_f32_e32 v123, 0, v123
	v_add_f32_e32 v124, 0, v124
	v_add_f32_e32 v125, 0, v125
	s_waitcnt vmcnt(6)
	v_lshlrev_b32_e32 v130, 16, v178
	v_and_b32_e32 v137, 0xffff0000, v178
	v_lshlrev_b32_e32 v167, 16, v179
	v_and_b32_e32 v170, 0xffff0000, v179
	v_fmac_f32_e32 v130, v122, v202
	v_fmac_f32_e32 v137, v123, v203
	v_fmac_f32_e32 v167, v124, v204
	v_fmac_f32_e32 v170, v125, v205
	v_cvt_pk_bf16_f32 v128, v130, v137
	v_cvt_pk_bf16_f32 v129, v167, v170
	s_nop 1
	v_permlane16_swap_b32 v126, v128
	v_permlane16_swap_b32 v127, v129
	v_lshl_add_u64 v[248:249], v[168:169], 0, v[246:247]
	s_nop 0
	global_store_dwordx4 v[248:249], v[126:129], off
	s_nop 1
	v_or_b32_e32 v122, 32, v132
	v_lshl_add_u64 v[126:127], v[132:133], 1, v[140:141]
	v_add_f32_e32 v118, 0, v118
	v_add_f32_e32 v119, 0, v119
	v_add_f32_e32 v120, 0, v120
	v_add_f32_e32 v121, 0, v121
	s_waitcnt vmcnt(6)
	v_lshlrev_b32_e32 v130, 16, v180
	v_and_b32_e32 v128, 0xffff0000, v180
	v_lshlrev_b32_e32 v137, 16, v181
	v_and_b32_e32 v129, 0xffff0000, v181
	v_fmac_f32_e32 v130, v118, v206
	v_fmac_f32_e32 v128, v119, v207
	v_fmac_f32_e32 v137, v120, v208
	v_fmac_f32_e32 v129, v121, v209
	v_cvt_pk_bf16_f32 v118, v130, v128
	v_cvt_pk_bf16_f32 v119, v137, v129
	v_lshl_add_u64 v[122:123], v[132:133], 1, v[140:141]
	v_add_f32_e32 v114, 0, v114
	v_add_f32_e32 v115, 0, v115
	v_add_f32_e32 v116, 0, v116
	v_add_f32_e32 v117, 0, v117
	s_waitcnt vmcnt(5)
	v_lshlrev_b32_e32 v126, 16, v182
	v_and_b32_e32 v124, 0xffff0000, v182
	v_lshlrev_b32_e32 v127, 16, v183
	v_and_b32_e32 v125, 0xffff0000, v183
	v_fmac_f32_e32 v126, v114, v210
	v_fmac_f32_e32 v124, v115, v211
	v_fmac_f32_e32 v127, v116, v212
	v_fmac_f32_e32 v125, v117, v213
	v_cvt_pk_bf16_f32 v120, v126, v124
	v_cvt_pk_bf16_f32 v121, v127, v125
	s_nop 1
	v_permlane16_swap_b32 v118, v120
	v_permlane16_swap_b32 v119, v121
	v_lshl_add_u64 v[248:249], v[122:123], 0, v[246:247]
	s_nop 0
	global_store_dwordx4 v[248:249], v[118:121], off offset:64
	s_nop 1
	v_or_b32_e32 v114, 64, v132
	v_lshl_add_u64 v[118:119], v[132:133], 1, v[140:141]
	v_add_f32_e32 v110, 0, v110
	v_add_f32_e32 v111, 0, v111
	v_add_f32_e32 v112, 0, v112
	v_add_f32_e32 v113, 0, v113
	s_waitcnt vmcnt(5)
; __device__ __forceinline__ unsigned pack2(float a, float b) { unsigned r; asm("v_cvt_pk_bf16_f32 %0, %1, %2" : "=v"(r) : "v"(a), "v"(b)); return r; }
; __device__ __forceinline__ float bf2f(bf16_t h) { return __uint_as_float(((unsigned)h) << 16); }
;   __device__ __forceinline__ void c4(int g, int rig, int col, f32x4 v) const {
;     const size_t o = ((size_t)g * 2048 + rig) * 1024 + col;
;     f32x4 bs;
;     if (BASE_F32) bs = __builtin_nontemporal_load((const f32x4*)((const float*)base + o));
;     else {
;       const uint2 u = *(const uint2*)((const bf16_t*)base + o);
;       bs[0] = bf2f((bf16_t)(u.x & 0xffff)); bs[1] = bf2f((bf16_t)(u.x >> 16)); bs[2] = bf2f((bf16_t)(u.y & 0xffff)); bs[3] = bf2f((bf16_t)(u.y >> 16));
;     }
;     const f32x4 gt = *(const f32x4*)(gate + (size_t)g * 6144 + col);
;     f32x4 bi = {0.f, 0.f, 0.f, 0.f};
;     if (bias) bi = *(const f32x4*)(bias + col);
;     f32x4 r;
; #pragma unroll
;     for (int j = 0; j < 4; ++j) r[j] = bs[j] + gt[j] * (v[j] + bi[j]);
;     uint2 w; w.x = pack2(r[0], r[1]); w.y = pack2(r[2], r[3]);
;     *(uint2*)(X16 + o) = w;
;   }
; template <bool SWAP, class Epi, bool THIN = false> ...
;     ...
;     if constexpr (Epi::KIND == 0) {
; #pragma unroll
;       for (int m = 0; m < 4; ++m) {
;         const int rig = rig0 + rw + m * 16 + fr_e;
;         if constexpr (Epi::ROWSUM) {
;           float ss = 0.f;
; #pragma unroll
;           for (int n = 0; n < 8; ++n) {
;             const int col = nt * 256 + wc_e * 128 + n * 16 + fq_e * 4;
;             if (col < N) ss += epi.c4(g, rig, col, acc[m][n]);
;           }
;           ss += __shfl_xor(ss, 16); ss += __shfl_xor(ss, 32);
;           if (fq_e == 0) epi.rowsum(g, rig, nt * 2 + wc_e, ss);
;         } else {
; #pragma unroll
;           for (int n = 0; n < 8; ++n) {
;             const int col = nt * 256 + wc_e * 128 + n * 16 + fq_e * 4;
;             if (col < N) epi.c4(g, rig, col, acc[m][n]);
;           }
;         }
	v_lshlrev_b32_e32 v122, 16, v184
	v_and_b32_e32 v120, 0xffff0000, v184
	v_lshlrev_b32_e32 v123, 16, v185
	v_and_b32_e32 v121, 0xffff0000, v185
	v_fmac_f32_e32 v122, v110, v214
	v_fmac_f32_e32 v120, v111, v215
	v_fmac_f32_e32 v123, v112, v216
	v_fmac_f32_e32 v121, v113, v217
	v_cvt_pk_bf16_f32 v110, v122, v120
	v_cvt_pk_bf16_f32 v111, v123, v121
	v_lshl_add_u64 v[114:115], v[132:133], 1, v[140:141]
	v_add_f32_e32 v106, 0, v106
	v_add_f32_e32 v107, 0, v107
	v_add_f32_e32 v108, 0, v108
	v_add_f32_e32 v109, 0, v109
	s_waitcnt vmcnt(4)
	v_lshlrev_b32_e32 v118, 16, v186
	v_and_b32_e32 v116, 0xffff0000, v186
	v_lshlrev_b32_e32 v119, 16, v187
	v_and_b32_e32 v117, 0xffff0000, v187
	v_fmac_f32_e32 v118, v106, v224
	v_fmac_f32_e32 v116, v107, v225
	v_fmac_f32_e32 v119, v108, v226
	v_fmac_f32_e32 v117, v109, v227
	v_cvt_pk_bf16_f32 v112, v118, v116
	v_cvt_pk_bf16_f32 v113, v119, v117
	s_nop 1
	v_permlane16_swap_b32 v110, v112
	v_permlane16_swap_b32 v111, v113
	v_lshl_add_u64 v[248:249], v[114:115], 0, v[246:247]
	s_nop 0
	global_store_dwordx4 v[248:249], v[110:113], off offset:128
	s_nop 1
	v_or_b32_e32 v106, 0x60, v132
	v_lshl_add_u64 v[110:111], v[132:133], 1, v[140:141]
	v_add_f32_e32 v102, 0, v102
	v_add_f32_e32 v103, 0, v103
	v_add_f32_e32 v104, 0, v104
	v_add_f32_e32 v105, 0, v105
	s_waitcnt vmcnt(4)
	v_lshlrev_b32_e32 v114, 16, v188
	v_and_b32_e32 v112, 0xffff0000, v188
	v_lshlrev_b32_e32 v115, 16, v189
	v_and_b32_e32 v113, 0xffff0000, v189
	v_fmac_f32_e32 v114, v102, v228
	v_fmac_f32_e32 v112, v103, v229
	v_fmac_f32_e32 v115, v104, v230
	v_fmac_f32_e32 v113, v105, v231
	v_cvt_pk_bf16_f32 v102, v114, v112
	v_cvt_pk_bf16_f32 v103, v115, v113
	v_lshl_add_u64 v[106:107], v[132:133], 1, v[140:141]
	v_add_f32_e32 v98, 0, v98
	v_add_f32_e32 v99, 0, v99
	v_add_f32_e32 v100, 0, v100
	v_add_f32_e32 v101, 0, v101
	s_waitcnt vmcnt(3)
	v_lshlrev_b32_e32 v110, 16, v190
	v_and_b32_e32 v108, 0xffff0000, v190
	v_lshlrev_b32_e32 v111, 16, v191
	v_and_b32_e32 v109, 0xffff0000, v191
	v_fmac_f32_e32 v110, v98, v232
	v_fmac_f32_e32 v108, v99, v233
	v_fmac_f32_e32 v111, v100, v234
	v_fmac_f32_e32 v109, v101, v235
	v_cvt_pk_bf16_f32 v104, v110, v108
	v_cvt_pk_bf16_f32 v105, v111, v109
	s_nop 1
	v_permlane16_swap_b32 v102, v104
	v_permlane16_swap_b32 v103, v105
	v_lshl_add_u64 v[248:249], v[106:107], 0, v[246:247]
	s_nop 0
	global_store_dwordx4 v[248:249], v[102:105], off offset:192
	s_nop 1
	v_or_b32_e32 v98, 16, v136
	v_ashrrev_i32_e32 v99, 31, v98
	v_lshlrev_b64 v[98:99], 10, v[98:99]
	v_lshl_add_u64 v[98:99], v[98:99], 0, v[138:139]
	v_lshl_add_u64 v[98:99], v[98:99], 1, s[18:19]
	v_lshl_add_u64 v[104:105], v[132:133], 1, v[98:99]
	v_lshl_add_u64 v[196:197], v[132:133], 1, v[98:99]
	global_load_dwordx2 v[176:177], v[196:197], off
	global_load_dwordx2 v[178:179], v[196:197], off offset:32
	global_load_dwordx2 v[180:181], v[196:197], off offset:64
	global_load_dwordx2 v[182:183], v[196:197], off offset:96
	global_load_dwordx2 v[184:185], v[196:197], off offset:128
	global_load_dwordx2 v[186:187], v[196:197], off offset:160
	global_load_dwordx2 v[188:189], v[196:197], off offset:192
	global_load_dwordx2 v[190:191], v[196:197], off offset:224
	v_add_f32_e32 v94, 0, v94
	v_add_f32_e32 v95, 0, v95
	v_add_f32_e32 v96, 0, v96
	v_add_f32_e32 v97, 0, v97
	s_waitcnt vmcnt(7)
	v_lshlrev_b32_e32 v108, 16, v176
	v_and_b32_e32 v106, 0xffff0000, v176
	v_lshlrev_b32_e32 v109, 16, v177
	v_and_b32_e32 v107, 0xffff0000, v177
	v_fmac_f32_e32 v108, v94, v198
	v_fmac_f32_e32 v106, v95, v199
	v_fmac_f32_e32 v109, v96, v200
	v_fmac_f32_e32 v107, v97, v201
	v_cvt_pk_bf16_f32 v94, v108, v106
	v_cvt_pk_bf16_f32 v95, v109, v107
	v_lshl_add_u64 v[100:101], v[132:133], 1, v[98:99]
	v_add_f32_e32 v90, 0, v90
	v_add_f32_e32 v91, 0, v91
	v_add_f32_e32 v92, 0, v92
	v_add_f32_e32 v93, 0, v93
	s_waitcnt vmcnt(6)
	v_lshlrev_b32_e32 v104, 16, v178
	v_and_b32_e32 v102, 0xffff0000, v178
	v_lshlrev_b32_e32 v105, 16, v179
	v_and_b32_e32 v103, 0xffff0000, v179
	v_fmac_f32_e32 v104, v90, v202
	v_fmac_f32_e32 v102, v91, v203
	v_fmac_f32_e32 v105, v92, v204
	v_fmac_f32_e32 v103, v93, v205
	v_cvt_pk_bf16_f32 v96, v104, v102
	v_cvt_pk_bf16_f32 v97, v105, v103
	s_nop 1
	v_permlane16_swap_b32 v94, v96
	v_permlane16_swap_b32 v95, v97
	v_lshl_add_u64 v[248:249], v[100:101], 0, v[246:247]
	s_nop 0
	global_store_dwordx4 v[248:249], v[94:97], off
	s_nop 1
	v_lshl_add_u64 v[94:95], v[132:133], 1, v[98:99]
	v_add_f32_e32 v86, 0, v86
	v_add_f32_e32 v87, 0, v87
	v_add_f32_e32 v88, 0, v88
	v_add_f32_e32 v89, 0, v89
	s_waitcnt vmcnt(6)
	v_lshlrev_b32_e32 v100, 16, v180
	v_and_b32_e32 v96, 0xffff0000, v180
	v_lshlrev_b32_e32 v101, 16, v181
	v_and_b32_e32 v97, 0xffff0000, v181
	v_fmac_f32_e32 v100, v86, v206
	v_fmac_f32_e32 v96, v87, v207
	v_fmac_f32_e32 v101, v88, v208
	v_fmac_f32_e32 v97, v89, v209
	v_cvt_pk_bf16_f32 v86, v100, v96
	v_cvt_pk_bf16_f32 v87, v101, v97
	v_lshl_add_u64 v[90:91], v[132:133], 1, v[98:99]
	v_add_f32_e32 v82, 0, v82
	v_add_f32_e32 v83, 0, v83
	v_add_f32_e32 v84, 0, v84
	v_add_f32_e32 v85, 0, v85
	s_waitcnt vmcnt(5)
	v_lshlrev_b32_e32 v94, 16, v182
	v_and_b32_e32 v92, 0xffff0000, v182
	v_lshlrev_b32_e32 v95, 16, v183
	v_and_b32_e32 v93, 0xffff0000, v183
	v_fmac_f32_e32 v94, v82, v210
	v_fmac_f32_e32 v92, v83, v211
	v_fmac_f32_e32 v95, v84, v212
	v_fmac_f32_e32 v93, v85, v213
	v_cvt_pk_bf16_f32 v88, v94, v92
	v_cvt_pk_bf16_f32 v89, v95, v93
	s_nop 1
	v_permlane16_swap_b32 v86, v88
	v_permlane16_swap_b32 v87, v89
	v_lshl_add_u64 v[248:249], v[90:91], 0, v[246:247]
	s_nop 0
	global_store_dwordx4 v[248:249], v[86:89], off offset:64
	s_nop 1
	v_lshl_add_u64 v[86:87], v[132:133], 1, v[98:99]
	v_add_f32_e32 v78, 0, v78
	v_add_f32_e32 v79, 0, v79
	v_add_f32_e32 v80, 0, v80
	v_add_f32_e32 v81, 0, v81
	s_waitcnt vmcnt(5)
; __device__ __forceinline__ unsigned pack2(float a, float b) { unsigned r; asm("v_cvt_pk_bf16_f32 %0, %1, %2" : "=v"(r) : "v"(a), "v"(b)); return r; }
; __device__ __forceinline__ float bf2f(bf16_t h) { return __uint_as_float(((unsigned)h) << 16); }
;   __device__ __forceinline__ void c4(int g, int rig, int col, f32x4 v) const {
;     const size_t o = ((size_t)g * 2048 + rig) * 1024 + col;
;     f32x4 bs;
;     if (BASE_F32) bs = __builtin_nontemporal_load((const f32x4*)((const float*)base + o));
;     else {
;       const uint2 u = *(const uint2*)((const bf16_t*)base + o);
;       bs[0] = bf2f((bf16_t)(u.x & 0xffff)); bs[1] = bf2f((bf16_t)(u.x >> 16)); bs[2] = bf2f((bf16_t)(u.y & 0xffff)); bs[3] = bf2f((bf16_t)(u.y >> 16));
;     }
;     const f32x4 gt = *(const f32x4*)(gate + (size_t)g * 6144 + col);
;     f32x4 bi = {0.f, 0.f, 0.f, 0.f};
;     if (bias) bi = *(const f32x4*)(bias + col);
;     f32x4 r;
; #pragma unroll
;     for (int j = 0; j < 4; ++j) r[j] = bs[j] + gt[j] * (v[j] + bi[j]);
;     uint2 w; w.x = pack2(r[0], r[1]); w.y = pack2(r[2], r[3]);
;     *(uint2*)(X16 + o) = w;
;   }
; template <bool SWAP, class Epi, bool THIN = false> ...
;     ...
;     if constexpr (Epi::KIND == 0) {
; #pragma unroll
;       for (int m = 0; m < 4; ++m) {
;         const int rig = rig0 + rw + m * 16 + fr_e;
;         if constexpr (Epi::ROWSUM) {
;           float ss = 0.f;
; #pragma unroll
;           for (int n = 0; n < 8; ++n) {
;             const int col = nt * 256 + wc_e * 128 + n * 16 + fq_e * 4;
;             if (col < N) ss += epi.c4(g, rig, col, acc[m][n]);
;           }
;           ss += __shfl_xor(ss, 16); ss += __shfl_xor(ss, 32);
;           if (fq_e == 0) epi.rowsum(g, rig, nt * 2 + wc_e, ss);
;         } else {
; #pragma unroll
;           for (int n = 0; n < 8; ++n) {
;             const int col = nt * 256 + wc_e * 128 + n * 16 + fq_e * 4;
;             if (col < N) epi.c4(g, rig, col, acc[m][n]);
;           }
;         }
	v_lshlrev_b32_e32 v90, 16, v184
	v_and_b32_e32 v88, 0xffff0000, v184
	v_lshlrev_b32_e32 v91, 16, v185
	v_and_b32_e32 v89, 0xffff0000, v185
	v_fmac_f32_e32 v90, v78, v214
	v_fmac_f32_e32 v88, v79, v215
	v_fmac_f32_e32 v91, v80, v216
	v_fmac_f32_e32 v89, v81, v217
	v_cvt_pk_bf16_f32 v78, v90, v88
	v_cvt_pk_bf16_f32 v79, v91, v89
	v_lshl_add_u64 v[82:83], v[132:133], 1, v[98:99]
	v_add_f32_e32 v74, 0, v74
	v_add_f32_e32 v75, 0, v75
	v_add_f32_e32 v76, 0, v76
	v_add_f32_e32 v77, 0, v77
	s_waitcnt vmcnt(4)
	v_lshlrev_b32_e32 v86, 16, v186
	v_and_b32_e32 v84, 0xffff0000, v186
	v_lshlrev_b32_e32 v87, 16, v187
	v_and_b32_e32 v85, 0xffff0000, v187
	v_fmac_f32_e32 v86, v74, v224
	v_fmac_f32_e32 v84, v75, v225
	v_fmac_f32_e32 v87, v76, v226
	v_fmac_f32_e32 v85, v77, v227
	v_cvt_pk_bf16_f32 v80, v86, v84
	v_cvt_pk_bf16_f32 v81, v87, v85
	s_nop 1
	v_permlane16_swap_b32 v78, v80
	v_permlane16_swap_b32 v79, v81
	v_lshl_add_u64 v[248:249], v[82:83], 0, v[246:247]
	s_nop 0
	global_store_dwordx4 v[248:249], v[78:81], off offset:128
	s_nop 1
	v_lshl_add_u64 v[78:79], v[132:133], 1, v[98:99]
	v_add_f32_e32 v70, 0, v70
	v_add_f32_e32 v71, 0, v71
	v_add_f32_e32 v72, 0, v72
	v_add_f32_e32 v73, 0, v73
	s_waitcnt vmcnt(4)
	v_lshlrev_b32_e32 v82, 16, v188
	v_and_b32_e32 v80, 0xffff0000, v188
	v_lshlrev_b32_e32 v83, 16, v189
	v_and_b32_e32 v81, 0xffff0000, v189
	v_fmac_f32_e32 v82, v70, v228
	v_fmac_f32_e32 v80, v71, v229
	v_fmac_f32_e32 v83, v72, v230
	v_fmac_f32_e32 v81, v73, v231
	v_cvt_pk_bf16_f32 v70, v82, v80
	v_cvt_pk_bf16_f32 v71, v83, v81
	v_lshl_add_u64 v[74:75], v[132:133], 1, v[98:99]
	v_add_f32_e32 v66, 0, v66
	v_add_f32_e32 v67, 0, v67
	v_add_f32_e32 v68, 0, v68
	v_add_f32_e32 v69, 0, v69
	s_waitcnt vmcnt(3)
	v_lshlrev_b32_e32 v78, 16, v190
	v_and_b32_e32 v76, 0xffff0000, v190
	v_lshlrev_b32_e32 v79, 16, v191
	v_and_b32_e32 v77, 0xffff0000, v191
	v_fmac_f32_e32 v78, v66, v232
	v_fmac_f32_e32 v76, v67, v233
	v_fmac_f32_e32 v79, v68, v234
	v_fmac_f32_e32 v77, v69, v235
	v_cvt_pk_bf16_f32 v72, v78, v76
	v_cvt_pk_bf16_f32 v73, v79, v77
	s_nop 1
	v_permlane16_swap_b32 v70, v72
	v_permlane16_swap_b32 v71, v73
	v_lshl_add_u64 v[248:249], v[74:75], 0, v[246:247]
	s_nop 0
	global_store_dwordx4 v[248:249], v[70:73], off offset:192
	s_nop 1
	v_or_b32_e32 v66, 32, v136
	v_ashrrev_i32_e32 v67, 31, v66
	v_lshlrev_b64 v[66:67], 10, v[66:67]
	v_lshl_add_u64 v[66:67], v[66:67], 0, v[138:139]
	v_lshl_add_u64 v[66:67], v[66:67], 1, s[18:19]
	v_lshl_add_u64 v[72:73], v[132:133], 1, v[66:67]
	v_lshl_add_u64 v[196:197], v[132:133], 1, v[66:67]
	global_load_dwordx2 v[176:177], v[196:197], off
	global_load_dwordx2 v[178:179], v[196:197], off offset:32
	global_load_dwordx2 v[180:181], v[196:197], off offset:64
	global_load_dwordx2 v[182:183], v[196:197], off offset:96
	global_load_dwordx2 v[184:185], v[196:197], off offset:128
	global_load_dwordx2 v[186:187], v[196:197], off offset:160
	global_load_dwordx2 v[188:189], v[196:197], off offset:192
	global_load_dwordx2 v[190:191], v[196:197], off offset:224
	v_add_f32_e32 v62, 0, v62
	v_add_f32_e32 v63, 0, v63
	v_add_f32_e32 v64, 0, v64
	v_add_f32_e32 v65, 0, v65
	s_waitcnt vmcnt(7)
	v_lshlrev_b32_e32 v76, 16, v176
	v_and_b32_e32 v74, 0xffff0000, v176
	v_lshlrev_b32_e32 v77, 16, v177
	v_and_b32_e32 v75, 0xffff0000, v177
	v_fmac_f32_e32 v76, v62, v198
	v_fmac_f32_e32 v74, v63, v199
	v_fmac_f32_e32 v77, v64, v200
	v_fmac_f32_e32 v75, v65, v201
	v_cvt_pk_bf16_f32 v62, v76, v74
	v_cvt_pk_bf16_f32 v63, v77, v75
	v_lshl_add_u64 v[68:69], v[132:133], 1, v[66:67]
	v_add_f32_e32 v58, 0, v58
	v_add_f32_e32 v59, 0, v59
	v_add_f32_e32 v60, 0, v60
	v_add_f32_e32 v61, 0, v61
	s_waitcnt vmcnt(6)
	v_lshlrev_b32_e32 v72, 16, v178
	v_and_b32_e32 v70, 0xffff0000, v178
	v_lshlrev_b32_e32 v73, 16, v179
	v_and_b32_e32 v71, 0xffff0000, v179
	v_fmac_f32_e32 v72, v58, v202
	v_fmac_f32_e32 v70, v59, v203
	v_fmac_f32_e32 v73, v60, v204
	v_fmac_f32_e32 v71, v61, v205
	v_cvt_pk_bf16_f32 v64, v72, v70
	v_cvt_pk_bf16_f32 v65, v73, v71
	s_nop 1
	v_permlane16_swap_b32 v62, v64
	v_permlane16_swap_b32 v63, v65
	v_lshl_add_u64 v[248:249], v[68:69], 0, v[246:247]
	s_nop 0
	global_store_dwordx4 v[248:249], v[62:65], off
	s_nop 1
	v_lshl_add_u64 v[62:63], v[132:133], 1, v[66:67]
	v_add_f32_e32 v54, 0, v54
	v_add_f32_e32 v55, 0, v55
	v_add_f32_e32 v56, 0, v56
	v_add_f32_e32 v57, 0, v57
	s_waitcnt vmcnt(6)
	v_lshlrev_b32_e32 v68, 16, v180
	v_and_b32_e32 v64, 0xffff0000, v180
	v_lshlrev_b32_e32 v69, 16, v181
	v_and_b32_e32 v65, 0xffff0000, v181
	v_fmac_f32_e32 v68, v54, v206
	v_fmac_f32_e32 v64, v55, v207
	v_fmac_f32_e32 v69, v56, v208
	v_fmac_f32_e32 v65, v57, v209
	v_cvt_pk_bf16_f32 v54, v68, v64
	v_cvt_pk_bf16_f32 v55, v69, v65
	v_lshl_add_u64 v[58:59], v[132:133], 1, v[66:67]
	v_add_f32_e32 v50, 0, v50
	v_add_f32_e32 v51, 0, v51
	v_add_f32_e32 v52, 0, v52
	v_add_f32_e32 v53, 0, v53
	s_waitcnt vmcnt(5)
	v_lshlrev_b32_e32 v62, 16, v182
	v_and_b32_e32 v60, 0xffff0000, v182
	v_lshlrev_b32_e32 v63, 16, v183
	v_and_b32_e32 v61, 0xffff0000, v183
	v_fmac_f32_e32 v62, v50, v210
	v_fmac_f32_e32 v60, v51, v211
	v_fmac_f32_e32 v63, v52, v212
	v_fmac_f32_e32 v61, v53, v213
	v_cvt_pk_bf16_f32 v56, v62, v60
	v_cvt_pk_bf16_f32 v57, v63, v61
	s_nop 1
	v_permlane16_swap_b32 v54, v56
	v_permlane16_swap_b32 v55, v57
	v_lshl_add_u64 v[248:249], v[58:59], 0, v[246:247]
	s_nop 0
	global_store_dwordx4 v[248:249], v[54:57], off offset:64
	s_nop 1
	v_lshl_add_u64 v[54:55], v[132:133], 1, v[66:67]
	v_add_f32_e32 v46, 0, v46
	v_add_f32_e32 v47, 0, v47
	v_add_f32_e32 v48, 0, v48
	v_add_f32_e32 v49, 0, v49
	s_waitcnt vmcnt(5)
; __device__ __forceinline__ unsigned pack2(float a, float b) { unsigned r; asm("v_cvt_pk_bf16_f32 %0, %1, %2" : "=v"(r) : "v"(a), "v"(b)); return r; }
; __device__ __forceinline__ float bf2f(bf16_t h) { return __uint_as_float(((unsigned)h) << 16); }
;   __device__ __forceinline__ void c4(int g, int rig, int col, f32x4 v) const {
;     const size_t o = ((size_t)g * 2048 + rig) * 1024 + col;
;     f32x4 bs;
;     if (BASE_F32) bs = __builtin_nontemporal_load((const f32x4*)((const float*)base + o));
;     else {
;       const uint2 u = *(const uint2*)((const bf16_t*)base + o);
;       bs[0] = bf2f((bf16_t)(u.x & 0xffff)); bs[1] = bf2f((bf16_t)(u.x >> 16)); bs[2] = bf2f((bf16_t)(u.y & 0xffff)); bs[3] = bf2f((bf16_t)(u.y >> 16));
;     }
;     const f32x4 gt = *(const f32x4*)(gate + (size_t)g * 6144 + col);
;     f32x4 bi = {0.f, 0.f, 0.f, 0.f};
;     if (bias) bi = *(const f32x4*)(bias + col);
;     f32x4 r;
; #pragma unroll
;     for (int j = 0; j < 4; ++j) r[j] = bs[j] + gt[j] * (v[j] + bi[j]);
;     uint2 w; w.x = pack2(r[0], r[1]); w.y = pack2(r[2], r[3]);
;     *(uint2*)(X16 + o) = w;
;   }
; template <bool SWAP, class Epi, bool THIN = false> ...
;     ...
;     if constexpr (Epi::KIND == 0) {
; #pragma unroll
;       for (int m = 0; m < 4; ++m) {
;         const int rig = rig0 + rw + m * 16 + fr_e;
;         if constexpr (Epi::ROWSUM) {
;           float ss = 0.f;
; #pragma unroll
;           for (int n = 0; n < 8; ++n) {
;             const int col = nt * 256 + wc_e * 128 + n * 16 + fq_e * 4;
;             if (col < N) ss += epi.c4(g, rig, col, acc[m][n]);
;           }
;           ss += __shfl_xor(ss, 16); ss += __shfl_xor(ss, 32);
;           if (fq_e == 0) epi.rowsum(g, rig, nt * 2 + wc_e, ss);
;         } else {
; #pragma unroll
;           for (int n = 0; n < 8; ++n) {
;             const int col = nt * 256 + wc_e * 128 + n * 16 + fq_e * 4;
;             if (col < N) epi.c4(g, rig, col, acc[m][n]);
;           }
;         }
	v_lshlrev_b32_e32 v58, 16, v184
	v_and_b32_e32 v56, 0xffff0000, v184
	v_lshlrev_b32_e32 v59, 16, v185
	v_and_b32_e32 v57, 0xffff0000, v185
	v_fmac_f32_e32 v58, v46, v214
	v_fmac_f32_e32 v56, v47, v215
	v_fmac_f32_e32 v59, v48, v216
	v_fmac_f32_e32 v57, v49, v217
	v_cvt_pk_bf16_f32 v46, v58, v56
	v_cvt_pk_bf16_f32 v47, v59, v57
	v_lshl_add_u64 v[50:51], v[132:133], 1, v[66:67]
	v_add_f32_e32 v42, 0, v42
	v_add_f32_e32 v43, 0, v43
	v_add_f32_e32 v44, 0, v44
	v_add_f32_e32 v45, 0, v45
	s_waitcnt vmcnt(4)
	v_lshlrev_b32_e32 v54, 16, v186
	v_and_b32_e32 v52, 0xffff0000, v186
	v_lshlrev_b32_e32 v55, 16, v187
	v_and_b32_e32 v53, 0xffff0000, v187
	v_fmac_f32_e32 v54, v42, v224
	v_fmac_f32_e32 v52, v43, v225
	v_fmac_f32_e32 v55, v44, v226
	v_fmac_f32_e32 v53, v45, v227
	v_cvt_pk_bf16_f32 v48, v54, v52
	v_cvt_pk_bf16_f32 v49, v55, v53
	s_nop 1
	v_permlane16_swap_b32 v46, v48
	v_permlane16_swap_b32 v47, v49
	v_lshl_add_u64 v[248:249], v[50:51], 0, v[246:247]
	s_nop 0
	global_store_dwordx4 v[248:249], v[46:49], off offset:128
	s_nop 1
	v_lshl_add_u64 v[46:47], v[132:133], 1, v[66:67]
	v_add_f32_e32 v38, 0, v38
	v_add_f32_e32 v39, 0, v39
	v_add_f32_e32 v40, 0, v40
	v_add_f32_e32 v41, 0, v41
	s_waitcnt vmcnt(4)
	v_lshlrev_b32_e32 v50, 16, v188
	v_and_b32_e32 v48, 0xffff0000, v188
	v_lshlrev_b32_e32 v51, 16, v189
	v_and_b32_e32 v49, 0xffff0000, v189
	v_fmac_f32_e32 v50, v38, v228
	v_fmac_f32_e32 v48, v39, v229
	v_fmac_f32_e32 v51, v40, v230
	v_fmac_f32_e32 v49, v41, v231
	v_cvt_pk_bf16_f32 v38, v50, v48
	v_cvt_pk_bf16_f32 v39, v51, v49
	v_lshl_add_u64 v[42:43], v[132:133], 1, v[66:67]
	v_add_f32_e32 v34, 0, v34
	v_add_f32_e32 v35, 0, v35
	v_add_f32_e32 v36, 0, v36
	v_add_f32_e32 v37, 0, v37
	s_waitcnt vmcnt(3)
	v_lshlrev_b32_e32 v46, 16, v190
	v_and_b32_e32 v44, 0xffff0000, v190
	v_lshlrev_b32_e32 v47, 16, v191
	v_and_b32_e32 v45, 0xffff0000, v191
	v_fmac_f32_e32 v46, v34, v232
	v_fmac_f32_e32 v44, v35, v233
	v_fmac_f32_e32 v47, v36, v234
	v_fmac_f32_e32 v45, v37, v235
	v_cvt_pk_bf16_f32 v40, v46, v44
	v_cvt_pk_bf16_f32 v41, v47, v45
	s_nop 1
	v_permlane16_swap_b32 v38, v40
	v_permlane16_swap_b32 v39, v41
	v_lshl_add_u64 v[248:249], v[42:43], 0, v[246:247]
	s_nop 0
	global_store_dwordx4 v[248:249], v[38:41], off offset:192
	s_nop 1
	v_or_b32_e32 v34, 48, v136
	v_ashrrev_i32_e32 v35, 31, v34
	v_lshlrev_b64 v[34:35], 10, v[34:35]
	v_lshl_add_u64 v[34:35], v[34:35], 0, v[138:139]
	v_lshl_add_u64 v[34:35], v[34:35], 1, s[18:19]
	v_lshl_add_u64 v[40:41], v[132:133], 1, v[34:35]
	v_lshl_add_u64 v[196:197], v[132:133], 1, v[34:35]
	global_load_dwordx2 v[176:177], v[196:197], off
	global_load_dwordx2 v[178:179], v[196:197], off offset:32
	global_load_dwordx2 v[180:181], v[196:197], off offset:64
	global_load_dwordx2 v[182:183], v[196:197], off offset:96
	global_load_dwordx2 v[184:185], v[196:197], off offset:128
	global_load_dwordx2 v[186:187], v[196:197], off offset:160
	global_load_dwordx2 v[188:189], v[196:197], off offset:192
	global_load_dwordx2 v[190:191], v[196:197], off offset:224
	v_add_f32_e32 v30, 0, v30
	v_add_f32_e32 v31, 0, v31
	v_add_f32_e32 v32, 0, v32
	v_add_f32_e32 v33, 0, v33
	s_waitcnt vmcnt(7)
	v_lshlrev_b32_e32 v44, 16, v176
	v_and_b32_e32 v42, 0xffff0000, v176
	v_lshlrev_b32_e32 v45, 16, v177
	v_and_b32_e32 v43, 0xffff0000, v177
	v_fmac_f32_e32 v44, v30, v198
	v_fmac_f32_e32 v42, v31, v199
	v_fmac_f32_e32 v45, v32, v200
	v_fmac_f32_e32 v43, v33, v201
	v_cvt_pk_bf16_f32 v30, v44, v42
	v_cvt_pk_bf16_f32 v31, v45, v43
	v_lshl_add_u64 v[36:37], v[132:133], 1, v[34:35]
	v_add_f32_e32 v26, 0, v26
	v_add_f32_e32 v27, 0, v27
	v_add_f32_e32 v28, 0, v28
	v_add_f32_e32 v29, 0, v29
	s_waitcnt vmcnt(6)
; __device__ __forceinline__ unsigned pack2(float a, float b) { unsigned r; asm("v_cvt_pk_bf16_f32 %0, %1, %2" : "=v"(r) : "v"(a), "v"(b)); return r; }
; __device__ __forceinline__ float bf2f(bf16_t h) { return __uint_as_float(((unsigned)h) << 16); }
;   __device__ __forceinline__ void c4(int g, int rig, int col, f32x4 v) const {
;     const size_t o = ((size_t)g * 2048 + rig) * 1024 + col;
;     f32x4 bs;
;     if (BASE_F32) bs = __builtin_nontemporal_load((const f32x4*)((const float*)base + o));
;     else {
;       const uint2 u = *(const uint2*)((const bf16_t*)base + o);
;       bs[0] = bf2f((bf16_t)(u.x & 0xffff)); bs[1] = bf2f((bf16_t)(u.x >> 16)); bs[2] = bf2f((bf16_t)(u.y & 0xffff)); bs[3] = bf2f((bf16_t)(u.y >> 16));
;     }
;     const f32x4 gt = *(const f32x4*)(gate + (size_t)g * 6144 + col);
;     f32x4 bi = {0.f, 0.f, 0.f, 0.f};
;     if (bias) bi = *(const f32x4*)(bias + col);
;     f32x4 r;
; #pragma unroll
;     for (int j = 0; j < 4; ++j) r[j] = bs[j] + gt[j] * (v[j] + bi[j]);
;     uint2 w; w.x = pack2(r[0], r[1]); w.y = pack2(r[2], r[3]);
;     *(uint2*)(X16 + o) = w;
;   }
; template <bool SWAP, class Epi, bool THIN = false> ...
;     ...
;     if constexpr (Epi::KIND == 0) {
; #pragma unroll
;       for (int m = 0; m < 4; ++m) {
;         const int rig = rig0 + rw + m * 16 + fr_e;
;         if constexpr (Epi::ROWSUM) {
;           float ss = 0.f;
; #pragma unroll
;           for (int n = 0; n < 8; ++n) {
;             const int col = nt * 256 + wc_e * 128 + n * 16 + fq_e * 4;
;             if (col < N) ss += epi.c4(g, rig, col, acc[m][n]);
;           }
;           ss += __shfl_xor(ss, 16); ss += __shfl_xor(ss, 32);
;           if (fq_e == 0) epi.rowsum(g, rig, nt * 2 + wc_e, ss);
;         } else {
; #pragma unroll
;           for (int n = 0; n < 8; ++n) {
;             const int col = nt * 256 + wc_e * 128 + n * 16 + fq_e * 4;
;             if (col < N) epi.c4(g, rig, col, acc[m][n]);
;           }
;         }
	v_lshlrev_b32_e32 v40, 16, v178
	v_and_b32_e32 v38, 0xffff0000, v178
	v_lshlrev_b32_e32 v41, 16, v179
	v_and_b32_e32 v39, 0xffff0000, v179
	v_fmac_f32_e32 v40, v26, v202
	v_fmac_f32_e32 v38, v27, v203
	v_fmac_f32_e32 v41, v28, v204
	v_fmac_f32_e32 v39, v29, v205
	v_cvt_pk_bf16_f32 v32, v40, v38
	v_cvt_pk_bf16_f32 v33, v41, v39
	s_nop 1
	v_permlane16_swap_b32 v30, v32
	v_permlane16_swap_b32 v31, v33
	v_lshl_add_u64 v[248:249], v[36:37], 0, v[246:247]
	s_nop 0
	global_store_dwordx4 v[248:249], v[30:33], off
	s_nop 1
	v_lshl_add_u64 v[30:31], v[132:133], 1, v[34:35]
	v_add_f32_e32 v22, 0, v22
	v_add_f32_e32 v23, 0, v23
	v_add_f32_e32 v24, 0, v24
	v_add_f32_e32 v25, 0, v25
	s_waitcnt vmcnt(6)
	v_lshlrev_b32_e32 v36, 16, v180
	v_and_b32_e32 v32, 0xffff0000, v180
	v_lshlrev_b32_e32 v37, 16, v181
	v_and_b32_e32 v33, 0xffff0000, v181
	v_fmac_f32_e32 v36, v22, v206
	v_fmac_f32_e32 v32, v23, v207
	v_fmac_f32_e32 v37, v24, v208
	v_fmac_f32_e32 v33, v25, v209
	v_cvt_pk_bf16_f32 v22, v36, v32
	v_cvt_pk_bf16_f32 v23, v37, v33
	v_lshl_add_u64 v[26:27], v[132:133], 1, v[34:35]
	v_add_f32_e32 v18, 0, v18
	v_add_f32_e32 v19, 0, v19
	v_add_f32_e32 v20, 0, v20
	v_add_f32_e32 v21, 0, v21
	s_waitcnt vmcnt(5)
	v_lshlrev_b32_e32 v30, 16, v182
	v_and_b32_e32 v28, 0xffff0000, v182
	v_lshlrev_b32_e32 v31, 16, v183
	v_and_b32_e32 v29, 0xffff0000, v183
	v_fmac_f32_e32 v30, v18, v210
	v_fmac_f32_e32 v28, v19, v211
	v_fmac_f32_e32 v31, v20, v212
	v_fmac_f32_e32 v29, v21, v213
	v_cvt_pk_bf16_f32 v24, v30, v28
	v_cvt_pk_bf16_f32 v25, v31, v29
	s_nop 1
	v_permlane16_swap_b32 v22, v24
	v_permlane16_swap_b32 v23, v25
	v_lshl_add_u64 v[248:249], v[26:27], 0, v[246:247]
	s_nop 0
	global_store_dwordx4 v[248:249], v[22:25], off offset:64
	s_nop 1
	v_lshl_add_u64 v[22:23], v[132:133], 1, v[34:35]
	v_add_f32_e32 v14, 0, v14
	v_add_f32_e32 v15, 0, v15
	v_add_f32_e32 v16, 0, v16
	v_add_f32_e32 v17, 0, v17
	s_waitcnt vmcnt(5)
	v_lshlrev_b32_e32 v26, 16, v184
	v_and_b32_e32 v24, 0xffff0000, v184
	v_lshlrev_b32_e32 v27, 16, v185
	v_and_b32_e32 v25, 0xffff0000, v185
	v_fmac_f32_e32 v26, v14, v214
	v_fmac_f32_e32 v24, v15, v215
	v_fmac_f32_e32 v27, v16, v216
	v_fmac_f32_e32 v25, v17, v217
	v_cvt_pk_bf16_f32 v14, v26, v24
	v_cvt_pk_bf16_f32 v15, v27, v25
	v_lshl_add_u64 v[18:19], v[132:133], 1, v[34:35]
	v_add_f32_e32 v10, 0, v10
	v_add_f32_e32 v11, 0, v11
	v_add_f32_e32 v12, 0, v12
	v_add_f32_e32 v13, 0, v13
	s_waitcnt vmcnt(4)
	v_lshlrev_b32_e32 v22, 16, v186
	v_and_b32_e32 v20, 0xffff0000, v186
	v_lshlrev_b32_e32 v23, 16, v187
	v_and_b32_e32 v21, 0xffff0000, v187
	v_fmac_f32_e32 v22, v10, v224
	v_fmac_f32_e32 v20, v11, v225
	v_fmac_f32_e32 v23, v12, v226
	v_fmac_f32_e32 v21, v13, v227
	v_cvt_pk_bf16_f32 v16, v22, v20
	v_cvt_pk_bf16_f32 v17, v23, v21
	s_nop 1
	v_permlane16_swap_b32 v14, v16
	v_permlane16_swap_b32 v15, v17
	v_lshl_add_u64 v[248:249], v[18:19], 0, v[246:247]
	s_nop 0
	global_store_dwordx4 v[248:249], v[14:17], off offset:128
	s_nop 1
	v_lshl_add_u64 v[14:15], v[132:133], 1, v[34:35]
	v_add_f32_e32 v6, 0, v6
	v_add_f32_e32 v7, 0, v7
	v_add_f32_e32 v8, 0, v8
	v_add_f32_e32 v9, 0, v9
	s_waitcnt vmcnt(4)
	v_lshlrev_b32_e32 v18, 16, v188
	v_and_b32_e32 v16, 0xffff0000, v188
	v_lshlrev_b32_e32 v19, 16, v189
	v_and_b32_e32 v17, 0xffff0000, v189
	v_fmac_f32_e32 v18, v6, v228
	v_fmac_f32_e32 v16, v7, v229
	v_fmac_f32_e32 v19, v8, v230
	v_fmac_f32_e32 v17, v9, v231
	v_cvt_pk_bf16_f32 v6, v18, v16
	v_cvt_pk_bf16_f32 v7, v19, v17
	v_lshl_add_u64 v[10:11], v[132:133], 1, v[34:35]
	v_add_f32_e32 v2, 0, v2
	v_add_f32_e32 v3, 0, v3
	v_add_f32_e32 v4, 0, v4
	v_add_f32_e32 v5, 0, v5
	s_waitcnt vmcnt(3)
	v_lshlrev_b32_e32 v14, 16, v190
	v_and_b32_e32 v12, 0xffff0000, v190
	v_lshlrev_b32_e32 v15, 16, v191
	v_and_b32_e32 v13, 0xffff0000, v191
	v_fmac_f32_e32 v14, v2, v232
	v_fmac_f32_e32 v12, v3, v233
	v_fmac_f32_e32 v15, v4, v234
	v_fmac_f32_e32 v13, v5, v235
	v_cvt_pk_bf16_f32 v8, v14, v12
	v_cvt_pk_bf16_f32 v9, v15, v13
	s_nop 1
	v_permlane16_swap_b32 v6, v8
	v_permlane16_swap_b32 v7, v9
	v_lshl_add_u64 v[248:249], v[10:11], 0, v[246:247]
	s_nop 0
	global_store_dwordx4 v[248:249], v[6:9], off offset:192
	s_nop 1
	s_branch .LBB0_3514
